# code placement: every GEMM MFMA cluster padded to start 8-byte aligned (s_nop 0 at the start of 20 load segments), on top of the best version
# speedup vs baseline: 1.0048x; 1.0021x over previous
; #define PG8_STAGE(bufoff, gbase, voff) do { _Pragma("unroll") for (int _i = 0; _i < 2; ++_i) \
;         __builtin_amdgcn_global_load_lds((const unsigned*)((const char*)(gbase) + (voff)[_i]), (PG8_LAS unsigned*)(lds + (bufoff) + ldsw + _i * 8192), 16, 0, 0); } while (0)
; #define PG8_LDA(dst, b, h) do { _Pragma("unroll") for (int m = 0; m < 4; ++m) _Pragma("unroll") for (int k = 0; k < 2; ++k) dst[m][k] = *(const PG8_LAS bf16x8*)(lds + PG8_SA(b, h) + aoff + m * 2048 + k * 1024); } while (0)
; #define PG8_LDB(dst, b, h) do { _Pragma("unroll") for (int n = 0; n < 2; ++n) _Pragma("unroll") for (int k = 0; k < 2; ++k) dst[n][k] = *(const PG8_LAS bf16x8*)(lds + PG8_SB(b, h) + boff + n * 2048 + k * 1024); } while (0)
; #define PG8_MMA(ai, bj, At, Bt) do { __builtin_amdgcn_s_setprio(1); _Pragma("unroll") for (int m = 0; m < 4; ++m) _Pragma("unroll") for (int n = 0; n < 2; ++n) _Pragma("unroll") for (int k = 0; k < 2; ++k) \
;         acc[ai][bj][m][n] = __builtin_amdgcn_mfma_f32_16x16x32_bf16(Bt[n][k], At[m][k], acc[ai][bj][m][n], 0, 0, 0); __builtin_amdgcn_s_setprio(0); } while (0)
; #define PG8_WAIT_V(n) asm volatile("s_waitcnt vmcnt(" #n ")" ::: "memory")
; #define PG8_WAIT_L(n) asm volatile("s_waitcnt lgkmcnt(" #n ")" ::: "memory")
; #define PG8_BAR __builtin_amdgcn_s_barrier()
; template <class Epi, class Sched, bool ALIGN_EPI = false, bool SP2 = false>
; __device__ __forceinline__ void gemm_phase(PG8_LAS unsigned char* lds, const Gemm g, const Sched& S, const Epi& E) {
;     ...
;             const char* a1 = cA + (size_t)(t + 1) * kstep;
;             const char* a2 = last ? nA : cA + (size_t)(t + 2) * kstep; const char* b2 = last ? nB : cB + (size_t)(t + 2) * kstep;
;             const char* a3 = a2 + kstep; const char* b3 = b2 + kstep;
;             if (last && has_next) S.a_ready(nxt);
;             if constexpr (SP2) {
;             PG8_LDB(B0, 0, 0); PG8_LDB(B1, 0, 1); PG8_SCHED; PG8_LDA(At, 0, 0); PG8_STAGE(PG8_SA(1, 1), a1 + hstepA, voffA);
;             PG8_WAIT_V(8); PG8_WAIT_L(0); PG8_BAR; PG8_MMA(0, 0, At, B0); PG8_MMA(0, 1, At, B1); PG8_BAR; PG8_SCHED;
;             PG8_LDA(At, 0, 1); PG8_STAGE(PG8_SB(0, 0), b2, voffB); PG8_STAGE(PG8_SB(0, 1), b2 + hstepB, voffB); PG8_STAGE(PG8_SA(0, 0), a2, voffA);
;             PG8_WAIT_V(8); PG8_WAIT_L(0); PG8_BAR; PG8_MMA(1, 0, At, B0); PG8_MMA(1, 1, At, B1); PG8_BAR; PG8_SCHED;
.LBB0_244:
	ds_read_b128 v[152:155], v147
	ds_read_b128 v[156:159], v147 offset:1024
	ds_read_b128 v[160:163], v147 offset:2048
	ds_read_b128 v[164:167], v147 offset:3072
	ds_read_b128 v[168:171], v148
	ds_read_b128 v[172:175], v148 offset:1024
	ds_read_b128 v[176:179], v148 offset:2048
	ds_read_b128 v[180:183], v148 offset:3072
	s_add_u32 s28, s26, 0xfffc0080
	s_addc_u32 s29, s27, -1
	s_cmp_eq_u32 s68, 12
	s_cselect_b32 s31, s15, s29
	s_cselect_b32 s30, s62, s28
	s_cselect_b32 s29, s13, s67
	s_cselect_b32 s28, s63, s66
	v_lshl_add_u64 v[184:185], s[26:27], 0, v[136:137]
	s_add_i32 m0, s25, 0xc000
	ds_read_b128 v[188:191], v149
	ds_read_b128 v[192:195], v149 offset:1024
	ds_read_b128 v[196:199], v149 offset:2048
	ds_read_b128 v[200:203], v149 offset:3072
	ds_read_b128 v[204:207], v149 offset:4096
	ds_read_b128 v[208:211], v149 offset:5120
	ds_read_b128 v[212:215], v149 offset:6144
	ds_read_b128 v[216:219], v149 offset:7168
	global_load_lds_dwordx4 v[184:185], off
	v_lshl_add_u64 v[184:185], s[26:27], 0, v[138:139]
	s_add_i32 m0, s25, 0xe000
	s_nop 0
	global_load_lds_dwordx4 v[184:185], off
	s_waitcnt vmcnt(8) lgkmcnt(0)
	s_barrier
	s_setprio 1
	v_mfma_f32_16x16x32_bf16 v[116:119], v[152:155], v[188:191], v[116:119]
	v_mfma_f32_16x16x32_bf16 v[108:111], v[160:163], v[188:191], v[108:111]
	v_mfma_f32_16x16x32_bf16 v[104:107], v[152:155], v[196:199], v[104:107]
	v_mfma_f32_16x16x32_bf16 v[100:103], v[160:163], v[196:199], v[100:103]
	v_mfma_f32_16x16x32_bf16 v[92:95], v[152:155], v[204:207], v[92:95]
	v_mfma_f32_16x16x32_bf16 v[84:87], v[160:163], v[204:207], v[84:87]
	v_mfma_f32_16x16x32_bf16 v[76:79], v[152:155], v[212:215], v[76:79]
	v_mfma_f32_16x16x32_bf16 v[68:71], v[160:163], v[212:215], v[68:71]
	v_mfma_f32_16x16x32_bf16 v[116:119], v[156:159], v[192:195], v[116:119]
	v_mfma_f32_16x16x32_bf16 v[108:111], v[164:167], v[192:195], v[108:111]
	v_mfma_f32_16x16x32_bf16 v[104:107], v[156:159], v[200:203], v[104:107]
	v_mfma_f32_16x16x32_bf16 v[100:103], v[164:167], v[200:203], v[100:103]
	v_mfma_f32_16x16x32_bf16 v[92:95], v[156:159], v[208:211], v[92:95]
	v_mfma_f32_16x16x32_bf16 v[84:87], v[164:167], v[208:211], v[84:87]
	v_mfma_f32_16x16x32_bf16 v[76:79], v[156:159], v[216:219], v[76:79]
	v_mfma_f32_16x16x32_bf16 v[68:71], v[164:167], v[216:219], v[68:71]
	s_setprio 0
	s_setprio 1
	v_mfma_f32_16x16x32_bf16 v[124:127], v[168:171], v[188:191], v[124:127]
	v_mfma_f32_16x16x32_bf16 v[120:123], v[176:179], v[188:191], v[120:123]
	v_mfma_f32_16x16x32_bf16 v[112:115], v[168:171], v[196:199], v[112:115]
	v_mfma_f32_16x16x32_bf16 v[96:99], v[176:179], v[196:199], v[96:99]
	v_mfma_f32_16x16x32_bf16 v[88:91], v[168:171], v[204:207], v[88:91]
	v_mfma_f32_16x16x32_bf16 v[80:83], v[176:179], v[204:207], v[80:83]
	v_mfma_f32_16x16x32_bf16 v[72:75], v[168:171], v[212:215], v[72:75]
	v_mfma_f32_16x16x32_bf16 v[64:67], v[176:179], v[212:215], v[64:67]
	v_mfma_f32_16x16x32_bf16 v[124:127], v[172:175], v[192:195], v[124:127]
	v_mfma_f32_16x16x32_bf16 v[120:123], v[180:183], v[192:195], v[120:123]
	v_mfma_f32_16x16x32_bf16 v[112:115], v[172:175], v[200:203], v[112:115]
	v_mfma_f32_16x16x32_bf16 v[96:99], v[180:183], v[200:203], v[96:99]
	v_mfma_f32_16x16x32_bf16 v[88:91], v[172:175], v[208:211], v[88:91]
	v_mfma_f32_16x16x32_bf16 v[80:83], v[180:183], v[208:211], v[80:83]
	v_mfma_f32_16x16x32_bf16 v[72:75], v[172:175], v[216:219], v[72:75]
	v_mfma_f32_16x16x32_bf16 v[64:67], v[180:183], v[216:219], v[64:67]
	s_barrier
	s_setprio 0
	s_nop 0
	s_add_i32 s58, s46, s36
	v_lshl_add_u64 v[184:185], s[28:29], 0, v[132:133]
	s_mov_b32 m0, s58
	ds_read_b128 v[188:191], v149 offset:16384
	ds_read_b128 v[192:195], v149 offset:17408
	ds_read_b128 v[196:199], v149 offset:18432
	ds_read_b128 v[200:203], v149 offset:19456
	ds_read_b128 v[204:207], v149 offset:20480
	ds_read_b128 v[208:211], v149 offset:21504
	ds_read_b128 v[212:215], v149 offset:22528
	ds_read_b128 v[216:219], v149 offset:23552
	global_load_lds_dwordx4 v[184:185], off
	s_add_i32 m0, s58, 0x2000
	s_add_u32 s58, s28, 0x40000
	v_lshl_add_u64 v[220:221], s[28:29], 0, v[128:129]
	s_addc_u32 s59, s29, 0
	s_add_i32 s69, s47, s36
	global_load_lds_dwordx4 v[220:221], off
	v_lshl_add_u64 v[222:223], s[58:59], 0, v[132:133]
	s_mov_b32 m0, s69
	v_lshl_add_u64 v[224:225], s[30:31], 0, v[130:131]
	global_load_lds_dwordx4 v[222:223], off
	v_lshl_add_u64 v[222:223], s[58:59], 0, v[128:129]
	s_add_i32 m0, s69, 0x2000
	s_nop 0
	global_load_lds_dwordx4 v[222:223], off
	v_lshl_add_u64 v[222:223], s[30:31], 0, v[134:135]
	s_mov_b32 m0, s25
	s_nop 0
	global_load_lds_dwordx4 v[222:223], off
	s_mov_b32 m0, s39
	s_nop 0
	global_load_lds_dwordx4 v[224:225], off
	s_waitcnt vmcnt(8) lgkmcnt(0)
	s_barrier
; #define PG8_STAGE(bufoff, gbase, voff) do { _Pragma("unroll") for (int _i = 0; _i < 2; ++_i) \
;         __builtin_amdgcn_global_load_lds((const unsigned*)((const char*)(gbase) + (voff)[_i]), (PG8_LAS unsigned*)(lds + (bufoff) + ldsw + _i * 8192), 16, 0, 0); } while (0)
; #define PG8_LDA(dst, b, h) do { _Pragma("unroll") for (int m = 0; m < 4; ++m) _Pragma("unroll") for (int k = 0; k < 2; ++k) dst[m][k] = *(const PG8_LAS bf16x8*)(lds + PG8_SA(b, h) + aoff + m * 2048 + k * 1024); } while (0)
; #define PG8_LDB(dst, b, h) do { _Pragma("unroll") for (int n = 0; n < 2; ++n) _Pragma("unroll") for (int k = 0; k < 2; ++k) dst[n][k] = *(const PG8_LAS bf16x8*)(lds + PG8_SB(b, h) + boff + n * 2048 + k * 1024); } while (0)
; #define PG8_MMA(ai, bj, At, Bt) do { __builtin_amdgcn_s_setprio(1); _Pragma("unroll") for (int m = 0; m < 4; ++m) _Pragma("unroll") for (int n = 0; n < 2; ++n) _Pragma("unroll") for (int k = 0; k < 2; ++k) \
;         acc[ai][bj][m][n] = __builtin_amdgcn_mfma_f32_16x16x32_bf16(Bt[n][k], At[m][k], acc[ai][bj][m][n], 0, 0, 0); __builtin_amdgcn_s_setprio(0); } while (0)
; #define PG8_WAIT_V(n) asm volatile("s_waitcnt vmcnt(" #n ")" ::: "memory")
; #define PG8_WAIT_L(n) asm volatile("s_waitcnt lgkmcnt(" #n ")" ::: "memory")
; #define PG8_BAR __builtin_amdgcn_s_barrier()
; #define PG8_SCHED __builtin_amdgcn_sched_barrier(0)
; template <class Epi, class Sched, bool ALIGN_EPI = false, bool SP2 = false>
; __device__ __forceinline__ void gemm_phase(PG8_LAS unsigned char* lds, const Gemm g, const Sched& S, const Epi& E) {
;     ...
;             PG8_WAIT_V(8); PG8_WAIT_L(0); PG8_BAR; PG8_MMA(1, 0, At, B0); PG8_MMA(1, 1, At, B1); PG8_BAR; PG8_SCHED;
;             PG8_LDB(B0, 1, 0); PG8_LDB(B1, 1, 1); PG8_SCHED; PG8_LDA(At, 1, 0); PG8_STAGE(PG8_SA(0, 1), a2 + hstepA, voffA);
;             PG8_WAIT_V(8); PG8_WAIT_L(0); PG8_BAR; PG8_MMA(0, 0, At, B0); PG8_MMA(0, 1, At, B1); PG8_BAR; PG8_SCHED;
	s_setprio 1
	v_mfma_f32_16x16x32_bf16 v[60:63], v[152:155], v[188:191], v[60:63]
	v_mfma_f32_16x16x32_bf16 v[52:55], v[160:163], v[188:191], v[52:55]
	v_mfma_f32_16x16x32_bf16 v[44:47], v[152:155], v[196:199], v[44:47]
	v_mfma_f32_16x16x32_bf16 v[36:39], v[160:163], v[196:199], v[36:39]
	v_mfma_f32_16x16x32_bf16 v[28:31], v[152:155], v[204:207], v[28:31]
	v_mfma_f32_16x16x32_bf16 v[20:23], v[160:163], v[204:207], v[20:23]
	v_mfma_f32_16x16x32_bf16 v[12:15], v[152:155], v[212:215], v[12:15]
	v_mfma_f32_16x16x32_bf16 v[4:7], v[160:163], v[212:215], v[4:7]
	v_mfma_f32_16x16x32_bf16 v[60:63], v[156:159], v[192:195], v[60:63]
	v_mfma_f32_16x16x32_bf16 v[52:55], v[164:167], v[192:195], v[52:55]
	v_mfma_f32_16x16x32_bf16 v[44:47], v[156:159], v[200:203], v[44:47]
	v_mfma_f32_16x16x32_bf16 v[36:39], v[164:167], v[200:203], v[36:39]
	v_mfma_f32_16x16x32_bf16 v[28:31], v[156:159], v[208:211], v[28:31]
	v_mfma_f32_16x16x32_bf16 v[20:23], v[164:167], v[208:211], v[20:23]
	v_mfma_f32_16x16x32_bf16 v[12:15], v[156:159], v[216:219], v[12:15]
	v_mfma_f32_16x16x32_bf16 v[4:7], v[164:167], v[216:219], v[4:7]
	s_setprio 0
	s_setprio 1
	v_mfma_f32_16x16x32_bf16 v[56:59], v[168:171], v[188:191], v[56:59]
	v_mfma_f32_16x16x32_bf16 v[48:51], v[176:179], v[188:191], v[48:51]
	v_mfma_f32_16x16x32_bf16 v[40:43], v[168:171], v[196:199], v[40:43]
	v_mfma_f32_16x16x32_bf16 v[32:35], v[176:179], v[196:199], v[32:35]
	v_mfma_f32_16x16x32_bf16 v[24:27], v[168:171], v[204:207], v[24:27]
	v_mfma_f32_16x16x32_bf16 v[16:19], v[176:179], v[204:207], v[16:19]
	v_mfma_f32_16x16x32_bf16 v[8:11], v[168:171], v[212:215], v[8:11]
	v_mfma_f32_16x16x32_bf16 v[0:3], v[176:179], v[212:215], v[0:3]
	v_mfma_f32_16x16x32_bf16 v[56:59], v[172:175], v[192:195], v[56:59]
	v_mfma_f32_16x16x32_bf16 v[48:51], v[180:183], v[192:195], v[48:51]
	v_mfma_f32_16x16x32_bf16 v[40:43], v[172:175], v[200:203], v[40:43]
	v_mfma_f32_16x16x32_bf16 v[32:35], v[180:183], v[200:203], v[32:35]
	v_mfma_f32_16x16x32_bf16 v[24:27], v[172:175], v[208:211], v[24:27]
	v_mfma_f32_16x16x32_bf16 v[16:19], v[180:183], v[208:211], v[16:19]
	v_mfma_f32_16x16x32_bf16 v[8:11], v[172:175], v[216:219], v[8:11]
	v_mfma_f32_16x16x32_bf16 v[0:3], v[180:183], v[216:219], v[0:3]
	s_barrier
	s_setprio 0
	s_nop 0
	s_add_i32 s58, 0, 0x18000
	v_add_u32_e32 v151, s58, v145
	s_add_i32 s59, 0, 0x1c000
	ds_read_b128 v[152:155], v151
	ds_read_b128 v[156:159], v151 offset:1024
	ds_read_b128 v[160:163], v151 offset:2048
	ds_read_b128 v[164:167], v151 offset:3072
	v_add_u32_e32 v151, s59, v145
	ds_read_b128 v[168:171], v151
	ds_read_b128 v[172:175], v151 offset:1024
	ds_read_b128 v[176:179], v151 offset:2048
	ds_read_b128 v[180:183], v151 offset:3072
	s_add_u32 s30, s30, 0x40000
	s_addc_u32 s31, s31, 0
	s_mov_b32 m0, s40
	v_lshl_add_u64 v[226:227], s[30:31], 0, v[134:135]
	ds_read_b128 v[188:191], v149 offset:32768
	ds_read_b128 v[192:195], v149 offset:33792
	ds_read_b128 v[196:199], v149 offset:34816
	ds_read_b128 v[200:203], v149 offset:35840
	ds_read_b128 v[204:207], v149 offset:36864
	ds_read_b128 v[208:211], v149 offset:37888
	ds_read_b128 v[212:215], v149 offset:38912
	ds_read_b128 v[216:219], v149 offset:39936
	global_load_lds_dwordx4 v[226:227], off
	v_lshl_add_u64 v[226:227], s[30:31], 0, v[130:131]
	s_mov_b32 m0, s41
	s_nop 0
	global_load_lds_dwordx4 v[226:227], off
	s_waitcnt vmcnt(8) lgkmcnt(0)
	s_barrier
	s_setprio 1
	v_mfma_f32_16x16x32_bf16 v[116:119], v[152:155], v[188:191], v[116:119]
	v_mfma_f32_16x16x32_bf16 v[108:111], v[160:163], v[188:191], v[108:111]
	v_mfma_f32_16x16x32_bf16 v[104:107], v[152:155], v[196:199], v[104:107]
	v_mfma_f32_16x16x32_bf16 v[100:103], v[160:163], v[196:199], v[100:103]
	v_mfma_f32_16x16x32_bf16 v[92:95], v[152:155], v[204:207], v[92:95]
	v_mfma_f32_16x16x32_bf16 v[84:87], v[160:163], v[204:207], v[84:87]
	v_mfma_f32_16x16x32_bf16 v[76:79], v[152:155], v[212:215], v[76:79]
	v_mfma_f32_16x16x32_bf16 v[68:71], v[160:163], v[212:215], v[68:71]
	v_mfma_f32_16x16x32_bf16 v[116:119], v[156:159], v[192:195], v[116:119]
	v_mfma_f32_16x16x32_bf16 v[108:111], v[164:167], v[192:195], v[108:111]
	v_mfma_f32_16x16x32_bf16 v[104:107], v[156:159], v[200:203], v[104:107]
	v_mfma_f32_16x16x32_bf16 v[100:103], v[164:167], v[200:203], v[100:103]
	v_mfma_f32_16x16x32_bf16 v[92:95], v[156:159], v[208:211], v[92:95]
	v_mfma_f32_16x16x32_bf16 v[84:87], v[164:167], v[208:211], v[84:87]
	v_mfma_f32_16x16x32_bf16 v[76:79], v[156:159], v[216:219], v[76:79]
	v_mfma_f32_16x16x32_bf16 v[68:71], v[164:167], v[216:219], v[68:71]
	s_setprio 0
	s_setprio 1
	v_mfma_f32_16x16x32_bf16 v[124:127], v[168:171], v[188:191], v[124:127]
	v_mfma_f32_16x16x32_bf16 v[120:123], v[176:179], v[188:191], v[120:123]
	v_mfma_f32_16x16x32_bf16 v[112:115], v[168:171], v[196:199], v[112:115]
	v_mfma_f32_16x16x32_bf16 v[96:99], v[176:179], v[196:199], v[96:99]
	v_mfma_f32_16x16x32_bf16 v[88:91], v[168:171], v[204:207], v[88:91]
	v_mfma_f32_16x16x32_bf16 v[80:83], v[176:179], v[204:207], v[80:83]
	v_mfma_f32_16x16x32_bf16 v[72:75], v[168:171], v[212:215], v[72:75]
	v_mfma_f32_16x16x32_bf16 v[64:67], v[176:179], v[212:215], v[64:67]
	v_mfma_f32_16x16x32_bf16 v[124:127], v[172:175], v[192:195], v[124:127]
	v_mfma_f32_16x16x32_bf16 v[120:123], v[180:183], v[192:195], v[120:123]
	v_mfma_f32_16x16x32_bf16 v[112:115], v[172:175], v[200:203], v[112:115]
	v_mfma_f32_16x16x32_bf16 v[96:99], v[180:183], v[200:203], v[96:99]
	v_mfma_f32_16x16x32_bf16 v[88:91], v[172:175], v[208:211], v[88:91]
	v_mfma_f32_16x16x32_bf16 v[80:83], v[180:183], v[208:211], v[80:83]
	v_mfma_f32_16x16x32_bf16 v[72:75], v[172:175], v[216:219], v[72:75]
	v_mfma_f32_16x16x32_bf16 v[64:67], v[180:183], v[216:219], v[64:67]
	s_barrier
; #define PG8_STAGE(bufoff, gbase, voff) do { _Pragma("unroll") for (int _i = 0; _i < 2; ++_i) \
;         __builtin_amdgcn_global_load_lds((const unsigned*)((const char*)(gbase) + (voff)[_i]), (PG8_LAS unsigned*)(lds + (bufoff) + ldsw + _i * 8192), 16, 0, 0); } while (0)
; #define PG8_LDA(dst, b, h) do { _Pragma("unroll") for (int m = 0; m < 4; ++m) _Pragma("unroll") for (int k = 0; k < 2; ++k) dst[m][k] = *(const PG8_LAS bf16x8*)(lds + PG8_SA(b, h) + aoff + m * 2048 + k * 1024); } while (0)
; #define PG8_MMA(ai, bj, At, Bt) do { __builtin_amdgcn_s_setprio(1); _Pragma("unroll") for (int m = 0; m < 4; ++m) _Pragma("unroll") for (int n = 0; n < 2; ++n) _Pragma("unroll") for (int k = 0; k < 2; ++k) \
;         acc[ai][bj][m][n] = __builtin_amdgcn_mfma_f32_16x16x32_bf16(Bt[n][k], At[m][k], acc[ai][bj][m][n], 0, 0, 0); __builtin_amdgcn_s_setprio(0); } while (0)
; #define PG8_WAIT_V(n) asm volatile("s_waitcnt vmcnt(" #n ")" ::: "memory")
; #define PG8_WAIT_L(n) asm volatile("s_waitcnt lgkmcnt(" #n ")" ::: "memory")
; #define PG8_BAR __builtin_amdgcn_s_barrier()
; #define PG8_SCHED __builtin_amdgcn_sched_barrier(0)
; template <class Epi, class Sched, bool ALIGN_EPI = false, bool SP2 = false>
; __device__ __forceinline__ void gemm_phase(PG8_LAS unsigned char* lds, const Gemm g, const Sched& S, const Epi& E) {
;     ...
;             PG8_LDA(At, 1, 1); PG8_STAGE(PG8_SB(1, 0), b3, voffB); PG8_STAGE(PG8_SB(1, 1), b3 + hstepB, voffB); PG8_STAGE(PG8_SA(1, 0), a3, voffA);
;             PG8_WAIT_V(8); PG8_WAIT_L(0); PG8_BAR; PG8_MMA(1, 0, At, B0); PG8_MMA(1, 1, At, B1); PG8_BAR; PG8_SCHED;
	s_setprio 0
	s_add_i32 s30, s58, s36
	v_lshl_add_u64 v[184:185], v[184:185], 0, s[8:9]
	s_mov_b32 m0, s30
	ds_read_b128 v[188:191], v149 offset:49152
	ds_read_b128 v[192:195], v149 offset:50176
	ds_read_b128 v[196:199], v149 offset:51200
	ds_read_b128 v[200:203], v149 offset:52224
	ds_read_b128 v[204:207], v149 offset:53248
	ds_read_b128 v[208:211], v149 offset:54272
	ds_read_b128 v[212:215], v149 offset:55296
	ds_read_b128 v[216:219], v149 offset:56320
	global_load_lds_dwordx4 v[184:185], off
	s_add_i32 m0, s30, 0x2000
	s_add_u32 s28, s28, 0x40080
	v_lshl_add_u64 v[184:185], v[220:221], 0, s[8:9]
	s_addc_u32 s29, s29, 0
	s_add_i32 s30, s59, s36
	global_load_lds_dwordx4 v[184:185], off
	v_lshl_add_u64 v[184:185], s[28:29], 0, v[132:133]
	s_mov_b32 m0, s30
	s_nop 0
	global_load_lds_dwordx4 v[184:185], off
	v_lshl_add_u64 v[184:185], s[28:29], 0, v[128:129]
	s_add_i32 m0, s30, 0x2000
	s_nop 0
	global_load_lds_dwordx4 v[184:185], off
	v_lshl_add_u64 v[184:185], v[222:223], 0, s[8:9]
	s_mov_b32 m0, s43
	s_nop 0
	global_load_lds_dwordx4 v[184:185], off
	v_lshl_add_u64 v[184:185], v[224:225], 0, s[8:9]
	s_mov_b32 m0, s44
	s_nop 0
	global_load_lds_dwordx4 v[184:185], off
	s_waitcnt vmcnt(8) lgkmcnt(0)
	s_barrier
	s_setprio 1
	v_mfma_f32_16x16x32_bf16 v[60:63], v[152:155], v[188:191], v[60:63]
	v_mfma_f32_16x16x32_bf16 v[52:55], v[160:163], v[188:191], v[52:55]
	v_mfma_f32_16x16x32_bf16 v[44:47], v[152:155], v[196:199], v[44:47]
	v_mfma_f32_16x16x32_bf16 v[36:39], v[160:163], v[196:199], v[36:39]
	v_mfma_f32_16x16x32_bf16 v[28:31], v[152:155], v[204:207], v[28:31]
	v_mfma_f32_16x16x32_bf16 v[20:23], v[160:163], v[204:207], v[20:23]
	v_mfma_f32_16x16x32_bf16 v[12:15], v[152:155], v[212:215], v[12:15]
	v_mfma_f32_16x16x32_bf16 v[4:7], v[160:163], v[212:215], v[4:7]
	v_mfma_f32_16x16x32_bf16 v[60:63], v[156:159], v[192:195], v[60:63]
	v_mfma_f32_16x16x32_bf16 v[52:55], v[164:167], v[192:195], v[52:55]
	v_mfma_f32_16x16x32_bf16 v[44:47], v[156:159], v[200:203], v[44:47]
	v_mfma_f32_16x16x32_bf16 v[36:39], v[164:167], v[200:203], v[36:39]
	v_mfma_f32_16x16x32_bf16 v[28:31], v[156:159], v[208:211], v[28:31]
	v_mfma_f32_16x16x32_bf16 v[20:23], v[164:167], v[208:211], v[20:23]
	v_mfma_f32_16x16x32_bf16 v[12:15], v[156:159], v[216:219], v[12:15]
	v_mfma_f32_16x16x32_bf16 v[4:7], v[164:167], v[216:219], v[4:7]
	s_setprio 0
	s_setprio 1
	v_mfma_f32_16x16x32_bf16 v[56:59], v[168:171], v[188:191], v[56:59]
	v_mfma_f32_16x16x32_bf16 v[48:51], v[176:179], v[188:191], v[48:51]
	v_mfma_f32_16x16x32_bf16 v[40:43], v[168:171], v[196:199], v[40:43]
	v_mfma_f32_16x16x32_bf16 v[32:35], v[176:179], v[196:199], v[32:35]
	v_mfma_f32_16x16x32_bf16 v[24:27], v[168:171], v[204:207], v[24:27]
	v_mfma_f32_16x16x32_bf16 v[16:19], v[176:179], v[204:207], v[16:19]
	v_mfma_f32_16x16x32_bf16 v[8:11], v[168:171], v[212:215], v[8:11]
	v_mfma_f32_16x16x32_bf16 v[0:3], v[176:179], v[212:215], v[0:3]
	v_mfma_f32_16x16x32_bf16 v[56:59], v[172:175], v[192:195], v[56:59]
	v_mfma_f32_16x16x32_bf16 v[48:51], v[180:183], v[192:195], v[48:51]
	v_mfma_f32_16x16x32_bf16 v[40:43], v[172:175], v[200:203], v[40:43]
	v_mfma_f32_16x16x32_bf16 v[32:35], v[180:183], v[200:203], v[32:35]
	v_mfma_f32_16x16x32_bf16 v[24:27], v[172:175], v[208:211], v[24:27]
	v_mfma_f32_16x16x32_bf16 v[16:19], v[180:183], v[208:211], v[16:19]
	v_mfma_f32_16x16x32_bf16 v[8:11], v[172:175], v[216:219], v[8:11]
	v_mfma_f32_16x16x32_bf16 v[0:3], v[180:183], v[216:219], v[0:3]
	s_barrier
	s_setprio 0
	s_add_i32 s68, s68, 2
	s_add_u32 s26, s26, 0x100
	s_addc_u32 s27, s27, 0
	s_add_u32 s66, s66, 0x100
	s_addc_u32 s67, s67, 0
	s_cmp_gt_u32 s68, 13
	s_cbranch_scc0 .LBB0_244
	s_and_b64 vcc, exec, s[10:11]
	s_cbranch_vccz .LBB0_247
	s_barrier

; #define PG8_STAGE(bufoff, gbase, voff) do { _Pragma("unroll") for (int _i = 0; _i < 2; ++_i) \
;         __builtin_amdgcn_global_load_lds((const unsigned*)((const char*)(gbase) + (voff)[_i]), (PG8_LAS unsigned*)(lds + (bufoff) + ldsw + _i * 8192), 16, 0, 0); } while (0)
; #define PG8_LDA(dst, b, h) do { _Pragma("unroll") for (int m = 0; m < 4; ++m) _Pragma("unroll") for (int k = 0; k < 2; ++k) dst[m][k] = *(const PG8_LAS bf16x8*)(lds + PG8_SA(b, h) + aoff + m * 2048 + k * 1024); } while (0)
; #define PG8_LDB(dst, b, h) do { _Pragma("unroll") for (int n = 0; n < 2; ++n) _Pragma("unroll") for (int k = 0; k < 2; ++k) dst[n][k] = *(const PG8_LAS bf16x8*)(lds + PG8_SB(b, h) + boff + n * 2048 + k * 1024); } while (0)
; #define PG8_MMA(ai, bj, At, Bt) do { __builtin_amdgcn_s_setprio(1); _Pragma("unroll") for (int m = 0; m < 4; ++m) _Pragma("unroll") for (int n = 0; n < 2; ++n) _Pragma("unroll") for (int k = 0; k < 2; ++k) \
;         acc[ai][bj][m][n] = __builtin_amdgcn_mfma_f32_16x16x32_bf16(Bt[n][k], At[m][k], acc[ai][bj][m][n], 0, 0, 0); __builtin_amdgcn_s_setprio(0); } while (0)
; #define PG8_WAIT_V(n) asm volatile("s_waitcnt vmcnt(" #n ")" ::: "memory")
; #define PG8_WAIT_L(n) asm volatile("s_waitcnt lgkmcnt(" #n ")" ::: "memory")
; #define PG8_BAR __builtin_amdgcn_s_barrier()
; template <class Epi, class Sched, bool ALIGN_EPI = false, bool SP2 = false>
; __device__ __forceinline__ void gemm_phase(PG8_LAS unsigned char* lds, const Gemm g, const Sched& S, const Epi& E) {
;     ...
;             const char* a1 = cA + (size_t)(t + 1) * kstep;
;             const char* a2 = last ? nA : cA + (size_t)(t + 2) * kstep; const char* b2 = last ? nB : cB + (size_t)(t + 2) * kstep;
;             const char* a3 = a2 + kstep; const char* b3 = b2 + kstep;
;             if (last && has_next) S.a_ready(nxt);
;             if constexpr (SP2) {
;             PG8_LDB(B0, 0, 0); PG8_LDB(B1, 0, 1); PG8_SCHED; PG8_LDA(At, 0, 0); PG8_STAGE(PG8_SA(1, 1), a1 + hstepA, voffA);
;             PG8_WAIT_V(8); PG8_WAIT_L(0); PG8_BAR; PG8_MMA(0, 0, At, B0); PG8_MMA(0, 1, At, B1); PG8_BAR; PG8_SCHED;
;             PG8_LDA(At, 0, 1); PG8_STAGE(PG8_SB(0, 0), b2, voffB); PG8_STAGE(PG8_SB(0, 1), b2 + hstepB, voffB); PG8_STAGE(PG8_SA(0, 0), a2, voffA);
;             PG8_WAIT_V(8); PG8_WAIT_L(0); PG8_BAR; PG8_MMA(1, 0, At, B0); PG8_MMA(1, 1, At, B1); PG8_BAR; PG8_SCHED;
.LBB0_318:
	ds_read_b128 v[128:131], v191
	ds_read_b128 v[132:135], v191 offset:1024
	ds_read_b128 v[136:139], v191 offset:2048
	ds_read_b128 v[140:143], v191 offset:3072
	ds_read_b128 v[144:147], v192
	ds_read_b128 v[148:151], v192 offset:1024
	ds_read_b128 v[168:171], v192 offset:2048
	ds_read_b128 v[172:175], v192 offset:3072
	s_add_u32 s28, s26, 0x100
	s_addc_u32 s29, s27, 0
	s_cmp_eq_u32 s72, 40
	s_cselect_b32 s35, s11, s29
	s_cselect_b32 s34, s10, s28
	s_cselect_b32 s31, s23, s71
	s_cselect_b32 s30, s22, s70
	v_lshl_add_u64 v[184:185], s[26:27], 0, v[160:161]
	s_add_i32 m0, s39, 0xc000
	ds_read_b128 v[176:179], v193
	ds_read_b128 v[180:183], v193 offset:1024
	ds_read_b128 v[196:199], v193 offset:2048
	ds_read_b128 v[200:203], v193 offset:3072
	ds_read_b128 v[204:207], v193 offset:4096
	ds_read_b128 v[208:211], v193 offset:5120
	ds_read_b128 v[212:215], v193 offset:6144
	ds_read_b128 v[216:219], v193 offset:7168
	global_load_lds_dwordx4 v[184:185], off
	v_lshl_add_u64 v[184:185], s[26:27], 0, v[162:163]
	s_add_i32 m0, s39, 0xe000
	s_nop 0
	global_load_lds_dwordx4 v[184:185], off
	s_waitcnt vmcnt(8) lgkmcnt(0)
	s_barrier
	s_setprio 1
	v_mfma_f32_16x16x32_bf16 v[124:127], v[128:131], v[176:179], v[124:127]
	v_mfma_f32_16x16x32_bf16 v[120:123], v[136:139], v[176:179], v[120:123]
	v_mfma_f32_16x16x32_bf16 v[108:111], v[128:131], v[196:199], v[108:111]
	v_mfma_f32_16x16x32_bf16 v[104:107], v[136:139], v[196:199], v[104:107]
	v_mfma_f32_16x16x32_bf16 v[92:95], v[128:131], v[204:207], v[92:95]
	v_mfma_f32_16x16x32_bf16 v[88:91], v[136:139], v[204:207], v[88:91]
	v_mfma_f32_16x16x32_bf16 v[76:79], v[128:131], v[212:215], v[76:79]
	v_mfma_f32_16x16x32_bf16 v[72:75], v[136:139], v[212:215], v[72:75]
	v_mfma_f32_16x16x32_bf16 v[124:127], v[132:135], v[180:183], v[124:127]
	v_mfma_f32_16x16x32_bf16 v[120:123], v[140:143], v[180:183], v[120:123]
	v_mfma_f32_16x16x32_bf16 v[108:111], v[132:135], v[200:203], v[108:111]
	v_mfma_f32_16x16x32_bf16 v[104:107], v[140:143], v[200:203], v[104:107]
	v_mfma_f32_16x16x32_bf16 v[92:95], v[132:135], v[208:211], v[92:95]
	v_mfma_f32_16x16x32_bf16 v[88:91], v[140:143], v[208:211], v[88:91]
	v_mfma_f32_16x16x32_bf16 v[76:79], v[132:135], v[216:219], v[76:79]
	v_mfma_f32_16x16x32_bf16 v[72:75], v[140:143], v[216:219], v[72:75]
	s_setprio 0
	s_setprio 1
	v_mfma_f32_16x16x32_bf16 v[116:119], v[144:147], v[176:179], v[116:119]
	v_mfma_f32_16x16x32_bf16 v[112:115], v[168:171], v[176:179], v[112:115]
	v_mfma_f32_16x16x32_bf16 v[100:103], v[144:147], v[196:199], v[100:103]
	v_mfma_f32_16x16x32_bf16 v[96:99], v[168:171], v[196:199], v[96:99]
	v_mfma_f32_16x16x32_bf16 v[84:87], v[144:147], v[204:207], v[84:87]
	v_mfma_f32_16x16x32_bf16 v[80:83], v[168:171], v[204:207], v[80:83]
	v_mfma_f32_16x16x32_bf16 v[68:71], v[144:147], v[212:215], v[68:71]
	v_mfma_f32_16x16x32_bf16 v[64:67], v[168:171], v[212:215], v[64:67]
	v_mfma_f32_16x16x32_bf16 v[116:119], v[148:151], v[180:183], v[116:119]
	v_mfma_f32_16x16x32_bf16 v[112:115], v[172:175], v[180:183], v[112:115]
	v_mfma_f32_16x16x32_bf16 v[100:103], v[148:151], v[200:203], v[100:103]
	v_mfma_f32_16x16x32_bf16 v[96:99], v[172:175], v[200:203], v[96:99]
	v_mfma_f32_16x16x32_bf16 v[84:87], v[148:151], v[208:211], v[84:87]
	v_mfma_f32_16x16x32_bf16 v[80:83], v[172:175], v[208:211], v[80:83]
	v_mfma_f32_16x16x32_bf16 v[68:71], v[148:151], v[216:219], v[68:71]
	v_mfma_f32_16x16x32_bf16 v[64:67], v[172:175], v[216:219], v[64:67]
	s_barrier
	s_setprio 0
	s_nop 0
	s_add_i32 s26, s49, s38
	v_lshl_add_u64 v[184:185], s[30:31], 0, v[154:155]
	s_mov_b32 m0, s26
	ds_read_b128 v[176:179], v193 offset:16384
	ds_read_b128 v[180:183], v193 offset:17408
	ds_read_b128 v[196:199], v193 offset:18432
	ds_read_b128 v[200:203], v193 offset:19456
	ds_read_b128 v[204:207], v193 offset:20480
	ds_read_b128 v[208:211], v193 offset:21504
	ds_read_b128 v[212:215], v193 offset:22528
	ds_read_b128 v[216:219], v193 offset:23552
	global_load_lds_dwordx4 v[184:185], off
	s_add_i32 m0, s26, 0x2000
	s_add_u32 s26, s30, 0xb0000
	v_lshl_add_u64 v[220:221], s[30:31], 0, v[158:159]
	s_addc_u32 s27, s31, 0
	s_add_i32 s58, s62, s38
	global_load_lds_dwordx4 v[220:221], off
	v_lshl_add_u64 v[222:223], s[26:27], 0, v[154:155]
	s_mov_b32 m0, s58
	v_lshl_add_u64 v[224:225], s[34:35], 0, v[156:157]
	global_load_lds_dwordx4 v[222:223], off
	v_lshl_add_u64 v[222:223], s[26:27], 0, v[158:159]
	s_add_i32 m0, s58, 0x2000
	s_nop 0
	global_load_lds_dwordx4 v[222:223], off
	v_lshl_add_u64 v[222:223], s[34:35], 0, v[152:153]
	s_mov_b32 m0, s39
	s_nop 0
	global_load_lds_dwordx4 v[222:223], off
	s_mov_b32 m0, s40
	s_nop 0
	global_load_lds_dwordx4 v[224:225], off
	s_waitcnt vmcnt(8) lgkmcnt(0)
	s_barrier
; #define PG8_STAGE(bufoff, gbase, voff) do { _Pragma("unroll") for (int _i = 0; _i < 2; ++_i) \
;         __builtin_amdgcn_global_load_lds((const unsigned*)((const char*)(gbase) + (voff)[_i]), (PG8_LAS unsigned*)(lds + (bufoff) + ldsw + _i * 8192), 16, 0, 0); } while (0)
; #define PG8_LDA(dst, b, h) do { _Pragma("unroll") for (int m = 0; m < 4; ++m) _Pragma("unroll") for (int k = 0; k < 2; ++k) dst[m][k] = *(const PG8_LAS bf16x8*)(lds + PG8_SA(b, h) + aoff + m * 2048 + k * 1024); } while (0)
; #define PG8_LDB(dst, b, h) do { _Pragma("unroll") for (int n = 0; n < 2; ++n) _Pragma("unroll") for (int k = 0; k < 2; ++k) dst[n][k] = *(const PG8_LAS bf16x8*)(lds + PG8_SB(b, h) + boff + n * 2048 + k * 1024); } while (0)
; #define PG8_MMA(ai, bj, At, Bt) do { __builtin_amdgcn_s_setprio(1); _Pragma("unroll") for (int m = 0; m < 4; ++m) _Pragma("unroll") for (int n = 0; n < 2; ++n) _Pragma("unroll") for (int k = 0; k < 2; ++k) \
;         acc[ai][bj][m][n] = __builtin_amdgcn_mfma_f32_16x16x32_bf16(Bt[n][k], At[m][k], acc[ai][bj][m][n], 0, 0, 0); __builtin_amdgcn_s_setprio(0); } while (0)
; #define PG8_WAIT_V(n) asm volatile("s_waitcnt vmcnt(" #n ")" ::: "memory")
; #define PG8_WAIT_L(n) asm volatile("s_waitcnt lgkmcnt(" #n ")" ::: "memory")
; #define PG8_BAR __builtin_amdgcn_s_barrier()
; #define PG8_SCHED __builtin_amdgcn_sched_barrier(0)
; template <class Epi, class Sched, bool ALIGN_EPI = false, bool SP2 = false>
; __device__ __forceinline__ void gemm_phase(PG8_LAS unsigned char* lds, const Gemm g, const Sched& S, const Epi& E) {
;     ...
;             PG8_WAIT_V(8); PG8_WAIT_L(0); PG8_BAR; PG8_MMA(1, 0, At, B0); PG8_MMA(1, 1, At, B1); PG8_BAR; PG8_SCHED;
;             PG8_LDB(B0, 1, 0); PG8_LDB(B1, 1, 1); PG8_SCHED; PG8_LDA(At, 1, 0); PG8_STAGE(PG8_SA(0, 1), a2 + hstepA, voffA);
;             PG8_WAIT_V(8); PG8_WAIT_L(0); PG8_BAR; PG8_MMA(0, 0, At, B0); PG8_MMA(0, 1, At, B1); PG8_BAR; PG8_SCHED;
	s_setprio 1
	v_mfma_f32_16x16x32_bf16 v[60:63], v[128:131], v[176:179], v[60:63]
	v_mfma_f32_16x16x32_bf16 v[56:59], v[136:139], v[176:179], v[56:59]
	v_mfma_f32_16x16x32_bf16 v[44:47], v[128:131], v[196:199], v[44:47]
	v_mfma_f32_16x16x32_bf16 v[40:43], v[136:139], v[196:199], v[40:43]
	v_mfma_f32_16x16x32_bf16 v[28:31], v[128:131], v[204:207], v[28:31]
	v_mfma_f32_16x16x32_bf16 v[24:27], v[136:139], v[204:207], v[24:27]
	v_mfma_f32_16x16x32_bf16 v[12:15], v[128:131], v[212:215], v[12:15]
	v_mfma_f32_16x16x32_bf16 v[8:11], v[136:139], v[212:215], v[8:11]
	v_mfma_f32_16x16x32_bf16 v[60:63], v[132:135], v[180:183], v[60:63]
	v_mfma_f32_16x16x32_bf16 v[56:59], v[140:143], v[180:183], v[56:59]
	v_mfma_f32_16x16x32_bf16 v[44:47], v[132:135], v[200:203], v[44:47]
	v_mfma_f32_16x16x32_bf16 v[40:43], v[140:143], v[200:203], v[40:43]
	v_mfma_f32_16x16x32_bf16 v[28:31], v[132:135], v[208:211], v[28:31]
	v_mfma_f32_16x16x32_bf16 v[24:27], v[140:143], v[208:211], v[24:27]
	v_mfma_f32_16x16x32_bf16 v[12:15], v[132:135], v[216:219], v[12:15]
	v_mfma_f32_16x16x32_bf16 v[8:11], v[140:143], v[216:219], v[8:11]
	s_setprio 0
	s_setprio 1
	v_mfma_f32_16x16x32_bf16 v[52:55], v[144:147], v[176:179], v[52:55]
	v_mfma_f32_16x16x32_bf16 v[48:51], v[168:171], v[176:179], v[48:51]
	v_mfma_f32_16x16x32_bf16 v[36:39], v[144:147], v[196:199], v[36:39]
	v_mfma_f32_16x16x32_bf16 v[32:35], v[168:171], v[196:199], v[32:35]
	v_mfma_f32_16x16x32_bf16 v[20:23], v[144:147], v[204:207], v[20:23]
	v_mfma_f32_16x16x32_bf16 v[16:19], v[168:171], v[204:207], v[16:19]
	v_mfma_f32_16x16x32_bf16 v[4:7], v[144:147], v[212:215], v[4:7]
	v_mfma_f32_16x16x32_bf16 v[0:3], v[168:171], v[212:215], v[0:3]
	v_mfma_f32_16x16x32_bf16 v[52:55], v[148:151], v[180:183], v[52:55]
	v_mfma_f32_16x16x32_bf16 v[48:51], v[172:175], v[180:183], v[48:51]
	v_mfma_f32_16x16x32_bf16 v[36:39], v[148:151], v[200:203], v[36:39]
	v_mfma_f32_16x16x32_bf16 v[32:35], v[172:175], v[200:203], v[32:35]
	v_mfma_f32_16x16x32_bf16 v[20:23], v[148:151], v[208:211], v[20:23]
	v_mfma_f32_16x16x32_bf16 v[16:19], v[172:175], v[208:211], v[16:19]
	v_mfma_f32_16x16x32_bf16 v[4:7], v[148:151], v[216:219], v[4:7]
	v_mfma_f32_16x16x32_bf16 v[0:3], v[172:175], v[216:219], v[0:3]
	s_barrier
	s_setprio 0
	s_nop 0
	s_add_i32 s58, 0, 0x18000
	s_add_i32 s59, 0, 0x1c000
	v_add_u32_e32 v140, s58, v189
	v_add_u32_e32 v172, s59, v189
	ds_read_b128 v[128:131], v140
	ds_read_b128 v[132:135], v140 offset:1024
	ds_read_b128 v[136:139], v140 offset:2048
	ds_read_b128 v[140:143], v140 offset:3072
	ds_read_b128 v[144:147], v172
	ds_read_b128 v[148:151], v172 offset:1024
	ds_read_b128 v[168:171], v172 offset:2048
	ds_read_b128 v[172:175], v172 offset:3072
	s_add_u32 s26, s34, 0xb0000
	s_addc_u32 s27, s35, 0
	s_mov_b32 m0, s41
	v_lshl_add_u64 v[226:227], s[26:27], 0, v[152:153]
	ds_read_b128 v[176:179], v193 offset:32768
	ds_read_b128 v[180:183], v193 offset:33792
	ds_read_b128 v[196:199], v193 offset:34816
	ds_read_b128 v[200:203], v193 offset:35840
	ds_read_b128 v[204:207], v193 offset:36864
	ds_read_b128 v[208:211], v193 offset:37888
	ds_read_b128 v[212:215], v193 offset:38912
	ds_read_b128 v[216:219], v193 offset:39936
	global_load_lds_dwordx4 v[226:227], off
	v_lshl_add_u64 v[226:227], s[26:27], 0, v[156:157]
	s_mov_b32 m0, s42
	s_nop 0
	global_load_lds_dwordx4 v[226:227], off
	s_waitcnt vmcnt(8) lgkmcnt(0)
	s_barrier
	s_setprio 1
	v_mfma_f32_16x16x32_bf16 v[124:127], v[128:131], v[176:179], v[124:127]
	v_mfma_f32_16x16x32_bf16 v[120:123], v[136:139], v[176:179], v[120:123]
	v_mfma_f32_16x16x32_bf16 v[108:111], v[128:131], v[196:199], v[108:111]
	v_mfma_f32_16x16x32_bf16 v[104:107], v[136:139], v[196:199], v[104:107]
	v_mfma_f32_16x16x32_bf16 v[92:95], v[128:131], v[204:207], v[92:95]
	v_mfma_f32_16x16x32_bf16 v[88:91], v[136:139], v[204:207], v[88:91]
	v_mfma_f32_16x16x32_bf16 v[76:79], v[128:131], v[212:215], v[76:79]
	v_mfma_f32_16x16x32_bf16 v[72:75], v[136:139], v[212:215], v[72:75]
	v_mfma_f32_16x16x32_bf16 v[124:127], v[132:135], v[180:183], v[124:127]
	v_mfma_f32_16x16x32_bf16 v[120:123], v[140:143], v[180:183], v[120:123]
	v_mfma_f32_16x16x32_bf16 v[108:111], v[132:135], v[200:203], v[108:111]
	v_mfma_f32_16x16x32_bf16 v[104:107], v[140:143], v[200:203], v[104:107]
	v_mfma_f32_16x16x32_bf16 v[92:95], v[132:135], v[208:211], v[92:95]
	v_mfma_f32_16x16x32_bf16 v[88:91], v[140:143], v[208:211], v[88:91]
	v_mfma_f32_16x16x32_bf16 v[76:79], v[132:135], v[216:219], v[76:79]
	v_mfma_f32_16x16x32_bf16 v[72:75], v[140:143], v[216:219], v[72:75]
	s_setprio 0
	s_setprio 1
	v_mfma_f32_16x16x32_bf16 v[116:119], v[144:147], v[176:179], v[116:119]
	v_mfma_f32_16x16x32_bf16 v[112:115], v[168:171], v[176:179], v[112:115]
	v_mfma_f32_16x16x32_bf16 v[100:103], v[144:147], v[196:199], v[100:103]
	v_mfma_f32_16x16x32_bf16 v[96:99], v[168:171], v[196:199], v[96:99]
	v_mfma_f32_16x16x32_bf16 v[84:87], v[144:147], v[204:207], v[84:87]
	v_mfma_f32_16x16x32_bf16 v[80:83], v[168:171], v[204:207], v[80:83]
	v_mfma_f32_16x16x32_bf16 v[68:71], v[144:147], v[212:215], v[68:71]
	v_mfma_f32_16x16x32_bf16 v[64:67], v[168:171], v[212:215], v[64:67]
	v_mfma_f32_16x16x32_bf16 v[116:119], v[148:151], v[180:183], v[116:119]
	v_mfma_f32_16x16x32_bf16 v[112:115], v[172:175], v[180:183], v[112:115]
	v_mfma_f32_16x16x32_bf16 v[100:103], v[148:151], v[200:203], v[100:103]
	v_mfma_f32_16x16x32_bf16 v[96:99], v[172:175], v[200:203], v[96:99]
	v_mfma_f32_16x16x32_bf16 v[84:87], v[148:151], v[208:211], v[84:87]
	v_mfma_f32_16x16x32_bf16 v[80:83], v[172:175], v[208:211], v[80:83]
	v_mfma_f32_16x16x32_bf16 v[68:71], v[148:151], v[216:219], v[68:71]
	v_mfma_f32_16x16x32_bf16 v[64:67], v[172:175], v[216:219], v[64:67]
	s_barrier
; #define PG8_STAGE(bufoff, gbase, voff) do { _Pragma("unroll") for (int _i = 0; _i < 2; ++_i) \
;         __builtin_amdgcn_global_load_lds((const unsigned*)((const char*)(gbase) + (voff)[_i]), (PG8_LAS unsigned*)(lds + (bufoff) + ldsw + _i * 8192), 16, 0, 0); } while (0)
; #define PG8_LDA(dst, b, h) do { _Pragma("unroll") for (int m = 0; m < 4; ++m) _Pragma("unroll") for (int k = 0; k < 2; ++k) dst[m][k] = *(const PG8_LAS bf16x8*)(lds + PG8_SA(b, h) + aoff + m * 2048 + k * 1024); } while (0)
; #define PG8_MMA(ai, bj, At, Bt) do { __builtin_amdgcn_s_setprio(1); _Pragma("unroll") for (int m = 0; m < 4; ++m) _Pragma("unroll") for (int n = 0; n < 2; ++n) _Pragma("unroll") for (int k = 0; k < 2; ++k) \
;         acc[ai][bj][m][n] = __builtin_amdgcn_mfma_f32_16x16x32_bf16(Bt[n][k], At[m][k], acc[ai][bj][m][n], 0, 0, 0); __builtin_amdgcn_s_setprio(0); } while (0)
; #define PG8_WAIT_V(n) asm volatile("s_waitcnt vmcnt(" #n ")" ::: "memory")
; #define PG8_WAIT_L(n) asm volatile("s_waitcnt lgkmcnt(" #n ")" ::: "memory")
; #define PG8_BAR __builtin_amdgcn_s_barrier()
; #define PG8_SCHED __builtin_amdgcn_sched_barrier(0)
; template <class Epi, class Sched, bool ALIGN_EPI = false, bool SP2 = false>
; __device__ __forceinline__ void gemm_phase(PG8_LAS unsigned char* lds, const Gemm g, const Sched& S, const Epi& E) {
;     ...
;             PG8_LDA(At, 1, 1); PG8_STAGE(PG8_SB(1, 0), b3, voffB); PG8_STAGE(PG8_SB(1, 1), b3 + hstepB, voffB); PG8_STAGE(PG8_SA(1, 0), a3, voffA);
;             PG8_WAIT_V(8); PG8_WAIT_L(0); PG8_BAR; PG8_MMA(1, 0, At, B0); PG8_MMA(1, 1, At, B1); PG8_BAR; PG8_SCHED;
	s_setprio 0
	s_add_i32 s26, s58, s38
	v_lshl_add_u64 v[184:185], v[184:185], 0, s[14:15]
	s_mov_b32 m0, s26
	ds_read_b128 v[176:179], v193 offset:49152
	ds_read_b128 v[180:183], v193 offset:50176
	ds_read_b128 v[196:199], v193 offset:51200
	ds_read_b128 v[200:203], v193 offset:52224
	ds_read_b128 v[204:207], v193 offset:53248
	ds_read_b128 v[208:211], v193 offset:54272
	ds_read_b128 v[212:215], v193 offset:55296
	ds_read_b128 v[216:219], v193 offset:56320
	global_load_lds_dwordx4 v[184:185], off
	s_add_i32 m0, s26, 0x2000
	s_add_u32 s26, s30, 0xb0080
	v_lshl_add_u64 v[184:185], v[220:221], 0, s[14:15]
	s_addc_u32 s27, s31, 0
	s_add_i32 s30, s59, s38
	global_load_lds_dwordx4 v[184:185], off
	v_lshl_add_u64 v[184:185], s[26:27], 0, v[154:155]
	s_mov_b32 m0, s30
	s_nop 0
	global_load_lds_dwordx4 v[184:185], off
	v_lshl_add_u64 v[184:185], s[26:27], 0, v[158:159]
	s_add_i32 m0, s30, 0x2000
	s_nop 0
	global_load_lds_dwordx4 v[184:185], off
	v_lshl_add_u64 v[184:185], v[222:223], 0, s[14:15]
	s_mov_b32 m0, s44
	s_nop 0
	global_load_lds_dwordx4 v[184:185], off
	v_lshl_add_u64 v[184:185], v[224:225], 0, s[14:15]
	s_mov_b32 m0, s45
	s_nop 0
	global_load_lds_dwordx4 v[184:185], off
	s_waitcnt vmcnt(8) lgkmcnt(0)
	s_barrier
	s_setprio 1
	v_mfma_f32_16x16x32_bf16 v[60:63], v[128:131], v[176:179], v[60:63]
	v_mfma_f32_16x16x32_bf16 v[56:59], v[136:139], v[176:179], v[56:59]
	v_mfma_f32_16x16x32_bf16 v[44:47], v[128:131], v[196:199], v[44:47]
	v_mfma_f32_16x16x32_bf16 v[40:43], v[136:139], v[196:199], v[40:43]
	v_mfma_f32_16x16x32_bf16 v[28:31], v[128:131], v[204:207], v[28:31]
	v_mfma_f32_16x16x32_bf16 v[24:27], v[136:139], v[204:207], v[24:27]
	v_mfma_f32_16x16x32_bf16 v[12:15], v[128:131], v[212:215], v[12:15]
	v_mfma_f32_16x16x32_bf16 v[8:11], v[136:139], v[212:215], v[8:11]
	v_mfma_f32_16x16x32_bf16 v[60:63], v[132:135], v[180:183], v[60:63]
	v_mfma_f32_16x16x32_bf16 v[56:59], v[140:143], v[180:183], v[56:59]
	v_mfma_f32_16x16x32_bf16 v[44:47], v[132:135], v[200:203], v[44:47]
	v_mfma_f32_16x16x32_bf16 v[40:43], v[140:143], v[200:203], v[40:43]
	v_mfma_f32_16x16x32_bf16 v[28:31], v[132:135], v[208:211], v[28:31]
	v_mfma_f32_16x16x32_bf16 v[24:27], v[140:143], v[208:211], v[24:27]
	v_mfma_f32_16x16x32_bf16 v[12:15], v[132:135], v[216:219], v[12:15]
	v_mfma_f32_16x16x32_bf16 v[8:11], v[140:143], v[216:219], v[8:11]
	s_setprio 0
	s_setprio 1
	v_mfma_f32_16x16x32_bf16 v[52:55], v[144:147], v[176:179], v[52:55]
	v_mfma_f32_16x16x32_bf16 v[48:51], v[168:171], v[176:179], v[48:51]
	v_mfma_f32_16x16x32_bf16 v[36:39], v[144:147], v[196:199], v[36:39]
	v_mfma_f32_16x16x32_bf16 v[32:35], v[168:171], v[196:199], v[32:35]
	v_mfma_f32_16x16x32_bf16 v[20:23], v[144:147], v[204:207], v[20:23]
	v_mfma_f32_16x16x32_bf16 v[16:19], v[168:171], v[204:207], v[16:19]
	v_mfma_f32_16x16x32_bf16 v[4:7], v[144:147], v[212:215], v[4:7]
	v_mfma_f32_16x16x32_bf16 v[0:3], v[168:171], v[212:215], v[0:3]
	v_mfma_f32_16x16x32_bf16 v[52:55], v[148:151], v[180:183], v[52:55]
	v_mfma_f32_16x16x32_bf16 v[48:51], v[172:175], v[180:183], v[48:51]
	v_mfma_f32_16x16x32_bf16 v[36:39], v[148:151], v[200:203], v[36:39]
	v_mfma_f32_16x16x32_bf16 v[32:35], v[172:175], v[200:203], v[32:35]
	v_mfma_f32_16x16x32_bf16 v[20:23], v[148:151], v[208:211], v[20:23]
	v_mfma_f32_16x16x32_bf16 v[16:19], v[172:175], v[208:211], v[16:19]
	v_mfma_f32_16x16x32_bf16 v[4:7], v[148:151], v[216:219], v[4:7]
	v_mfma_f32_16x16x32_bf16 v[0:3], v[172:175], v[216:219], v[0:3]
	s_barrier
	s_setprio 0
	s_add_i32 s72, s72, 2
	s_add_u32 s70, s70, 0x100
	s_addc_u32 s71, s71, 0
	s_cmp_gt_u32 s72, 41
	s_mov_b64 s[26:27], s[28:29]
	s_cbranch_scc0 .LBB0_318
	s_and_b64 vcc, exec, s[20:21]
	s_cbranch_vccz .LBB0_321
	s_barrier

; #define PG8_STAGE(bufoff, gbase, voff) do { _Pragma("unroll") for (int _i = 0; _i < 2; ++_i) \
;         __builtin_amdgcn_global_load_lds((const unsigned*)((const char*)(gbase) + (voff)[_i]), (PG8_LAS unsigned*)(lds + (bufoff) + ldsw + _i * 8192), 16, 0, 0); } while (0)
; #define PG8_LDA(dst, b, h) do { _Pragma("unroll") for (int m = 0; m < 4; ++m) _Pragma("unroll") for (int k = 0; k < 2; ++k) dst[m][k] = *(const PG8_LAS bf16x8*)(lds + PG8_SA(b, h) + aoff + m * 2048 + k * 1024); } while (0)
; #define PG8_LDB(dst, b, h) do { _Pragma("unroll") for (int n = 0; n < 2; ++n) _Pragma("unroll") for (int k = 0; k < 2; ++k) dst[n][k] = *(const PG8_LAS bf16x8*)(lds + PG8_SB(b, h) + boff + n * 2048 + k * 1024); } while (0)
; #define PG8_MMA(ai, bj, At, Bt) do { __builtin_amdgcn_s_setprio(1); _Pragma("unroll") for (int m = 0; m < 4; ++m) _Pragma("unroll") for (int n = 0; n < 2; ++n) _Pragma("unroll") for (int k = 0; k < 2; ++k) \
;         acc[ai][bj][m][n] = __builtin_amdgcn_mfma_f32_16x16x32_bf16(Bt[n][k], At[m][k], acc[ai][bj][m][n], 0, 0, 0); __builtin_amdgcn_s_setprio(0); } while (0)
; #define PG8_WAIT_V(n) asm volatile("s_waitcnt vmcnt(" #n ")" ::: "memory")
; #define PG8_WAIT_L(n) asm volatile("s_waitcnt lgkmcnt(" #n ")" ::: "memory")
; #define PG8_BAR __builtin_amdgcn_s_barrier()
; template <class Epi, class Sched, bool ALIGN_EPI = false, bool SP2 = false>
; __device__ __forceinline__ void gemm_phase(PG8_LAS unsigned char* lds, const Gemm g, const Sched& S, const Epi& E) {
;     ...
;             const char* a1 = cA + (size_t)(t + 1) * kstep;
;             const char* a2 = last ? nA : cA + (size_t)(t + 2) * kstep; const char* b2 = last ? nB : cB + (size_t)(t + 2) * kstep;
;             const char* a3 = a2 + kstep; const char* b3 = b2 + kstep;
;             if (last && has_next) S.a_ready(nxt);
;             if constexpr (SP2) {
;             PG8_LDB(B0, 0, 0); PG8_LDB(B1, 0, 1); PG8_SCHED; PG8_LDA(At, 0, 0); PG8_STAGE(PG8_SA(1, 1), a1 + hstepA, voffA);
;             PG8_WAIT_V(8); PG8_WAIT_L(0); PG8_BAR; PG8_MMA(0, 0, At, B0); PG8_MMA(0, 1, At, B1); PG8_BAR; PG8_SCHED;
;             PG8_LDA(At, 0, 1); PG8_STAGE(PG8_SB(0, 0), b2, voffB); PG8_STAGE(PG8_SB(0, 1), b2 + hstepB, voffB); PG8_STAGE(PG8_SA(0, 0), a2, voffA);
;             PG8_WAIT_V(8); PG8_WAIT_L(0); PG8_BAR; PG8_MMA(1, 0, At, B0); PG8_MMA(1, 1, At, B1); PG8_BAR; PG8_SCHED;
.LBB0_404:
	ds_read_b128 v[152:155], v165
	ds_read_b128 v[156:159], v165 offset:1024
	ds_read_b128 v[178:181], v165 offset:2048
	ds_read_b128 v[182:185], v165 offset:3072
	ds_read_b128 v[188:191], v166
	ds_read_b128 v[192:195], v166 offset:1024
	ds_read_b128 v[196:199], v166 offset:2048
	ds_read_b128 v[200:203], v166 offset:3072
	s_add_u32 s46, s14, 0xfffc0080
	s_addc_u32 s47, s15, -1
	s_cmp_eq_u32 s91, 12
	s_cselect_b32 s49, s11, s47
	s_cselect_b32 s48, s13, s46
	s_cselect_b32 s47, s39, s67
	s_cselect_b32 s46, s41, s66
	v_lshl_add_u64 v[160:161], s[14:15], 0, v[144:145]
	s_add_i32 m0, s71, 0xc000
	ds_read_b128 v[204:207], v167
	ds_read_b128 v[208:211], v167 offset:1024
	ds_read_b128 v[212:215], v167 offset:2048
	ds_read_b128 v[216:219], v167 offset:3072
	ds_read_b128 v[220:223], v167 offset:4096
	ds_read_b128 v[224:227], v167 offset:5120
	ds_read_b128 v[228:231], v167 offset:6144
	ds_read_b128 v[232:235], v167 offset:7168
	global_load_lds_dwordx4 v[160:161], off
	v_lshl_add_u64 v[160:161], s[14:15], 0, v[146:147]
	s_add_i32 m0, s71, 0xe000
	s_nop 0
	global_load_lds_dwordx4 v[160:161], off
	s_waitcnt vmcnt(8) lgkmcnt(0)
	s_barrier
	s_setprio 1
	v_mfma_f32_16x16x32_bf16 v[124:127], v[152:155], v[204:207], v[124:127]
	v_mfma_f32_16x16x32_bf16 v[120:123], v[178:181], v[204:207], v[120:123]
	v_mfma_f32_16x16x32_bf16 v[108:111], v[152:155], v[212:215], v[108:111]
	v_mfma_f32_16x16x32_bf16 v[104:107], v[178:181], v[212:215], v[104:107]
	v_mfma_f32_16x16x32_bf16 v[92:95], v[152:155], v[220:223], v[92:95]
	v_mfma_f32_16x16x32_bf16 v[88:91], v[178:181], v[220:223], v[88:91]
	v_mfma_f32_16x16x32_bf16 v[76:79], v[152:155], v[228:231], v[76:79]
	v_mfma_f32_16x16x32_bf16 v[72:75], v[178:181], v[228:231], v[72:75]
	v_mfma_f32_16x16x32_bf16 v[124:127], v[156:159], v[208:211], v[124:127]
	v_mfma_f32_16x16x32_bf16 v[120:123], v[182:185], v[208:211], v[120:123]
	v_mfma_f32_16x16x32_bf16 v[108:111], v[156:159], v[216:219], v[108:111]
	v_mfma_f32_16x16x32_bf16 v[104:107], v[182:185], v[216:219], v[104:107]
	v_mfma_f32_16x16x32_bf16 v[92:95], v[156:159], v[224:227], v[92:95]
	v_mfma_f32_16x16x32_bf16 v[88:91], v[182:185], v[224:227], v[88:91]
	v_mfma_f32_16x16x32_bf16 v[76:79], v[156:159], v[232:235], v[76:79]
	v_mfma_f32_16x16x32_bf16 v[72:75], v[182:185], v[232:235], v[72:75]
	s_setprio 0
	s_setprio 1
	v_mfma_f32_16x16x32_bf16 v[116:119], v[188:191], v[204:207], v[116:119]
	v_mfma_f32_16x16x32_bf16 v[112:115], v[196:199], v[204:207], v[112:115]
	v_mfma_f32_16x16x32_bf16 v[100:103], v[188:191], v[212:215], v[100:103]
	v_mfma_f32_16x16x32_bf16 v[96:99], v[196:199], v[212:215], v[96:99]
	v_mfma_f32_16x16x32_bf16 v[84:87], v[188:191], v[220:223], v[84:87]
	v_mfma_f32_16x16x32_bf16 v[80:83], v[196:199], v[220:223], v[80:83]
	v_mfma_f32_16x16x32_bf16 v[68:71], v[188:191], v[228:231], v[68:71]
	v_mfma_f32_16x16x32_bf16 v[64:67], v[196:199], v[228:231], v[64:67]
	v_mfma_f32_16x16x32_bf16 v[116:119], v[192:195], v[208:211], v[116:119]
	v_mfma_f32_16x16x32_bf16 v[112:115], v[200:203], v[208:211], v[112:115]
	v_mfma_f32_16x16x32_bf16 v[100:103], v[192:195], v[216:219], v[100:103]
	v_mfma_f32_16x16x32_bf16 v[96:99], v[200:203], v[216:219], v[96:99]
	v_mfma_f32_16x16x32_bf16 v[84:87], v[192:195], v[224:227], v[84:87]
	v_mfma_f32_16x16x32_bf16 v[80:83], v[200:203], v[224:227], v[80:83]
	v_mfma_f32_16x16x32_bf16 v[68:71], v[192:195], v[232:235], v[68:71]
	v_mfma_f32_16x16x32_bf16 v[64:67], v[200:203], v[232:235], v[64:67]
	s_barrier
	s_setprio 0
	s_nop 0
	s_add_i32 s58, s83, s70
	v_lshl_add_u64 v[160:161], s[46:47], 0, v[130:131]
	s_mov_b32 m0, s58
	ds_read_b128 v[204:207], v167 offset:16384
	ds_read_b128 v[208:211], v167 offset:17408
	ds_read_b128 v[212:215], v167 offset:18432
	ds_read_b128 v[216:219], v167 offset:19456
	ds_read_b128 v[220:223], v167 offset:20480
	ds_read_b128 v[224:227], v167 offset:21504
	ds_read_b128 v[228:231], v167 offset:22528
	ds_read_b128 v[232:235], v167 offset:23552
	global_load_lds_dwordx4 v[160:161], off
	s_add_i32 m0, s58, 0x2000
	s_add_u32 s58, s46, 0x40000
	v_lshl_add_u64 v[236:237], s[46:47], 0, v[134:135]
	s_addc_u32 s59, s47, 0
	s_add_i32 s92, s84, s70
	global_load_lds_dwordx4 v[236:237], off
	v_lshl_add_u64 v[238:239], s[58:59], 0, v[130:131]
	s_mov_b32 m0, s92
	v_lshl_add_u64 v[240:241], s[48:49], 0, v[132:133]
	global_load_lds_dwordx4 v[238:239], off
	v_lshl_add_u64 v[238:239], s[58:59], 0, v[134:135]
	s_add_i32 m0, s92, 0x2000
	s_nop 0
	global_load_lds_dwordx4 v[238:239], off
	v_lshl_add_u64 v[238:239], s[48:49], 0, v[128:129]
	s_mov_b32 m0, s71
	s_nop 0
	global_load_lds_dwordx4 v[238:239], off
	s_mov_b32 m0, s72
	s_nop 0
	global_load_lds_dwordx4 v[240:241], off
	s_waitcnt vmcnt(8) lgkmcnt(0)
	s_barrier
; #define PG8_STAGE(bufoff, gbase, voff) do { _Pragma("unroll") for (int _i = 0; _i < 2; ++_i) \
;         __builtin_amdgcn_global_load_lds((const unsigned*)((const char*)(gbase) + (voff)[_i]), (PG8_LAS unsigned*)(lds + (bufoff) + ldsw + _i * 8192), 16, 0, 0); } while (0)
; #define PG8_LDA(dst, b, h) do { _Pragma("unroll") for (int m = 0; m < 4; ++m) _Pragma("unroll") for (int k = 0; k < 2; ++k) dst[m][k] = *(const PG8_LAS bf16x8*)(lds + PG8_SA(b, h) + aoff + m * 2048 + k * 1024); } while (0)
; #define PG8_LDB(dst, b, h) do { _Pragma("unroll") for (int n = 0; n < 2; ++n) _Pragma("unroll") for (int k = 0; k < 2; ++k) dst[n][k] = *(const PG8_LAS bf16x8*)(lds + PG8_SB(b, h) + boff + n * 2048 + k * 1024); } while (0)
; #define PG8_MMA(ai, bj, At, Bt) do { __builtin_amdgcn_s_setprio(1); _Pragma("unroll") for (int m = 0; m < 4; ++m) _Pragma("unroll") for (int n = 0; n < 2; ++n) _Pragma("unroll") for (int k = 0; k < 2; ++k) \
;         acc[ai][bj][m][n] = __builtin_amdgcn_mfma_f32_16x16x32_bf16(Bt[n][k], At[m][k], acc[ai][bj][m][n], 0, 0, 0); __builtin_amdgcn_s_setprio(0); } while (0)
; #define PG8_WAIT_V(n) asm volatile("s_waitcnt vmcnt(" #n ")" ::: "memory")
; #define PG8_WAIT_L(n) asm volatile("s_waitcnt lgkmcnt(" #n ")" ::: "memory")
; #define PG8_BAR __builtin_amdgcn_s_barrier()
; #define PG8_SCHED __builtin_amdgcn_sched_barrier(0)
; template <class Epi, class Sched, bool ALIGN_EPI = false, bool SP2 = false>
; __device__ __forceinline__ void gemm_phase(PG8_LAS unsigned char* lds, const Gemm g, const Sched& S, const Epi& E) {
;     ...
;             PG8_WAIT_V(8); PG8_WAIT_L(0); PG8_BAR; PG8_MMA(1, 0, At, B0); PG8_MMA(1, 1, At, B1); PG8_BAR; PG8_SCHED;
;             PG8_LDB(B0, 1, 0); PG8_LDB(B1, 1, 1); PG8_SCHED; PG8_LDA(At, 1, 0); PG8_STAGE(PG8_SA(0, 1), a2 + hstepA, voffA);
;             PG8_WAIT_V(8); PG8_WAIT_L(0); PG8_BAR; PG8_MMA(0, 0, At, B0); PG8_MMA(0, 1, At, B1); PG8_BAR; PG8_SCHED;
	s_setprio 1
	v_mfma_f32_16x16x32_bf16 v[60:63], v[152:155], v[204:207], v[60:63]
	v_mfma_f32_16x16x32_bf16 v[56:59], v[178:181], v[204:207], v[56:59]
	v_mfma_f32_16x16x32_bf16 v[44:47], v[152:155], v[212:215], v[44:47]
	v_mfma_f32_16x16x32_bf16 v[40:43], v[178:181], v[212:215], v[40:43]
	v_mfma_f32_16x16x32_bf16 v[28:31], v[152:155], v[220:223], v[28:31]
	v_mfma_f32_16x16x32_bf16 v[24:27], v[178:181], v[220:223], v[24:27]
	v_mfma_f32_16x16x32_bf16 v[12:15], v[152:155], v[228:231], v[12:15]
	v_mfma_f32_16x16x32_bf16 v[8:11], v[178:181], v[228:231], v[8:11]
	v_mfma_f32_16x16x32_bf16 v[60:63], v[156:159], v[208:211], v[60:63]
	v_mfma_f32_16x16x32_bf16 v[56:59], v[182:185], v[208:211], v[56:59]
	v_mfma_f32_16x16x32_bf16 v[44:47], v[156:159], v[216:219], v[44:47]
	v_mfma_f32_16x16x32_bf16 v[40:43], v[182:185], v[216:219], v[40:43]
	v_mfma_f32_16x16x32_bf16 v[28:31], v[156:159], v[224:227], v[28:31]
	v_mfma_f32_16x16x32_bf16 v[24:27], v[182:185], v[224:227], v[24:27]
	v_mfma_f32_16x16x32_bf16 v[12:15], v[156:159], v[232:235], v[12:15]
	v_mfma_f32_16x16x32_bf16 v[8:11], v[182:185], v[232:235], v[8:11]
	s_setprio 0
	s_setprio 1
	v_mfma_f32_16x16x32_bf16 v[52:55], v[188:191], v[204:207], v[52:55]
	v_mfma_f32_16x16x32_bf16 v[48:51], v[196:199], v[204:207], v[48:51]
	v_mfma_f32_16x16x32_bf16 v[36:39], v[188:191], v[212:215], v[36:39]
	v_mfma_f32_16x16x32_bf16 v[32:35], v[196:199], v[212:215], v[32:35]
	v_mfma_f32_16x16x32_bf16 v[20:23], v[188:191], v[220:223], v[20:23]
	v_mfma_f32_16x16x32_bf16 v[16:19], v[196:199], v[220:223], v[16:19]
	v_mfma_f32_16x16x32_bf16 v[4:7], v[188:191], v[228:231], v[4:7]
	v_mfma_f32_16x16x32_bf16 v[0:3], v[196:199], v[228:231], v[0:3]
	v_mfma_f32_16x16x32_bf16 v[52:55], v[192:195], v[208:211], v[52:55]
	v_mfma_f32_16x16x32_bf16 v[48:51], v[200:203], v[208:211], v[48:51]
	v_mfma_f32_16x16x32_bf16 v[36:39], v[192:195], v[216:219], v[36:39]
	v_mfma_f32_16x16x32_bf16 v[32:35], v[200:203], v[216:219], v[32:35]
	v_mfma_f32_16x16x32_bf16 v[20:23], v[192:195], v[224:227], v[20:23]
	v_mfma_f32_16x16x32_bf16 v[16:19], v[200:203], v[224:227], v[16:19]
	v_mfma_f32_16x16x32_bf16 v[4:7], v[192:195], v[232:235], v[4:7]
	v_mfma_f32_16x16x32_bf16 v[0:3], v[200:203], v[232:235], v[0:3]
	s_barrier
	s_setprio 0
	s_nop 0
	s_add_i32 s58, 0, 0x18000
	v_add_u32_e32 v136, s58, v163
	s_add_i32 s59, 0, 0x1c000
	ds_read_b128 v[152:155], v136
	ds_read_b128 v[156:159], v136 offset:1024
	ds_read_b128 v[178:181], v136 offset:2048
	ds_read_b128 v[182:185], v136 offset:3072
	v_add_u32_e32 v136, s59, v163
	ds_read_b128 v[188:191], v136
	ds_read_b128 v[192:195], v136 offset:1024
	ds_read_b128 v[196:199], v136 offset:2048
	ds_read_b128 v[200:203], v136 offset:3072
	s_add_u32 s48, s48, 0x40000
	s_addc_u32 s49, s49, 0
	s_mov_b32 m0, s73
	v_lshl_add_u64 v[242:243], s[48:49], 0, v[128:129]
	ds_read_b128 v[204:207], v167 offset:32768
	ds_read_b128 v[208:211], v167 offset:33792
	ds_read_b128 v[212:215], v167 offset:34816
	ds_read_b128 v[216:219], v167 offset:35840
	ds_read_b128 v[220:223], v167 offset:36864
	ds_read_b128 v[224:227], v167 offset:37888
	ds_read_b128 v[228:231], v167 offset:38912
	ds_read_b128 v[232:235], v167 offset:39936
	global_load_lds_dwordx4 v[242:243], off
	v_lshl_add_u64 v[242:243], s[48:49], 0, v[132:133]
	s_mov_b32 m0, s74
	s_nop 0
	global_load_lds_dwordx4 v[242:243], off
	s_waitcnt vmcnt(8) lgkmcnt(0)
	s_barrier
	s_setprio 1
	v_mfma_f32_16x16x32_bf16 v[124:127], v[152:155], v[204:207], v[124:127]
	v_mfma_f32_16x16x32_bf16 v[120:123], v[178:181], v[204:207], v[120:123]
	v_mfma_f32_16x16x32_bf16 v[108:111], v[152:155], v[212:215], v[108:111]
	v_mfma_f32_16x16x32_bf16 v[104:107], v[178:181], v[212:215], v[104:107]
	v_mfma_f32_16x16x32_bf16 v[92:95], v[152:155], v[220:223], v[92:95]
	v_mfma_f32_16x16x32_bf16 v[88:91], v[178:181], v[220:223], v[88:91]
	v_mfma_f32_16x16x32_bf16 v[76:79], v[152:155], v[228:231], v[76:79]
	v_mfma_f32_16x16x32_bf16 v[72:75], v[178:181], v[228:231], v[72:75]
	v_mfma_f32_16x16x32_bf16 v[124:127], v[156:159], v[208:211], v[124:127]
	v_mfma_f32_16x16x32_bf16 v[120:123], v[182:185], v[208:211], v[120:123]
	v_mfma_f32_16x16x32_bf16 v[108:111], v[156:159], v[216:219], v[108:111]
	v_mfma_f32_16x16x32_bf16 v[104:107], v[182:185], v[216:219], v[104:107]
	v_mfma_f32_16x16x32_bf16 v[92:95], v[156:159], v[224:227], v[92:95]
	v_mfma_f32_16x16x32_bf16 v[88:91], v[182:185], v[224:227], v[88:91]
	v_mfma_f32_16x16x32_bf16 v[76:79], v[156:159], v[232:235], v[76:79]
	v_mfma_f32_16x16x32_bf16 v[72:75], v[182:185], v[232:235], v[72:75]
	s_setprio 0
	s_setprio 1
	v_mfma_f32_16x16x32_bf16 v[116:119], v[188:191], v[204:207], v[116:119]
	v_mfma_f32_16x16x32_bf16 v[112:115], v[196:199], v[204:207], v[112:115]
	v_mfma_f32_16x16x32_bf16 v[100:103], v[188:191], v[212:215], v[100:103]
	v_mfma_f32_16x16x32_bf16 v[96:99], v[196:199], v[212:215], v[96:99]
	v_mfma_f32_16x16x32_bf16 v[84:87], v[188:191], v[220:223], v[84:87]
	v_mfma_f32_16x16x32_bf16 v[80:83], v[196:199], v[220:223], v[80:83]
	v_mfma_f32_16x16x32_bf16 v[68:71], v[188:191], v[228:231], v[68:71]
	v_mfma_f32_16x16x32_bf16 v[64:67], v[196:199], v[228:231], v[64:67]
	v_mfma_f32_16x16x32_bf16 v[116:119], v[192:195], v[208:211], v[116:119]
	v_mfma_f32_16x16x32_bf16 v[112:115], v[200:203], v[208:211], v[112:115]
	v_mfma_f32_16x16x32_bf16 v[100:103], v[192:195], v[216:219], v[100:103]
	v_mfma_f32_16x16x32_bf16 v[96:99], v[200:203], v[216:219], v[96:99]
	v_mfma_f32_16x16x32_bf16 v[84:87], v[192:195], v[224:227], v[84:87]
	v_mfma_f32_16x16x32_bf16 v[80:83], v[200:203], v[224:227], v[80:83]
	v_mfma_f32_16x16x32_bf16 v[68:71], v[192:195], v[232:235], v[68:71]
	v_mfma_f32_16x16x32_bf16 v[64:67], v[200:203], v[232:235], v[64:67]
	s_barrier
; #define PG8_STAGE(bufoff, gbase, voff) do { _Pragma("unroll") for (int _i = 0; _i < 2; ++_i) \
;         __builtin_amdgcn_global_load_lds((const unsigned*)((const char*)(gbase) + (voff)[_i]), (PG8_LAS unsigned*)(lds + (bufoff) + ldsw + _i * 8192), 16, 0, 0); } while (0)
; #define PG8_LDA(dst, b, h) do { _Pragma("unroll") for (int m = 0; m < 4; ++m) _Pragma("unroll") for (int k = 0; k < 2; ++k) dst[m][k] = *(const PG8_LAS bf16x8*)(lds + PG8_SA(b, h) + aoff + m * 2048 + k * 1024); } while (0)
; #define PG8_MMA(ai, bj, At, Bt) do { __builtin_amdgcn_s_setprio(1); _Pragma("unroll") for (int m = 0; m < 4; ++m) _Pragma("unroll") for (int n = 0; n < 2; ++n) _Pragma("unroll") for (int k = 0; k < 2; ++k) \
;         acc[ai][bj][m][n] = __builtin_amdgcn_mfma_f32_16x16x32_bf16(Bt[n][k], At[m][k], acc[ai][bj][m][n], 0, 0, 0); __builtin_amdgcn_s_setprio(0); } while (0)
; #define PG8_WAIT_V(n) asm volatile("s_waitcnt vmcnt(" #n ")" ::: "memory")
; #define PG8_WAIT_L(n) asm volatile("s_waitcnt lgkmcnt(" #n ")" ::: "memory")
; #define PG8_BAR __builtin_amdgcn_s_barrier()
; #define PG8_SCHED __builtin_amdgcn_sched_barrier(0)
; template <class Epi, class Sched, bool ALIGN_EPI = false, bool SP2 = false>
; __device__ __forceinline__ void gemm_phase(PG8_LAS unsigned char* lds, const Gemm g, const Sched& S, const Epi& E) {
;     ...
;             PG8_LDA(At, 1, 1); PG8_STAGE(PG8_SB(1, 0), b3, voffB); PG8_STAGE(PG8_SB(1, 1), b3 + hstepB, voffB); PG8_STAGE(PG8_SA(1, 0), a3, voffA);
;             PG8_WAIT_V(8); PG8_WAIT_L(0); PG8_BAR; PG8_MMA(1, 0, At, B0); PG8_MMA(1, 1, At, B1); PG8_BAR; PG8_SCHED;
	s_setprio 0
	s_add_i32 s48, s58, s70
	v_lshl_add_u64 v[160:161], v[160:161], 0, s[30:31]
	s_mov_b32 m0, s48
	ds_read_b128 v[204:207], v167 offset:49152
	ds_read_b128 v[208:211], v167 offset:50176
	ds_read_b128 v[212:215], v167 offset:51200
	ds_read_b128 v[216:219], v167 offset:52224
	ds_read_b128 v[220:223], v167 offset:53248
	ds_read_b128 v[224:227], v167 offset:54272
	ds_read_b128 v[228:231], v167 offset:55296
	ds_read_b128 v[232:235], v167 offset:56320
	global_load_lds_dwordx4 v[160:161], off
	s_add_i32 m0, s48, 0x2000
	s_add_u32 s46, s46, 0x40080
	v_lshl_add_u64 v[160:161], v[236:237], 0, s[30:31]
	s_addc_u32 s47, s47, 0
	s_add_i32 s48, s59, s70
	global_load_lds_dwordx4 v[160:161], off
	v_lshl_add_u64 v[160:161], s[46:47], 0, v[130:131]
	s_mov_b32 m0, s48
	s_nop 0
	global_load_lds_dwordx4 v[160:161], off
	v_lshl_add_u64 v[160:161], s[46:47], 0, v[134:135]
	s_add_i32 m0, s48, 0x2000
	s_nop 0
	global_load_lds_dwordx4 v[160:161], off
	v_lshl_add_u64 v[160:161], v[238:239], 0, s[30:31]
	s_mov_b32 m0, s76
	s_nop 0
	global_load_lds_dwordx4 v[160:161], off
	v_lshl_add_u64 v[160:161], v[240:241], 0, s[30:31]
	s_mov_b32 m0, s77
	s_nop 0
	global_load_lds_dwordx4 v[160:161], off
	s_waitcnt vmcnt(8) lgkmcnt(0)
	s_barrier
	s_setprio 1
	v_mfma_f32_16x16x32_bf16 v[60:63], v[152:155], v[204:207], v[60:63]
	v_mfma_f32_16x16x32_bf16 v[56:59], v[178:181], v[204:207], v[56:59]
	v_mfma_f32_16x16x32_bf16 v[44:47], v[152:155], v[212:215], v[44:47]
	v_mfma_f32_16x16x32_bf16 v[40:43], v[178:181], v[212:215], v[40:43]
	v_mfma_f32_16x16x32_bf16 v[28:31], v[152:155], v[220:223], v[28:31]
	v_mfma_f32_16x16x32_bf16 v[24:27], v[178:181], v[220:223], v[24:27]
	v_mfma_f32_16x16x32_bf16 v[12:15], v[152:155], v[228:231], v[12:15]
	v_mfma_f32_16x16x32_bf16 v[8:11], v[178:181], v[228:231], v[8:11]
	v_mfma_f32_16x16x32_bf16 v[60:63], v[156:159], v[208:211], v[60:63]
	v_mfma_f32_16x16x32_bf16 v[56:59], v[182:185], v[208:211], v[56:59]
	v_mfma_f32_16x16x32_bf16 v[44:47], v[156:159], v[216:219], v[44:47]
	v_mfma_f32_16x16x32_bf16 v[40:43], v[182:185], v[216:219], v[40:43]
	v_mfma_f32_16x16x32_bf16 v[28:31], v[156:159], v[224:227], v[28:31]
	v_mfma_f32_16x16x32_bf16 v[24:27], v[182:185], v[224:227], v[24:27]
	v_mfma_f32_16x16x32_bf16 v[12:15], v[156:159], v[232:235], v[12:15]
	v_mfma_f32_16x16x32_bf16 v[8:11], v[182:185], v[232:235], v[8:11]
	s_setprio 0
	s_setprio 1
	v_mfma_f32_16x16x32_bf16 v[52:55], v[188:191], v[204:207], v[52:55]
	v_mfma_f32_16x16x32_bf16 v[48:51], v[196:199], v[204:207], v[48:51]
	v_mfma_f32_16x16x32_bf16 v[36:39], v[188:191], v[212:215], v[36:39]
	v_mfma_f32_16x16x32_bf16 v[32:35], v[196:199], v[212:215], v[32:35]
	v_mfma_f32_16x16x32_bf16 v[20:23], v[188:191], v[220:223], v[20:23]
	v_mfma_f32_16x16x32_bf16 v[16:19], v[196:199], v[220:223], v[16:19]
	v_mfma_f32_16x16x32_bf16 v[4:7], v[188:191], v[228:231], v[4:7]
	v_mfma_f32_16x16x32_bf16 v[0:3], v[196:199], v[228:231], v[0:3]
	v_mfma_f32_16x16x32_bf16 v[52:55], v[192:195], v[208:211], v[52:55]
	v_mfma_f32_16x16x32_bf16 v[48:51], v[200:203], v[208:211], v[48:51]
	v_mfma_f32_16x16x32_bf16 v[36:39], v[192:195], v[216:219], v[36:39]
	v_mfma_f32_16x16x32_bf16 v[32:35], v[200:203], v[216:219], v[32:35]
	v_mfma_f32_16x16x32_bf16 v[20:23], v[192:195], v[224:227], v[20:23]
	v_mfma_f32_16x16x32_bf16 v[16:19], v[200:203], v[224:227], v[16:19]
	v_mfma_f32_16x16x32_bf16 v[4:7], v[192:195], v[232:235], v[4:7]
	v_mfma_f32_16x16x32_bf16 v[0:3], v[200:203], v[232:235], v[0:3]
	s_barrier
	s_setprio 0
	s_add_i32 s91, s91, 2
	s_add_u32 s14, s14, 0x100
	s_addc_u32 s15, s15, 0
	s_add_u32 s66, s66, 0x100
	s_addc_u32 s67, s67, 0
	s_cmp_gt_u32 s91, 13
	s_cbranch_scc0 .LBB0_404
	s_and_b64 vcc, exec, s[34:35]
	s_cbranch_vccz .LBB0_407
	s_barrier

; #define PG8_STAGE(bufoff, gbase, voff) do { _Pragma("unroll") for (int _i = 0; _i < 2; ++_i) \
;         __builtin_amdgcn_global_load_lds((const unsigned*)((const char*)(gbase) + (voff)[_i]), (PG8_LAS unsigned*)(lds + (bufoff) + ldsw + _i * 8192), 16, 0, 0); } while (0)
; #define PG8_LDA(dst, b, h) do { _Pragma("unroll") for (int m = 0; m < 4; ++m) _Pragma("unroll") for (int k = 0; k < 2; ++k) dst[m][k] = *(const PG8_LAS bf16x8*)(lds + PG8_SA(b, h) + aoff + m * 2048 + k * 1024); } while (0)
; #define PG8_LDB(dst, b, h) do { _Pragma("unroll") for (int n = 0; n < 2; ++n) _Pragma("unroll") for (int k = 0; k < 2; ++k) dst[n][k] = *(const PG8_LAS bf16x8*)(lds + PG8_SB(b, h) + boff + n * 2048 + k * 1024); } while (0)
; #define PG8_MMA(ai, bj, At, Bt) do { __builtin_amdgcn_s_setprio(1); _Pragma("unroll") for (int m = 0; m < 4; ++m) _Pragma("unroll") for (int n = 0; n < 2; ++n) _Pragma("unroll") for (int k = 0; k < 2; ++k) \
;         acc[ai][bj][m][n] = __builtin_amdgcn_mfma_f32_16x16x32_bf16(Bt[n][k], At[m][k], acc[ai][bj][m][n], 0, 0, 0); __builtin_amdgcn_s_setprio(0); } while (0)
; #define PG8_WAIT_V(n) asm volatile("s_waitcnt vmcnt(" #n ")" ::: "memory")
; #define PG8_BAR __builtin_amdgcn_s_barrier()
; template <class Epi, class Sched, bool ALIGN_EPI = false, bool SP2 = false>
; __device__ __forceinline__ void gemm_phase(PG8_LAS unsigned char* lds, const Gemm g, const Sched& S, const Epi& E) {
;     ...
;         for (int t = 0; t < nt; t += 2) {
;             const bool last = (t == nt - 2);
;             const char* a1 = cA + (size_t)(t + 1) * kstep;
;             const char* a2 = last ? nA : cA + (size_t)(t + 2) * kstep; const char* b2 = last ? nB : cB + (size_t)(t + 2) * kstep;
;             const char* a3 = a2 + kstep; const char* b3 = b2 + kstep;
;             if (last && has_next) S.a_ready(nxt);
;             if constexpr (SP2) {
;             PG8_LDB(B0, 0, 0); PG8_LDB(B1, 0, 1); PG8_SCHED; PG8_LDA(At, 0, 0); PG8_STAGE(PG8_SA(1, 1), a1 + hstepA, voffA);
;             PG8_WAIT_V(8); PG8_WAIT_L(0); PG8_BAR; PG8_MMA(0, 0, At, B0); PG8_MMA(0, 1, At, B1); PG8_BAR; PG8_SCHED;
;             PG8_LDA(At, 0, 1); PG8_STAGE(PG8_SB(0, 0), b2, voffB); PG8_STAGE(PG8_SB(0, 1), b2 + hstepB, voffB); PG8_STAGE(PG8_SA(0, 0), a2, voffA);
;             PG8_WAIT_V(8); PG8_WAIT_L(0); PG8_BAR; PG8_MMA(1, 0, At, B0); PG8_MMA(1, 1, At, B1); PG8_BAR; PG8_SCHED;
.LBB0_524:
	s_nop 0
	ds_read_b128 v[144:147], v153
	ds_read_b128 v[158:161], v153 offset:1024
	ds_read_b128 v[162:165], v153 offset:2048
	ds_read_b128 v[166:169], v153 offset:3072
	ds_read_b128 v[170:173], v154
	ds_read_b128 v[174:177], v154 offset:1024
	ds_read_b128 v[178:181], v154 offset:2048
	ds_read_b128 v[182:185], v154 offset:3072
	s_add_u32 s30, s28, 0x100
	s_addc_u32 s31, s29, 0
	s_cmp_eq_u32 s76, 2
	s_cselect_b32 s37, s9, s31
	s_cselect_b32 s36, s8, s30
	s_cselect_b32 s35, s25, s75
	s_cselect_b32 s34, s24, s74
	v_lshl_add_u64 v[148:149], s[28:29], 0, v[136:137]
	s_add_i32 m0, s42, 0xc000
	ds_read_b128 v[188:191], v155
	ds_read_b128 v[192:195], v155 offset:1024
	ds_read_b128 v[196:199], v155 offset:2048
	ds_read_b128 v[200:203], v155 offset:3072
	ds_read_b128 v[204:207], v155 offset:4096
	ds_read_b128 v[208:211], v155 offset:5120
	ds_read_b128 v[212:215], v155 offset:6144
	ds_read_b128 v[216:219], v155 offset:7168
	global_load_lds_dwordx4 v[148:149], off
	v_lshl_add_u64 v[148:149], s[28:29], 0, v[138:139]
	s_add_i32 m0, s42, 0xe000
	s_nop 0
	global_load_lds_dwordx4 v[148:149], off
	s_waitcnt vmcnt(8) lgkmcnt(0)
	s_barrier
	s_setprio 1
	v_mfma_f32_16x16x32_bf16 v[124:127], v[144:147], v[188:191], v[124:127]
	v_mfma_f32_16x16x32_bf16 v[120:123], v[162:165], v[188:191], v[120:123]
	v_mfma_f32_16x16x32_bf16 v[108:111], v[144:147], v[196:199], v[108:111]
	v_mfma_f32_16x16x32_bf16 v[104:107], v[162:165], v[196:199], v[104:107]
	v_mfma_f32_16x16x32_bf16 v[92:95], v[144:147], v[204:207], v[92:95]
	v_mfma_f32_16x16x32_bf16 v[88:91], v[162:165], v[204:207], v[88:91]
	v_mfma_f32_16x16x32_bf16 v[76:79], v[144:147], v[212:215], v[76:79]
	v_mfma_f32_16x16x32_bf16 v[72:75], v[162:165], v[212:215], v[72:75]
	v_mfma_f32_16x16x32_bf16 v[124:127], v[158:161], v[192:195], v[124:127]
	v_mfma_f32_16x16x32_bf16 v[120:123], v[166:169], v[192:195], v[120:123]
	v_mfma_f32_16x16x32_bf16 v[108:111], v[158:161], v[200:203], v[108:111]
	v_mfma_f32_16x16x32_bf16 v[104:107], v[166:169], v[200:203], v[104:107]
	v_mfma_f32_16x16x32_bf16 v[92:95], v[158:161], v[208:211], v[92:95]
	v_mfma_f32_16x16x32_bf16 v[88:91], v[166:169], v[208:211], v[88:91]
	v_mfma_f32_16x16x32_bf16 v[76:79], v[158:161], v[216:219], v[76:79]
	v_mfma_f32_16x16x32_bf16 v[72:75], v[166:169], v[216:219], v[72:75]
	s_setprio 0
	s_setprio 1
	v_mfma_f32_16x16x32_bf16 v[116:119], v[170:173], v[188:191], v[116:119]
	v_mfma_f32_16x16x32_bf16 v[112:115], v[178:181], v[188:191], v[112:115]
	v_mfma_f32_16x16x32_bf16 v[100:103], v[170:173], v[196:199], v[100:103]
	v_mfma_f32_16x16x32_bf16 v[96:99], v[178:181], v[196:199], v[96:99]
	v_mfma_f32_16x16x32_bf16 v[84:87], v[170:173], v[204:207], v[84:87]
	v_mfma_f32_16x16x32_bf16 v[80:83], v[178:181], v[204:207], v[80:83]
	v_mfma_f32_16x16x32_bf16 v[68:71], v[170:173], v[212:215], v[68:71]
	v_mfma_f32_16x16x32_bf16 v[64:67], v[178:181], v[212:215], v[64:67]
	v_mfma_f32_16x16x32_bf16 v[116:119], v[174:177], v[192:195], v[116:119]
	v_mfma_f32_16x16x32_bf16 v[112:115], v[182:185], v[192:195], v[112:115]
	v_mfma_f32_16x16x32_bf16 v[100:103], v[174:177], v[200:203], v[100:103]
	v_mfma_f32_16x16x32_bf16 v[96:99], v[182:185], v[200:203], v[96:99]
	v_mfma_f32_16x16x32_bf16 v[84:87], v[174:177], v[208:211], v[84:87]
	v_mfma_f32_16x16x32_bf16 v[80:83], v[182:185], v[208:211], v[80:83]
	v_mfma_f32_16x16x32_bf16 v[68:71], v[174:177], v[216:219], v[68:71]
	v_mfma_f32_16x16x32_bf16 v[64:67], v[182:185], v[216:219], v[64:67]
	s_barrier
	s_setprio 0
	s_nop 0
	s_add_i32 s28, s66, s40
	v_lshl_add_u64 v[148:149], s[34:35], 0, v[132:133]
	s_mov_b32 m0, s28
	ds_read_b128 v[188:191], v155 offset:16384
	ds_read_b128 v[192:195], v155 offset:17408
	ds_read_b128 v[196:199], v155 offset:18432
	ds_read_b128 v[200:203], v155 offset:19456
	ds_read_b128 v[204:207], v155 offset:20480
	ds_read_b128 v[208:211], v155 offset:21504
	ds_read_b128 v[212:215], v155 offset:22528
	ds_read_b128 v[216:219], v155 offset:23552
	global_load_lds_dwordx4 v[148:149], off
	s_add_i32 m0, s28, 0x2000
	s_add_u32 s28, s34, 0x18000
	v_lshl_add_u64 v[220:221], s[34:35], 0, v[128:129]
	s_addc_u32 s29, s35, 0
	s_add_i32 s58, s67, s40
	global_load_lds_dwordx4 v[220:221], off
	v_lshl_add_u64 v[222:223], s[28:29], 0, v[132:133]
	s_mov_b32 m0, s58
	v_lshl_add_u64 v[224:225], s[36:37], 0, v[130:131]
	global_load_lds_dwordx4 v[222:223], off
	v_lshl_add_u64 v[222:223], s[28:29], 0, v[128:129]
	s_add_i32 m0, s58, 0x2000
	s_nop 0
	global_load_lds_dwordx4 v[222:223], off
	v_lshl_add_u64 v[222:223], s[36:37], 0, v[134:135]
	s_mov_b32 m0, s42
	s_nop 0
	global_load_lds_dwordx4 v[222:223], off
	s_mov_b32 m0, s43
	s_nop 0
	global_load_lds_dwordx4 v[224:225], off
	s_waitcnt vmcnt(8) lgkmcnt(0)
	s_barrier
; #define PG8_STAGE(bufoff, gbase, voff) do { _Pragma("unroll") for (int _i = 0; _i < 2; ++_i) \
;         __builtin_amdgcn_global_load_lds((const unsigned*)((const char*)(gbase) + (voff)[_i]), (PG8_LAS unsigned*)(lds + (bufoff) + ldsw + _i * 8192), 16, 0, 0); } while (0)
; #define PG8_LDA(dst, b, h) do { _Pragma("unroll") for (int m = 0; m < 4; ++m) _Pragma("unroll") for (int k = 0; k < 2; ++k) dst[m][k] = *(const PG8_LAS bf16x8*)(lds + PG8_SA(b, h) + aoff + m * 2048 + k * 1024); } while (0)
; #define PG8_LDB(dst, b, h) do { _Pragma("unroll") for (int n = 0; n < 2; ++n) _Pragma("unroll") for (int k = 0; k < 2; ++k) dst[n][k] = *(const PG8_LAS bf16x8*)(lds + PG8_SB(b, h) + boff + n * 2048 + k * 1024); } while (0)
; #define PG8_MMA(ai, bj, At, Bt) do { __builtin_amdgcn_s_setprio(1); _Pragma("unroll") for (int m = 0; m < 4; ++m) _Pragma("unroll") for (int n = 0; n < 2; ++n) _Pragma("unroll") for (int k = 0; k < 2; ++k) \
;         acc[ai][bj][m][n] = __builtin_amdgcn_mfma_f32_16x16x32_bf16(Bt[n][k], At[m][k], acc[ai][bj][m][n], 0, 0, 0); __builtin_amdgcn_s_setprio(0); } while (0)
; #define PG8_WAIT_V(n) asm volatile("s_waitcnt vmcnt(" #n ")" ::: "memory")
; #define PG8_WAIT_L(n) asm volatile("s_waitcnt lgkmcnt(" #n ")" ::: "memory")
; #define PG8_BAR __builtin_amdgcn_s_barrier()
; #define PG8_SCHED __builtin_amdgcn_sched_barrier(0)
; template <class Epi, class Sched, bool ALIGN_EPI = false, bool SP2 = false>
; __device__ __forceinline__ void gemm_phase(PG8_LAS unsigned char* lds, const Gemm g, const Sched& S, const Epi& E) {
;     ...
;             PG8_WAIT_V(8); PG8_WAIT_L(0); PG8_BAR; PG8_MMA(1, 0, At, B0); PG8_MMA(1, 1, At, B1); PG8_BAR; PG8_SCHED;
;             PG8_LDB(B0, 1, 0); PG8_LDB(B1, 1, 1); PG8_SCHED; PG8_LDA(At, 1, 0); PG8_STAGE(PG8_SA(0, 1), a2 + hstepA, voffA);
;             PG8_WAIT_V(8); PG8_WAIT_L(0); PG8_BAR; PG8_MMA(0, 0, At, B0); PG8_MMA(0, 1, At, B1); PG8_BAR; PG8_SCHED;
;             PG8_LDA(At, 1, 1); PG8_STAGE(PG8_SB(1, 0), b3, voffB); PG8_STAGE(PG8_SB(1, 1), b3 + hstepB, voffB); PG8_STAGE(PG8_SA(1, 0), a3, voffA);
;             PG8_WAIT_V(8); PG8_WAIT_L(0); PG8_BAR; PG8_MMA(1, 0, At, B0); PG8_MMA(1, 1, At, B1); PG8_BAR; PG8_SCHED;
	s_setprio 1
	v_mfma_f32_16x16x32_bf16 v[60:63], v[144:147], v[188:191], v[60:63]
	v_mfma_f32_16x16x32_bf16 v[56:59], v[162:165], v[188:191], v[56:59]
	v_mfma_f32_16x16x32_bf16 v[44:47], v[144:147], v[196:199], v[44:47]
	v_mfma_f32_16x16x32_bf16 v[40:43], v[162:165], v[196:199], v[40:43]
	v_mfma_f32_16x16x32_bf16 v[28:31], v[144:147], v[204:207], v[28:31]
	v_mfma_f32_16x16x32_bf16 v[24:27], v[162:165], v[204:207], v[24:27]
	v_mfma_f32_16x16x32_bf16 v[12:15], v[144:147], v[212:215], v[12:15]
	v_mfma_f32_16x16x32_bf16 v[8:11], v[162:165], v[212:215], v[8:11]
	v_mfma_f32_16x16x32_bf16 v[60:63], v[158:161], v[192:195], v[60:63]
	v_mfma_f32_16x16x32_bf16 v[56:59], v[166:169], v[192:195], v[56:59]
	v_mfma_f32_16x16x32_bf16 v[44:47], v[158:161], v[200:203], v[44:47]
	v_mfma_f32_16x16x32_bf16 v[40:43], v[166:169], v[200:203], v[40:43]
	v_mfma_f32_16x16x32_bf16 v[28:31], v[158:161], v[208:211], v[28:31]
	v_mfma_f32_16x16x32_bf16 v[24:27], v[166:169], v[208:211], v[24:27]
	v_mfma_f32_16x16x32_bf16 v[12:15], v[158:161], v[216:219], v[12:15]
	v_mfma_f32_16x16x32_bf16 v[8:11], v[166:169], v[216:219], v[8:11]
	s_setprio 0
	s_setprio 1
	v_mfma_f32_16x16x32_bf16 v[52:55], v[170:173], v[188:191], v[52:55]
	v_mfma_f32_16x16x32_bf16 v[48:51], v[178:181], v[188:191], v[48:51]
	v_mfma_f32_16x16x32_bf16 v[36:39], v[170:173], v[196:199], v[36:39]
	v_mfma_f32_16x16x32_bf16 v[32:35], v[178:181], v[196:199], v[32:35]
	v_mfma_f32_16x16x32_bf16 v[20:23], v[170:173], v[204:207], v[20:23]
	v_mfma_f32_16x16x32_bf16 v[16:19], v[178:181], v[204:207], v[16:19]
	v_mfma_f32_16x16x32_bf16 v[4:7], v[170:173], v[212:215], v[4:7]
	v_mfma_f32_16x16x32_bf16 v[0:3], v[178:181], v[212:215], v[0:3]
	v_mfma_f32_16x16x32_bf16 v[52:55], v[174:177], v[192:195], v[52:55]
	v_mfma_f32_16x16x32_bf16 v[48:51], v[182:185], v[192:195], v[48:51]
	v_mfma_f32_16x16x32_bf16 v[36:39], v[174:177], v[200:203], v[36:39]
	v_mfma_f32_16x16x32_bf16 v[32:35], v[182:185], v[200:203], v[32:35]
	v_mfma_f32_16x16x32_bf16 v[20:23], v[174:177], v[208:211], v[20:23]
	v_mfma_f32_16x16x32_bf16 v[16:19], v[182:185], v[208:211], v[16:19]
	v_mfma_f32_16x16x32_bf16 v[4:7], v[174:177], v[216:219], v[4:7]
	v_mfma_f32_16x16x32_bf16 v[0:3], v[182:185], v[216:219], v[0:3]
	s_barrier
	s_setprio 0
	s_nop 0
	s_add_i32 s58, 0, 0x18000
	v_add_u32_e32 v157, s58, v151
	s_add_i32 s59, 0, 0x1c000
	ds_read_b128 v[144:147], v157
	ds_read_b128 v[158:161], v157 offset:1024
	ds_read_b128 v[162:165], v157 offset:2048
	ds_read_b128 v[166:169], v157 offset:3072
	v_add_u32_e32 v157, s59, v151
	ds_read_b128 v[170:173], v157
	ds_read_b128 v[174:177], v157 offset:1024
	ds_read_b128 v[178:181], v157 offset:2048
	ds_read_b128 v[182:185], v157 offset:3072
	s_add_u32 s28, s36, 0x30000
	s_addc_u32 s29, s37, 0
	s_mov_b32 m0, s44
	v_lshl_add_u64 v[226:227], s[28:29], 0, v[134:135]
	ds_read_b128 v[188:191], v155 offset:32768
	ds_read_b128 v[192:195], v155 offset:33792
	ds_read_b128 v[196:199], v155 offset:34816
	ds_read_b128 v[200:203], v155 offset:35840
	ds_read_b128 v[204:207], v155 offset:36864
	ds_read_b128 v[208:211], v155 offset:37888
	ds_read_b128 v[212:215], v155 offset:38912
	ds_read_b128 v[216:219], v155 offset:39936
	global_load_lds_dwordx4 v[226:227], off
	v_lshl_add_u64 v[226:227], s[28:29], 0, v[130:131]
	s_mov_b32 m0, s45
	s_nop 0
	global_load_lds_dwordx4 v[226:227], off
	s_waitcnt vmcnt(8) lgkmcnt(0)
	s_barrier
	s_setprio 1
	v_mfma_f32_16x16x32_bf16 v[124:127], v[144:147], v[188:191], v[124:127]
	v_mfma_f32_16x16x32_bf16 v[120:123], v[162:165], v[188:191], v[120:123]
	v_mfma_f32_16x16x32_bf16 v[108:111], v[144:147], v[196:199], v[108:111]
	v_mfma_f32_16x16x32_bf16 v[104:107], v[162:165], v[196:199], v[104:107]
	v_mfma_f32_16x16x32_bf16 v[92:95], v[144:147], v[204:207], v[92:95]
	v_mfma_f32_16x16x32_bf16 v[88:91], v[162:165], v[204:207], v[88:91]
	v_mfma_f32_16x16x32_bf16 v[76:79], v[144:147], v[212:215], v[76:79]
	v_mfma_f32_16x16x32_bf16 v[72:75], v[162:165], v[212:215], v[72:75]
	v_mfma_f32_16x16x32_bf16 v[124:127], v[158:161], v[192:195], v[124:127]
	v_mfma_f32_16x16x32_bf16 v[120:123], v[166:169], v[192:195], v[120:123]
	v_mfma_f32_16x16x32_bf16 v[108:111], v[158:161], v[200:203], v[108:111]
	v_mfma_f32_16x16x32_bf16 v[104:107], v[166:169], v[200:203], v[104:107]
	v_mfma_f32_16x16x32_bf16 v[92:95], v[158:161], v[208:211], v[92:95]
	v_mfma_f32_16x16x32_bf16 v[88:91], v[166:169], v[208:211], v[88:91]
	v_mfma_f32_16x16x32_bf16 v[76:79], v[158:161], v[216:219], v[76:79]
	v_mfma_f32_16x16x32_bf16 v[72:75], v[166:169], v[216:219], v[72:75]
	s_setprio 0
	s_setprio 1
	v_mfma_f32_16x16x32_bf16 v[116:119], v[170:173], v[188:191], v[116:119]
	v_mfma_f32_16x16x32_bf16 v[112:115], v[178:181], v[188:191], v[112:115]
	v_mfma_f32_16x16x32_bf16 v[100:103], v[170:173], v[196:199], v[100:103]
	v_mfma_f32_16x16x32_bf16 v[96:99], v[178:181], v[196:199], v[96:99]
	v_mfma_f32_16x16x32_bf16 v[84:87], v[170:173], v[204:207], v[84:87]
	v_mfma_f32_16x16x32_bf16 v[80:83], v[178:181], v[204:207], v[80:83]
	v_mfma_f32_16x16x32_bf16 v[68:71], v[170:173], v[212:215], v[68:71]
	v_mfma_f32_16x16x32_bf16 v[64:67], v[178:181], v[212:215], v[64:67]
	v_mfma_f32_16x16x32_bf16 v[116:119], v[174:177], v[192:195], v[116:119]
	v_mfma_f32_16x16x32_bf16 v[112:115], v[182:185], v[192:195], v[112:115]
	v_mfma_f32_16x16x32_bf16 v[100:103], v[174:177], v[200:203], v[100:103]
	v_mfma_f32_16x16x32_bf16 v[96:99], v[182:185], v[200:203], v[96:99]
	v_mfma_f32_16x16x32_bf16 v[84:87], v[174:177], v[208:211], v[84:87]
	v_mfma_f32_16x16x32_bf16 v[80:83], v[182:185], v[208:211], v[80:83]
	v_mfma_f32_16x16x32_bf16 v[68:71], v[174:177], v[216:219], v[68:71]
	v_mfma_f32_16x16x32_bf16 v[64:67], v[182:185], v[216:219], v[64:67]
	s_barrier
; #define PG8_STAGE(bufoff, gbase, voff) do { _Pragma("unroll") for (int _i = 0; _i < 2; ++_i) \
;         __builtin_amdgcn_global_load_lds((const unsigned*)((const char*)(gbase) + (voff)[_i]), (PG8_LAS unsigned*)(lds + (bufoff) + ldsw + _i * 8192), 16, 0, 0); } while (0)
; #define PG8_LDA(dst, b, h) do { _Pragma("unroll") for (int m = 0; m < 4; ++m) _Pragma("unroll") for (int k = 0; k < 2; ++k) dst[m][k] = *(const PG8_LAS bf16x8*)(lds + PG8_SA(b, h) + aoff + m * 2048 + k * 1024); } while (0)
; #define PG8_MMA(ai, bj, At, Bt) do { __builtin_amdgcn_s_setprio(1); _Pragma("unroll") for (int m = 0; m < 4; ++m) _Pragma("unroll") for (int n = 0; n < 2; ++n) _Pragma("unroll") for (int k = 0; k < 2; ++k) \
;         acc[ai][bj][m][n] = __builtin_amdgcn_mfma_f32_16x16x32_bf16(Bt[n][k], At[m][k], acc[ai][bj][m][n], 0, 0, 0); __builtin_amdgcn_s_setprio(0); } while (0)
; #define PG8_WAIT_V(n) asm volatile("s_waitcnt vmcnt(" #n ")" ::: "memory")
; #define PG8_WAIT_L(n) asm volatile("s_waitcnt lgkmcnt(" #n ")" ::: "memory")
; #define PG8_BAR __builtin_amdgcn_s_barrier()
; #define PG8_SCHED __builtin_amdgcn_sched_barrier(0)
; template <class Epi, class Sched, bool ALIGN_EPI = false, bool SP2 = false>
; __device__ __forceinline__ void gemm_phase(PG8_LAS unsigned char* lds, const Gemm g, const Sched& S, const Epi& E) {
;     ...
;         for (int t = 0; t < nt; t += 2) {
;             const bool last = (t == nt - 2);
;             const char* a1 = cA + (size_t)(t + 1) * kstep;
;             const char* a2 = last ? nA : cA + (size_t)(t + 2) * kstep; const char* b2 = last ? nB : cB + (size_t)(t + 2) * kstep;
;     ...
;             PG8_LDA(At, 1, 1); PG8_STAGE(PG8_SB(1, 0), b3, voffB); PG8_STAGE(PG8_SB(1, 1), b3 + hstepB, voffB); PG8_STAGE(PG8_SA(1, 0), a3, voffA);
;             PG8_WAIT_V(8); PG8_WAIT_L(0); PG8_BAR; PG8_MMA(1, 0, At, B0); PG8_MMA(1, 1, At, B1); PG8_BAR; PG8_SCHED;
;     ...
;         if constexpr (ALIGN_EPI) { if (wr == 0) PG8_BAR; }
	s_setprio 0
	s_add_i32 s28, s58, s40
	v_lshl_add_u64 v[148:149], v[148:149], 0, s[12:13]
	s_mov_b32 m0, s28
	ds_read_b128 v[188:191], v155 offset:49152
	ds_read_b128 v[192:195], v155 offset:50176
	ds_read_b128 v[196:199], v155 offset:51200
	ds_read_b128 v[200:203], v155 offset:52224
	ds_read_b128 v[204:207], v155 offset:53248
	ds_read_b128 v[208:211], v155 offset:54272
	ds_read_b128 v[212:215], v155 offset:55296
	ds_read_b128 v[216:219], v155 offset:56320
	global_load_lds_dwordx4 v[148:149], off
	s_add_i32 m0, s28, 0x2000
	s_add_u32 s28, s34, 0x18080
	v_lshl_add_u64 v[148:149], v[220:221], 0, s[12:13]
	s_addc_u32 s29, s35, 0
	s_add_i32 s34, s59, s40
	global_load_lds_dwordx4 v[148:149], off
	v_lshl_add_u64 v[148:149], s[28:29], 0, v[132:133]
	s_mov_b32 m0, s34
	s_nop 0
	global_load_lds_dwordx4 v[148:149], off
	v_lshl_add_u64 v[148:149], s[28:29], 0, v[128:129]
	s_add_i32 m0, s34, 0x2000
	s_nop 0
	global_load_lds_dwordx4 v[148:149], off
	v_lshl_add_u64 v[148:149], v[222:223], 0, s[12:13]
	s_mov_b32 m0, s47
	s_nop 0
	global_load_lds_dwordx4 v[148:149], off
	v_lshl_add_u64 v[148:149], v[224:225], 0, s[12:13]
	s_mov_b32 m0, s48
	s_nop 0
	global_load_lds_dwordx4 v[148:149], off
	s_waitcnt vmcnt(8) lgkmcnt(0)
	s_barrier
	s_setprio 1
	v_mfma_f32_16x16x32_bf16 v[60:63], v[144:147], v[188:191], v[60:63]
	v_mfma_f32_16x16x32_bf16 v[56:59], v[162:165], v[188:191], v[56:59]
	v_mfma_f32_16x16x32_bf16 v[44:47], v[144:147], v[196:199], v[44:47]
	v_mfma_f32_16x16x32_bf16 v[40:43], v[162:165], v[196:199], v[40:43]
	v_mfma_f32_16x16x32_bf16 v[28:31], v[144:147], v[204:207], v[28:31]
	v_mfma_f32_16x16x32_bf16 v[24:27], v[162:165], v[204:207], v[24:27]
	v_mfma_f32_16x16x32_bf16 v[12:15], v[144:147], v[212:215], v[12:15]
	v_mfma_f32_16x16x32_bf16 v[8:11], v[162:165], v[212:215], v[8:11]
	v_mfma_f32_16x16x32_bf16 v[60:63], v[158:161], v[192:195], v[60:63]
	v_mfma_f32_16x16x32_bf16 v[56:59], v[166:169], v[192:195], v[56:59]
	v_mfma_f32_16x16x32_bf16 v[44:47], v[158:161], v[200:203], v[44:47]
	v_mfma_f32_16x16x32_bf16 v[40:43], v[166:169], v[200:203], v[40:43]
	v_mfma_f32_16x16x32_bf16 v[28:31], v[158:161], v[208:211], v[28:31]
	v_mfma_f32_16x16x32_bf16 v[24:27], v[166:169], v[208:211], v[24:27]
	v_mfma_f32_16x16x32_bf16 v[12:15], v[158:161], v[216:219], v[12:15]
	v_mfma_f32_16x16x32_bf16 v[8:11], v[166:169], v[216:219], v[8:11]
	s_setprio 0
	s_setprio 1
	v_mfma_f32_16x16x32_bf16 v[52:55], v[170:173], v[188:191], v[52:55]
	v_mfma_f32_16x16x32_bf16 v[48:51], v[178:181], v[188:191], v[48:51]
	v_mfma_f32_16x16x32_bf16 v[36:39], v[170:173], v[196:199], v[36:39]
	v_mfma_f32_16x16x32_bf16 v[32:35], v[178:181], v[196:199], v[32:35]
	v_mfma_f32_16x16x32_bf16 v[20:23], v[170:173], v[204:207], v[20:23]
	v_mfma_f32_16x16x32_bf16 v[16:19], v[178:181], v[204:207], v[16:19]
	v_mfma_f32_16x16x32_bf16 v[4:7], v[170:173], v[212:215], v[4:7]
	v_mfma_f32_16x16x32_bf16 v[0:3], v[178:181], v[212:215], v[0:3]
	v_mfma_f32_16x16x32_bf16 v[52:55], v[174:177], v[192:195], v[52:55]
	v_mfma_f32_16x16x32_bf16 v[48:51], v[182:185], v[192:195], v[48:51]
	v_mfma_f32_16x16x32_bf16 v[36:39], v[174:177], v[200:203], v[36:39]
	v_mfma_f32_16x16x32_bf16 v[32:35], v[182:185], v[200:203], v[32:35]
	v_mfma_f32_16x16x32_bf16 v[20:23], v[174:177], v[208:211], v[20:23]
	v_mfma_f32_16x16x32_bf16 v[16:19], v[182:185], v[208:211], v[16:19]
	v_mfma_f32_16x16x32_bf16 v[4:7], v[174:177], v[216:219], v[4:7]
	v_mfma_f32_16x16x32_bf16 v[0:3], v[182:185], v[216:219], v[0:3]
	s_barrier
	s_setprio 0
	s_add_i32 s76, s76, 2
	s_add_u32 s74, s74, 0x100
	s_addc_u32 s75, s75, 0
	s_cmp_gt_u32 s76, 3
	s_mov_b64 s[28:29], s[30:31]
	s_cbranch_scc0 .LBB0_524
	s_and_b64 vcc, exec, s[14:15]
	s_cbranch_vccz .LBB0_527
	s_barrier

; #define PG8_STAGE(bufoff, gbase, voff) do { _Pragma("unroll") for (int _i = 0; _i < 2; ++_i) \
;         __builtin_amdgcn_global_load_lds((const unsigned*)((const char*)(gbase) + (voff)[_i]), (PG8_LAS unsigned*)(lds + (bufoff) + ldsw + _i * 8192), 16, 0, 0); } while (0)
; #define PG8_LDA(dst, b, h) do { _Pragma("unroll") for (int m = 0; m < 4; ++m) _Pragma("unroll") for (int k = 0; k < 2; ++k) dst[m][k] = *(const PG8_LAS bf16x8*)(lds + PG8_SA(b, h) + aoff + m * 2048 + k * 1024); } while (0)
; #define PG8_LDB(dst, b, h) do { _Pragma("unroll") for (int n = 0; n < 2; ++n) _Pragma("unroll") for (int k = 0; k < 2; ++k) dst[n][k] = *(const PG8_LAS bf16x8*)(lds + PG8_SB(b, h) + boff + n * 2048 + k * 1024); } while (0)
; #define PG8_WAIT_V(n) asm volatile("s_waitcnt vmcnt(" #n ")" ::: "memory")
; #define PG8_WAIT_L(n) asm volatile("s_waitcnt lgkmcnt(" #n ")" ::: "memory")
; #define PG8_BAR __builtin_amdgcn_s_barrier()
; #define PG8_SCHED __builtin_amdgcn_sched_barrier(0)
; template <class Epi, class Sched, bool ALIGN_EPI = false, bool SP2 = false>
; __device__ __forceinline__ void gemm_phase(PG8_LAS unsigned char* lds, const Gemm g, const Sched& S, const Epi& E) {
;     ...
;         const char* nA = has_next ? (const char*)g.A + (size_t)nxt.pm * tstepA : cA; const char* nB = has_next ? (const char*)g.Bt + (size_t)nxt.pn * tstepB : cB;
;         for (int t = 0; t < nt; t += 2) {
;             const bool last = (t == nt - 2);
;             const char* a1 = cA + (size_t)(t + 1) * kstep;
;             const char* a2 = last ? nA : cA + (size_t)(t + 2) * kstep; const char* b2 = last ? nB : cB + (size_t)(t + 2) * kstep;
;             const char* a3 = a2 + kstep; const char* b3 = b2 + kstep;
;             if (last && has_next) S.a_ready(nxt);
;             if constexpr (SP2) {
;             PG8_LDB(B0, 0, 0); PG8_LDB(B1, 0, 1); PG8_SCHED; PG8_LDA(At, 0, 0); PG8_STAGE(PG8_SA(1, 1), a1 + hstepA, voffA);
;             PG8_WAIT_V(8); PG8_WAIT_L(0); PG8_BAR; PG8_MMA(0, 0, At, B0); PG8_MMA(0, 1, At, B1); PG8_BAR; PG8_SCHED;
;             PG8_LDA(At, 0, 1); PG8_STAGE(PG8_SB(0, 0), b2, voffB); PG8_STAGE(PG8_SB(0, 1), b2 + hstepB, voffB); PG8_STAGE(PG8_SA(0, 0), a2, voffA);
;             PG8_WAIT_V(8); PG8_WAIT_L(0); PG8_BAR; PG8_MMA(1, 0, At, B0); PG8_MMA(1, 1, At, B1); PG8_BAR; PG8_SCHED;
.LBB0_542:
	s_nop 0
	s_add_u32 s39, s34, s38
	s_addc_u32 s44, s35, 0
	s_add_u32 s42, s39, 0x100
	s_addc_u32 s43, s44, 0
	s_and_b64 s[40:41], s[36:37], exec
	s_cselect_b32 s41, s27, s43
	s_cselect_b32 s40, s26, s42
	s_add_u32 s38, s30, s38
	s_addc_u32 s42, s31, 0
	s_add_u32 s38, s38, 0x100
	s_addc_u32 s42, s42, 0
	s_and_b64 s[36:37], s[36:37], exec
	s_cselect_b32 s43, s25, s42
	s_cselect_b32 s42, s89, s38
	s_add_u32 s46, s39, 0x30080
	ds_read_b128 v[140:143], v149
	ds_read_b128 v[154:157], v149 offset:1024
	ds_read_b128 v[158:161], v149 offset:2048
	ds_read_b128 v[162:165], v149 offset:3072
	ds_read_b128 v[166:169], v150
	ds_read_b128 v[170:173], v150 offset:1024
	ds_read_b128 v[174:177], v150 offset:2048
	ds_read_b128 v[178:181], v150 offset:3072
	s_addc_u32 s47, s44, 0
	s_add_i32 vcc_hi, s78, s68
	s_add_i32 m0, s70, 0xc000
	s_add_i32 s58, s70, 0xe000
	s_add_i32 s96, vcc_hi, 0x2000
	s_add_u32 s44, s42, 0x10000
	s_addc_u32 s45, s43, 0
	s_add_i32 vcc_lo, s79, s68
	s_add_i32 s97, vcc_lo, 0x2000
	s_add_i32 s95, 0, 0x18000
	s_add_i32 s94, 0, 0x1c000
	s_add_u32 s38, s40, 0x30000
	s_addc_u32 s39, s41, 0
	s_add_i32 s93, s95, s68
	s_add_i32 s91, s93, 0x2000
	s_add_u32 s36, s42, 0x10080
	s_addc_u32 s37, s43, 0
	s_add_i32 s92, s94, s68
	s_add_i32 s90, s92, 0x2000
	v_lshl_add_u64 v[144:145], s[46:47], 0, v[134:135]
	ds_read_b128 v[182:185], v151
	ds_read_b128 v[188:191], v151 offset:1024
	ds_read_b128 v[192:195], v151 offset:2048
	ds_read_b128 v[196:199], v151 offset:3072
	ds_read_b128 v[200:203], v151 offset:4096
	ds_read_b128 v[204:207], v151 offset:5120
	ds_read_b128 v[208:211], v151 offset:6144
	ds_read_b128 v[212:215], v151 offset:7168
	global_load_lds_dwordx4 v[144:145], off
	v_lshl_add_u64 v[144:145], s[46:47], 0, v[130:131]
	s_mov_b32 m0, s58
	s_nop 0
	global_load_lds_dwordx4 v[144:145], off
	s_waitcnt vmcnt(8) lgkmcnt(0)
	s_barrier
	s_setprio 1
	v_mfma_f32_16x16x32_bf16 v[124:127], v[140:143], v[182:185], v[124:127]
	v_mfma_f32_16x16x32_bf16 v[120:123], v[158:161], v[182:185], v[120:123]
	v_mfma_f32_16x16x32_bf16 v[108:111], v[140:143], v[192:195], v[108:111]
	v_mfma_f32_16x16x32_bf16 v[104:107], v[158:161], v[192:195], v[104:107]
	v_mfma_f32_16x16x32_bf16 v[92:95], v[140:143], v[200:203], v[92:95]
	v_mfma_f32_16x16x32_bf16 v[88:91], v[158:161], v[200:203], v[88:91]
	v_mfma_f32_16x16x32_bf16 v[76:79], v[140:143], v[208:211], v[76:79]
	v_mfma_f32_16x16x32_bf16 v[72:75], v[158:161], v[208:211], v[72:75]
	v_mfma_f32_16x16x32_bf16 v[124:127], v[154:157], v[188:191], v[124:127]
	v_mfma_f32_16x16x32_bf16 v[120:123], v[162:165], v[188:191], v[120:123]
	v_mfma_f32_16x16x32_bf16 v[108:111], v[154:157], v[196:199], v[108:111]
	v_mfma_f32_16x16x32_bf16 v[104:107], v[162:165], v[196:199], v[104:107]
	v_mfma_f32_16x16x32_bf16 v[92:95], v[154:157], v[204:207], v[92:95]
	v_mfma_f32_16x16x32_bf16 v[88:91], v[162:165], v[204:207], v[88:91]
	v_mfma_f32_16x16x32_bf16 v[76:79], v[154:157], v[212:215], v[76:79]
	v_mfma_f32_16x16x32_bf16 v[72:75], v[162:165], v[212:215], v[72:75]
	s_setprio 0
	s_setprio 1
	v_mfma_f32_16x16x32_bf16 v[116:119], v[166:169], v[182:185], v[116:119]
	v_mfma_f32_16x16x32_bf16 v[112:115], v[174:177], v[182:185], v[112:115]
	v_mfma_f32_16x16x32_bf16 v[100:103], v[166:169], v[192:195], v[100:103]
	v_mfma_f32_16x16x32_bf16 v[96:99], v[174:177], v[192:195], v[96:99]
	v_mfma_f32_16x16x32_bf16 v[84:87], v[166:169], v[200:203], v[84:87]
	v_mfma_f32_16x16x32_bf16 v[80:83], v[174:177], v[200:203], v[80:83]
	v_mfma_f32_16x16x32_bf16 v[68:71], v[166:169], v[208:211], v[68:71]
	v_mfma_f32_16x16x32_bf16 v[64:67], v[174:177], v[208:211], v[64:67]
	v_mfma_f32_16x16x32_bf16 v[116:119], v[170:173], v[188:191], v[116:119]
	v_mfma_f32_16x16x32_bf16 v[112:115], v[178:181], v[188:191], v[112:115]
	v_mfma_f32_16x16x32_bf16 v[100:103], v[170:173], v[196:199], v[100:103]
	v_mfma_f32_16x16x32_bf16 v[96:99], v[178:181], v[196:199], v[96:99]
	v_mfma_f32_16x16x32_bf16 v[84:87], v[170:173], v[204:207], v[84:87]
	v_mfma_f32_16x16x32_bf16 v[80:83], v[178:181], v[204:207], v[80:83]
	v_mfma_f32_16x16x32_bf16 v[68:71], v[170:173], v[212:215], v[68:71]
	v_mfma_f32_16x16x32_bf16 v[64:67], v[178:181], v[212:215], v[64:67]
	s_barrier
	s_setprio 0
	s_mov_b32 m0, vcc_hi
	v_lshl_add_u64 v[144:145], s[42:43], 0, v[132:133]
	ds_read_b128 v[182:185], v151 offset:16384
	ds_read_b128 v[188:191], v151 offset:17408
	ds_read_b128 v[192:195], v151 offset:18432
	ds_read_b128 v[196:199], v151 offset:19456
	ds_read_b128 v[200:203], v151 offset:20480
	ds_read_b128 v[204:207], v151 offset:21504
	ds_read_b128 v[208:211], v151 offset:22528
	ds_read_b128 v[212:215], v151 offset:23552
	global_load_lds_dwordx4 v[144:145], off
	v_lshl_add_u64 v[216:217], s[42:43], 0, v[128:129]
	s_mov_b32 m0, s96
	v_lshl_add_u64 v[218:219], s[44:45], 0, v[132:133]
	global_load_lds_dwordx4 v[216:217], off
	s_mov_b32 m0, vcc_lo
	v_lshl_add_u64 v[220:221], s[40:41], 0, v[130:131]
	global_load_lds_dwordx4 v[218:219], off
	v_lshl_add_u64 v[218:219], s[44:45], 0, v[128:129]
	s_mov_b32 m0, s97
	s_nop 0
	global_load_lds_dwordx4 v[218:219], off
	v_lshl_add_u64 v[218:219], s[40:41], 0, v[134:135]
	s_mov_b32 m0, s70
	s_nop 0
	global_load_lds_dwordx4 v[218:219], off
	s_mov_b32 m0, s71
	s_nop 0
	global_load_lds_dwordx4 v[220:221], off
	s_waitcnt vmcnt(8) lgkmcnt(0)
	s_barrier
; #define PG8_STAGE(bufoff, gbase, voff) do { _Pragma("unroll") for (int _i = 0; _i < 2; ++_i) \
;         __builtin_amdgcn_global_load_lds((const unsigned*)((const char*)(gbase) + (voff)[_i]), (PG8_LAS unsigned*)(lds + (bufoff) + ldsw + _i * 8192), 16, 0, 0); } while (0)
; #define PG8_LDA(dst, b, h) do { _Pragma("unroll") for (int m = 0; m < 4; ++m) _Pragma("unroll") for (int k = 0; k < 2; ++k) dst[m][k] = *(const PG8_LAS bf16x8*)(lds + PG8_SA(b, h) + aoff + m * 2048 + k * 1024); } while (0)
; #define PG8_LDB(dst, b, h) do { _Pragma("unroll") for (int n = 0; n < 2; ++n) _Pragma("unroll") for (int k = 0; k < 2; ++k) dst[n][k] = *(const PG8_LAS bf16x8*)(lds + PG8_SB(b, h) + boff + n * 2048 + k * 1024); } while (0)
; #define PG8_MMA(ai, bj, At, Bt) do { __builtin_amdgcn_s_setprio(1); _Pragma("unroll") for (int m = 0; m < 4; ++m) _Pragma("unroll") for (int n = 0; n < 2; ++n) _Pragma("unroll") for (int k = 0; k < 2; ++k) \
;         acc[ai][bj][m][n] = __builtin_amdgcn_mfma_f32_16x16x32_bf16(Bt[n][k], At[m][k], acc[ai][bj][m][n], 0, 0, 0); __builtin_amdgcn_s_setprio(0); } while (0)
; #define PG8_WAIT_V(n) asm volatile("s_waitcnt vmcnt(" #n ")" ::: "memory")
; #define PG8_WAIT_L(n) asm volatile("s_waitcnt lgkmcnt(" #n ")" ::: "memory")
; #define PG8_BAR __builtin_amdgcn_s_barrier()
; #define PG8_SCHED __builtin_amdgcn_sched_barrier(0)
; template <class Epi, class Sched, bool ALIGN_EPI = false, bool SP2 = false>
; __device__ __forceinline__ void gemm_phase(PG8_LAS unsigned char* lds, const Gemm g, const Sched& S, const Epi& E) {
;     ...
;             PG8_WAIT_V(8); PG8_WAIT_L(0); PG8_BAR; PG8_MMA(1, 0, At, B0); PG8_MMA(1, 1, At, B1); PG8_BAR; PG8_SCHED;
;             PG8_LDB(B0, 1, 0); PG8_LDB(B1, 1, 1); PG8_SCHED; PG8_LDA(At, 1, 0); PG8_STAGE(PG8_SA(0, 1), a2 + hstepA, voffA);
;             PG8_WAIT_V(8); PG8_WAIT_L(0); PG8_BAR; PG8_MMA(0, 0, At, B0); PG8_MMA(0, 1, At, B1); PG8_BAR; PG8_SCHED;
;             PG8_LDA(At, 1, 1); PG8_STAGE(PG8_SB(1, 0), b3, voffB); PG8_STAGE(PG8_SB(1, 1), b3 + hstepB, voffB); PG8_STAGE(PG8_SA(1, 0), a3, voffA);
;             PG8_WAIT_V(8); PG8_WAIT_L(0); PG8_BAR; PG8_MMA(1, 0, At, B0); PG8_MMA(1, 1, At, B1); PG8_BAR; PG8_SCHED;
	s_setprio 1
	v_mfma_f32_16x16x32_bf16 v[60:63], v[140:143], v[182:185], v[60:63]
	v_mfma_f32_16x16x32_bf16 v[56:59], v[158:161], v[182:185], v[56:59]
	v_mfma_f32_16x16x32_bf16 v[44:47], v[140:143], v[192:195], v[44:47]
	v_mfma_f32_16x16x32_bf16 v[40:43], v[158:161], v[192:195], v[40:43]
	v_mfma_f32_16x16x32_bf16 v[28:31], v[140:143], v[200:203], v[28:31]
	v_mfma_f32_16x16x32_bf16 v[24:27], v[158:161], v[200:203], v[24:27]
	v_mfma_f32_16x16x32_bf16 v[12:15], v[140:143], v[208:211], v[12:15]
	v_mfma_f32_16x16x32_bf16 v[8:11], v[158:161], v[208:211], v[8:11]
	v_mfma_f32_16x16x32_bf16 v[60:63], v[154:157], v[188:191], v[60:63]
	v_mfma_f32_16x16x32_bf16 v[56:59], v[162:165], v[188:191], v[56:59]
	v_mfma_f32_16x16x32_bf16 v[44:47], v[154:157], v[196:199], v[44:47]
	v_mfma_f32_16x16x32_bf16 v[40:43], v[162:165], v[196:199], v[40:43]
	v_mfma_f32_16x16x32_bf16 v[28:31], v[154:157], v[204:207], v[28:31]
	v_mfma_f32_16x16x32_bf16 v[24:27], v[162:165], v[204:207], v[24:27]
	v_mfma_f32_16x16x32_bf16 v[12:15], v[154:157], v[212:215], v[12:15]
	v_mfma_f32_16x16x32_bf16 v[8:11], v[162:165], v[212:215], v[8:11]
	s_setprio 0
	s_setprio 1
	v_mfma_f32_16x16x32_bf16 v[52:55], v[166:169], v[182:185], v[52:55]
	v_mfma_f32_16x16x32_bf16 v[48:51], v[174:177], v[182:185], v[48:51]
	v_mfma_f32_16x16x32_bf16 v[36:39], v[166:169], v[192:195], v[36:39]
	v_mfma_f32_16x16x32_bf16 v[32:35], v[174:177], v[192:195], v[32:35]
	v_mfma_f32_16x16x32_bf16 v[20:23], v[166:169], v[200:203], v[20:23]
	v_mfma_f32_16x16x32_bf16 v[16:19], v[174:177], v[200:203], v[16:19]
	v_mfma_f32_16x16x32_bf16 v[4:7], v[166:169], v[208:211], v[4:7]
	v_mfma_f32_16x16x32_bf16 v[0:3], v[174:177], v[208:211], v[0:3]
	v_mfma_f32_16x16x32_bf16 v[52:55], v[170:173], v[188:191], v[52:55]
	v_mfma_f32_16x16x32_bf16 v[48:51], v[178:181], v[188:191], v[48:51]
	v_mfma_f32_16x16x32_bf16 v[36:39], v[170:173], v[196:199], v[36:39]
	v_mfma_f32_16x16x32_bf16 v[32:35], v[178:181], v[196:199], v[32:35]
	v_mfma_f32_16x16x32_bf16 v[20:23], v[170:173], v[204:207], v[20:23]
	v_mfma_f32_16x16x32_bf16 v[16:19], v[178:181], v[204:207], v[16:19]
	v_mfma_f32_16x16x32_bf16 v[4:7], v[170:173], v[212:215], v[4:7]
	v_mfma_f32_16x16x32_bf16 v[0:3], v[178:181], v[212:215], v[0:3]
	s_barrier
	s_setprio 0
	v_add_u32_e32 v153, s95, v147
	ds_read_b128 v[140:143], v153
	ds_read_b128 v[154:157], v153 offset:1024
	ds_read_b128 v[158:161], v153 offset:2048
	ds_read_b128 v[162:165], v153 offset:3072
	v_add_u32_e32 v153, s94, v147
	ds_read_b128 v[166:169], v153
	ds_read_b128 v[170:173], v153 offset:1024
	ds_read_b128 v[174:177], v153 offset:2048
	ds_read_b128 v[178:181], v153 offset:3072
	s_mov_b32 m0, s72
	v_lshl_add_u64 v[222:223], s[38:39], 0, v[134:135]
	ds_read_b128 v[182:185], v151 offset:32768
	ds_read_b128 v[188:191], v151 offset:33792
	ds_read_b128 v[192:195], v151 offset:34816
	ds_read_b128 v[196:199], v151 offset:35840
	ds_read_b128 v[200:203], v151 offset:36864
	ds_read_b128 v[204:207], v151 offset:37888
	ds_read_b128 v[208:211], v151 offset:38912
	ds_read_b128 v[212:215], v151 offset:39936
	global_load_lds_dwordx4 v[222:223], off
	v_lshl_add_u64 v[222:223], s[38:39], 0, v[130:131]
	s_mov_b32 m0, s73
	s_nop 0
	global_load_lds_dwordx4 v[222:223], off
	s_waitcnt vmcnt(8) lgkmcnt(0)
	s_barrier
	s_setprio 1
	v_mfma_f32_16x16x32_bf16 v[124:127], v[140:143], v[182:185], v[124:127]
	v_mfma_f32_16x16x32_bf16 v[120:123], v[158:161], v[182:185], v[120:123]
	v_mfma_f32_16x16x32_bf16 v[108:111], v[140:143], v[192:195], v[108:111]
	v_mfma_f32_16x16x32_bf16 v[104:107], v[158:161], v[192:195], v[104:107]
	v_mfma_f32_16x16x32_bf16 v[92:95], v[140:143], v[200:203], v[92:95]
	v_mfma_f32_16x16x32_bf16 v[88:91], v[158:161], v[200:203], v[88:91]
	v_mfma_f32_16x16x32_bf16 v[76:79], v[140:143], v[208:211], v[76:79]
	v_mfma_f32_16x16x32_bf16 v[72:75], v[158:161], v[208:211], v[72:75]
	v_mfma_f32_16x16x32_bf16 v[124:127], v[154:157], v[188:191], v[124:127]
	v_mfma_f32_16x16x32_bf16 v[120:123], v[162:165], v[188:191], v[120:123]
	v_mfma_f32_16x16x32_bf16 v[108:111], v[154:157], v[196:199], v[108:111]
	v_mfma_f32_16x16x32_bf16 v[104:107], v[162:165], v[196:199], v[104:107]
	v_mfma_f32_16x16x32_bf16 v[92:95], v[154:157], v[204:207], v[92:95]
	v_mfma_f32_16x16x32_bf16 v[88:91], v[162:165], v[204:207], v[88:91]
	v_mfma_f32_16x16x32_bf16 v[76:79], v[154:157], v[212:215], v[76:79]
	v_mfma_f32_16x16x32_bf16 v[72:75], v[162:165], v[212:215], v[72:75]
	s_setprio 0
	s_setprio 1
	v_mfma_f32_16x16x32_bf16 v[116:119], v[166:169], v[182:185], v[116:119]
	v_mfma_f32_16x16x32_bf16 v[112:115], v[174:177], v[182:185], v[112:115]
	v_mfma_f32_16x16x32_bf16 v[100:103], v[166:169], v[192:195], v[100:103]
	v_mfma_f32_16x16x32_bf16 v[96:99], v[174:177], v[192:195], v[96:99]
	v_mfma_f32_16x16x32_bf16 v[84:87], v[166:169], v[200:203], v[84:87]
	v_mfma_f32_16x16x32_bf16 v[80:83], v[174:177], v[200:203], v[80:83]
	v_mfma_f32_16x16x32_bf16 v[68:71], v[166:169], v[208:211], v[68:71]
	v_mfma_f32_16x16x32_bf16 v[64:67], v[174:177], v[208:211], v[64:67]
	v_mfma_f32_16x16x32_bf16 v[116:119], v[170:173], v[188:191], v[116:119]
	v_mfma_f32_16x16x32_bf16 v[112:115], v[178:181], v[188:191], v[112:115]
	v_mfma_f32_16x16x32_bf16 v[100:103], v[170:173], v[196:199], v[100:103]
	v_mfma_f32_16x16x32_bf16 v[96:99], v[178:181], v[196:199], v[96:99]
	v_mfma_f32_16x16x32_bf16 v[84:87], v[170:173], v[204:207], v[84:87]
	v_mfma_f32_16x16x32_bf16 v[80:83], v[178:181], v[204:207], v[80:83]
	v_mfma_f32_16x16x32_bf16 v[68:71], v[170:173], v[212:215], v[68:71]
	v_mfma_f32_16x16x32_bf16 v[64:67], v[178:181], v[212:215], v[64:67]
	s_barrier
; #define PG8_STAGE(bufoff, gbase, voff) do { _Pragma("unroll") for (int _i = 0; _i < 2; ++_i) \
;         __builtin_amdgcn_global_load_lds((const unsigned*)((const char*)(gbase) + (voff)[_i]), (PG8_LAS unsigned*)(lds + (bufoff) + ldsw + _i * 8192), 16, 0, 0); } while (0)
; #define PG8_LDA(dst, b, h) do { _Pragma("unroll") for (int m = 0; m < 4; ++m) _Pragma("unroll") for (int k = 0; k < 2; ++k) dst[m][k] = *(const PG8_LAS bf16x8*)(lds + PG8_SA(b, h) + aoff + m * 2048 + k * 1024); } while (0)
; #define PG8_MMA(ai, bj, At, Bt) do { __builtin_amdgcn_s_setprio(1); _Pragma("unroll") for (int m = 0; m < 4; ++m) _Pragma("unroll") for (int n = 0; n < 2; ++n) _Pragma("unroll") for (int k = 0; k < 2; ++k) \
;         acc[ai][bj][m][n] = __builtin_amdgcn_mfma_f32_16x16x32_bf16(Bt[n][k], At[m][k], acc[ai][bj][m][n], 0, 0, 0); __builtin_amdgcn_s_setprio(0); } while (0)
; #define PG8_WAIT_V(n) asm volatile("s_waitcnt vmcnt(" #n ")" ::: "memory")
; #define PG8_WAIT_L(n) asm volatile("s_waitcnt lgkmcnt(" #n ")" ::: "memory")
; #define PG8_BAR __builtin_amdgcn_s_barrier()
; #define PG8_SCHED __builtin_amdgcn_sched_barrier(0)
; template <class Epi, class Sched, bool ALIGN_EPI = false, bool SP2 = false>
; __device__ __forceinline__ void gemm_phase(PG8_LAS unsigned char* lds, const Gemm g, const Sched& S, const Epi& E) {
;     ...
;             PG8_LDA(At, 1, 1); PG8_STAGE(PG8_SB(1, 0), b3, voffB); PG8_STAGE(PG8_SB(1, 1), b3 + hstepB, voffB); PG8_STAGE(PG8_SA(1, 0), a3, voffA);
;             PG8_WAIT_V(8); PG8_WAIT_L(0); PG8_BAR; PG8_MMA(1, 0, At, B0); PG8_MMA(1, 1, At, B1); PG8_BAR; PG8_SCHED;
;     ...
;         if constexpr (ALIGN_EPI) { if (wr == 0) PG8_BAR; }
	s_setprio 0
	s_mov_b32 m0, s93
	v_lshl_add_u64 v[144:145], v[144:145], 0, s[12:13]
	ds_read_b128 v[182:185], v151 offset:49152
	ds_read_b128 v[188:191], v151 offset:50176
	ds_read_b128 v[192:195], v151 offset:51200
	ds_read_b128 v[196:199], v151 offset:52224
	ds_read_b128 v[200:203], v151 offset:53248
	ds_read_b128 v[204:207], v151 offset:54272
	ds_read_b128 v[208:211], v151 offset:55296
	ds_read_b128 v[212:215], v151 offset:56320
	global_load_lds_dwordx4 v[144:145], off
	v_lshl_add_u64 v[144:145], v[216:217], 0, s[12:13]
	s_mov_b32 m0, s91
	s_nop 0
	global_load_lds_dwordx4 v[144:145], off
	v_lshl_add_u64 v[144:145], s[36:37], 0, v[132:133]
	s_mov_b32 m0, s92
	s_nop 0
	global_load_lds_dwordx4 v[144:145], off
	v_lshl_add_u64 v[144:145], s[36:37], 0, v[128:129]
	s_mov_b32 m0, s90
	s_nop 0
	global_load_lds_dwordx4 v[144:145], off
	v_lshl_add_u64 v[144:145], v[218:219], 0, s[12:13]
	s_mov_b32 m0, s75
	s_nop 0
	global_load_lds_dwordx4 v[144:145], off
	v_lshl_add_u64 v[144:145], v[220:221], 0, s[12:13]
	s_mov_b32 m0, s76
	s_nop 0
	global_load_lds_dwordx4 v[144:145], off
	s_waitcnt vmcnt(8) lgkmcnt(0)
	s_barrier
	s_setprio 1
	v_mfma_f32_16x16x32_bf16 v[60:63], v[140:143], v[182:185], v[60:63]
	v_mfma_f32_16x16x32_bf16 v[56:59], v[158:161], v[182:185], v[56:59]
	v_mfma_f32_16x16x32_bf16 v[44:47], v[140:143], v[192:195], v[44:47]
	v_mfma_f32_16x16x32_bf16 v[40:43], v[158:161], v[192:195], v[40:43]
	v_mfma_f32_16x16x32_bf16 v[28:31], v[140:143], v[200:203], v[28:31]
	v_mfma_f32_16x16x32_bf16 v[24:27], v[158:161], v[200:203], v[24:27]
	v_mfma_f32_16x16x32_bf16 v[12:15], v[140:143], v[208:211], v[12:15]
	v_mfma_f32_16x16x32_bf16 v[8:11], v[158:161], v[208:211], v[8:11]
	v_mfma_f32_16x16x32_bf16 v[60:63], v[154:157], v[188:191], v[60:63]
	v_mfma_f32_16x16x32_bf16 v[56:59], v[162:165], v[188:191], v[56:59]
	v_mfma_f32_16x16x32_bf16 v[44:47], v[154:157], v[196:199], v[44:47]
	v_mfma_f32_16x16x32_bf16 v[40:43], v[162:165], v[196:199], v[40:43]
	v_mfma_f32_16x16x32_bf16 v[28:31], v[154:157], v[204:207], v[28:31]
	v_mfma_f32_16x16x32_bf16 v[24:27], v[162:165], v[204:207], v[24:27]
	v_mfma_f32_16x16x32_bf16 v[12:15], v[154:157], v[212:215], v[12:15]
	v_mfma_f32_16x16x32_bf16 v[8:11], v[162:165], v[212:215], v[8:11]
	s_setprio 0
	s_setprio 1
	v_mfma_f32_16x16x32_bf16 v[52:55], v[166:169], v[182:185], v[52:55]
	v_mfma_f32_16x16x32_bf16 v[48:51], v[174:177], v[182:185], v[48:51]
	v_mfma_f32_16x16x32_bf16 v[36:39], v[166:169], v[192:195], v[36:39]
	v_mfma_f32_16x16x32_bf16 v[32:35], v[174:177], v[192:195], v[32:35]
	v_mfma_f32_16x16x32_bf16 v[20:23], v[166:169], v[200:203], v[20:23]
	v_mfma_f32_16x16x32_bf16 v[16:19], v[174:177], v[200:203], v[16:19]
	v_mfma_f32_16x16x32_bf16 v[4:7], v[166:169], v[208:211], v[4:7]
	v_mfma_f32_16x16x32_bf16 v[0:3], v[174:177], v[208:211], v[0:3]
	v_mfma_f32_16x16x32_bf16 v[52:55], v[170:173], v[188:191], v[52:55]
	v_mfma_f32_16x16x32_bf16 v[48:51], v[178:181], v[188:191], v[48:51]
	v_mfma_f32_16x16x32_bf16 v[36:39], v[170:173], v[196:199], v[36:39]
	v_mfma_f32_16x16x32_bf16 v[32:35], v[178:181], v[196:199], v[32:35]
	v_mfma_f32_16x16x32_bf16 v[20:23], v[170:173], v[204:207], v[20:23]
	v_mfma_f32_16x16x32_bf16 v[16:19], v[178:181], v[204:207], v[16:19]
	v_mfma_f32_16x16x32_bf16 v[4:7], v[170:173], v[212:215], v[4:7]
	v_mfma_f32_16x16x32_bf16 v[0:3], v[178:181], v[212:215], v[0:3]
	s_barrier
	s_setprio 0
	s_movk_i32 s38, 0x100
	s_andn2_b64 vcc, exec, s[8:9]
	s_mov_b64 s[36:37], -1
	s_mov_b64 s[8:9], 0
	s_cbranch_vccz .LBB0_542
	s_and_b64 vcc, exec, s[14:15]
	s_cbranch_vccz .LBB0_545
	s_barrier

; #define PG8_STAGE(bufoff, gbase, voff) do { _Pragma("unroll") for (int _i = 0; _i < 2; ++_i) \
;         __builtin_amdgcn_global_load_lds((const unsigned*)((const char*)(gbase) + (voff)[_i]), (PG8_LAS unsigned*)(lds + (bufoff) + ldsw + _i * 8192), 16, 0, 0); } while (0)
; #define PG8_LDA(dst, b, h) do { _Pragma("unroll") for (int m = 0; m < 4; ++m) _Pragma("unroll") for (int k = 0; k < 2; ++k) dst[m][k] = *(const PG8_LAS bf16x8*)(lds + PG8_SA(b, h) + aoff + m * 2048 + k * 1024); } while (0)
; #define PG8_LDB(dst, b, h) do { _Pragma("unroll") for (int n = 0; n < 2; ++n) _Pragma("unroll") for (int k = 0; k < 2; ++k) dst[n][k] = *(const PG8_LAS bf16x8*)(lds + PG8_SB(b, h) + boff + n * 2048 + k * 1024); } while (0)
; #define PG8_MMA(ai, bj, At, Bt) do { __builtin_amdgcn_s_setprio(1); _Pragma("unroll") for (int m = 0; m < 4; ++m) _Pragma("unroll") for (int n = 0; n < 2; ++n) _Pragma("unroll") for (int k = 0; k < 2; ++k) \
;         acc[ai][bj][m][n] = __builtin_amdgcn_mfma_f32_16x16x32_bf16(Bt[n][k], At[m][k], acc[ai][bj][m][n], 0, 0, 0); __builtin_amdgcn_s_setprio(0); } while (0)
; #define PG8_WAIT_V(n) asm volatile("s_waitcnt vmcnt(" #n ")" ::: "memory")
; #define PG8_BAR __builtin_amdgcn_s_barrier()
; template <class Epi, class Sched, bool ALIGN_EPI = false, bool SP2 = false>
; __device__ __forceinline__ void gemm_phase(PG8_LAS unsigned char* lds, const Gemm g, const Sched& S, const Epi& E) {
;     ...
;         for (int t = 0; t < nt; t += 2) {
;             const bool last = (t == nt - 2);
;             const char* a1 = cA + (size_t)(t + 1) * kstep;
;             const char* a2 = last ? nA : cA + (size_t)(t + 2) * kstep; const char* b2 = last ? nB : cB + (size_t)(t + 2) * kstep;
;             const char* a3 = a2 + kstep; const char* b3 = b2 + kstep;
;             if (last && has_next) S.a_ready(nxt);
;             if constexpr (SP2) {
;             PG8_LDB(B0, 0, 0); PG8_LDB(B1, 0, 1); PG8_SCHED; PG8_LDA(At, 0, 0); PG8_STAGE(PG8_SA(1, 1), a1 + hstepA, voffA);
;             PG8_WAIT_V(8); PG8_WAIT_L(0); PG8_BAR; PG8_MMA(0, 0, At, B0); PG8_MMA(0, 1, At, B1); PG8_BAR; PG8_SCHED;
;             PG8_LDA(At, 0, 1); PG8_STAGE(PG8_SB(0, 0), b2, voffB); PG8_STAGE(PG8_SB(0, 1), b2 + hstepB, voffB); PG8_STAGE(PG8_SA(0, 0), a2, voffA);
;             PG8_WAIT_V(8); PG8_WAIT_L(0); PG8_BAR; PG8_MMA(1, 0, At, B0); PG8_MMA(1, 1, At, B1); PG8_BAR; PG8_SCHED;
.LBB0_971:
	s_nop 0
	ds_read_b128 v[128:131], v191
	ds_read_b128 v[132:135], v191 offset:1024
	ds_read_b128 v[136:139], v191 offset:2048
	ds_read_b128 v[140:143], v191 offset:3072
	ds_read_b128 v[144:147], v192
	ds_read_b128 v[148:151], v192 offset:1024
	ds_read_b128 v[168:171], v192 offset:2048
	ds_read_b128 v[172:175], v192 offset:3072
	s_add_u32 s34, s30, 0xfffc0080
	s_addc_u32 s35, s31, -1
	s_cmp_eq_u32 s74, 12
	s_cselect_b32 s37, s21, s35
	s_cselect_b32 s36, s27, s34
	s_cselect_b32 s35, s19, s73
	s_cselect_b32 s34, s68, s69
	v_lshl_add_u64 v[184:185], s[30:31], 0, v[160:161]
	s_add_i32 m0, s29, 0xc000
	ds_read_b128 v[176:179], v193
	ds_read_b128 v[180:183], v193 offset:1024
	ds_read_b128 v[196:199], v193 offset:2048
	ds_read_b128 v[200:203], v193 offset:3072
	ds_read_b128 v[204:207], v193 offset:4096
	ds_read_b128 v[208:211], v193 offset:5120
	ds_read_b128 v[212:215], v193 offset:6144
	ds_read_b128 v[216:219], v193 offset:7168
	global_load_lds_dwordx4 v[184:185], off
	v_lshl_add_u64 v[184:185], s[30:31], 0, v[162:163]
	s_add_i32 m0, s29, 0xe000
	s_nop 0
	global_load_lds_dwordx4 v[184:185], off
	s_waitcnt vmcnt(8) lgkmcnt(0)
	s_barrier
	s_setprio 1
	v_mfma_f32_16x16x32_bf16 v[124:127], v[128:131], v[176:179], v[124:127]
	v_mfma_f32_16x16x32_bf16 v[120:123], v[136:139], v[176:179], v[120:123]
	v_mfma_f32_16x16x32_bf16 v[108:111], v[128:131], v[196:199], v[108:111]
	v_mfma_f32_16x16x32_bf16 v[104:107], v[136:139], v[196:199], v[104:107]
	v_mfma_f32_16x16x32_bf16 v[92:95], v[128:131], v[204:207], v[92:95]
	v_mfma_f32_16x16x32_bf16 v[88:91], v[136:139], v[204:207], v[88:91]
	v_mfma_f32_16x16x32_bf16 v[76:79], v[128:131], v[212:215], v[76:79]
	v_mfma_f32_16x16x32_bf16 v[72:75], v[136:139], v[212:215], v[72:75]
	v_mfma_f32_16x16x32_bf16 v[124:127], v[132:135], v[180:183], v[124:127]
	v_mfma_f32_16x16x32_bf16 v[120:123], v[140:143], v[180:183], v[120:123]
	v_mfma_f32_16x16x32_bf16 v[108:111], v[132:135], v[200:203], v[108:111]
	v_mfma_f32_16x16x32_bf16 v[104:107], v[140:143], v[200:203], v[104:107]
	v_mfma_f32_16x16x32_bf16 v[92:95], v[132:135], v[208:211], v[92:95]
	v_mfma_f32_16x16x32_bf16 v[88:91], v[140:143], v[208:211], v[88:91]
	v_mfma_f32_16x16x32_bf16 v[76:79], v[132:135], v[216:219], v[76:79]
	v_mfma_f32_16x16x32_bf16 v[72:75], v[140:143], v[216:219], v[72:75]
	s_setprio 0
	s_setprio 1
	v_mfma_f32_16x16x32_bf16 v[116:119], v[144:147], v[176:179], v[116:119]
	v_mfma_f32_16x16x32_bf16 v[112:115], v[168:171], v[176:179], v[112:115]
	v_mfma_f32_16x16x32_bf16 v[100:103], v[144:147], v[196:199], v[100:103]
	v_mfma_f32_16x16x32_bf16 v[96:99], v[168:171], v[196:199], v[96:99]
	v_mfma_f32_16x16x32_bf16 v[84:87], v[144:147], v[204:207], v[84:87]
	v_mfma_f32_16x16x32_bf16 v[80:83], v[168:171], v[204:207], v[80:83]
	v_mfma_f32_16x16x32_bf16 v[68:71], v[144:147], v[212:215], v[68:71]
	v_mfma_f32_16x16x32_bf16 v[64:67], v[168:171], v[212:215], v[64:67]
	v_mfma_f32_16x16x32_bf16 v[116:119], v[148:151], v[180:183], v[116:119]
	v_mfma_f32_16x16x32_bf16 v[112:115], v[172:175], v[180:183], v[112:115]
	v_mfma_f32_16x16x32_bf16 v[100:103], v[148:151], v[200:203], v[100:103]
	v_mfma_f32_16x16x32_bf16 v[96:99], v[172:175], v[200:203], v[96:99]
	v_mfma_f32_16x16x32_bf16 v[84:87], v[148:151], v[208:211], v[84:87]
	v_mfma_f32_16x16x32_bf16 v[80:83], v[172:175], v[208:211], v[80:83]
	v_mfma_f32_16x16x32_bf16 v[68:71], v[148:151], v[216:219], v[68:71]
	v_mfma_f32_16x16x32_bf16 v[64:67], v[172:175], v[216:219], v[64:67]
	s_barrier
	s_setprio 0
	s_nop 0
	s_add_i32 s58, s49, s39
	v_lshl_add_u64 v[184:185], s[34:35], 0, v[154:155]
	s_mov_b32 m0, s58
	ds_read_b128 v[176:179], v193 offset:16384
	ds_read_b128 v[180:183], v193 offset:17408
	ds_read_b128 v[196:199], v193 offset:18432
	ds_read_b128 v[200:203], v193 offset:19456
	ds_read_b128 v[204:207], v193 offset:20480
	ds_read_b128 v[208:211], v193 offset:21504
	ds_read_b128 v[212:215], v193 offset:22528
	ds_read_b128 v[216:219], v193 offset:23552
	global_load_lds_dwordx4 v[184:185], off
	s_add_i32 m0, s58, 0x2000
	s_add_u32 s58, s34, 0x40000
	v_lshl_add_u64 v[220:221], s[34:35], 0, v[158:159]
	s_addc_u32 s59, s35, 0
	s_add_i32 s75, s66, s39
	global_load_lds_dwordx4 v[220:221], off
	v_lshl_add_u64 v[222:223], s[58:59], 0, v[154:155]
	s_mov_b32 m0, s75
	v_lshl_add_u64 v[224:225], s[36:37], 0, v[156:157]
	global_load_lds_dwordx4 v[222:223], off
	v_lshl_add_u64 v[222:223], s[58:59], 0, v[158:159]
	s_add_i32 m0, s75, 0x2000
	s_nop 0
	global_load_lds_dwordx4 v[222:223], off
	v_lshl_add_u64 v[222:223], s[36:37], 0, v[152:153]
	s_mov_b32 m0, s29
	s_nop 0
	global_load_lds_dwordx4 v[222:223], off
	s_mov_b32 m0, s40
	s_nop 0
	global_load_lds_dwordx4 v[224:225], off
	s_waitcnt vmcnt(8) lgkmcnt(0)
	s_barrier
; #define PG8_STAGE(bufoff, gbase, voff) do { _Pragma("unroll") for (int _i = 0; _i < 2; ++_i) \
;         __builtin_amdgcn_global_load_lds((const unsigned*)((const char*)(gbase) + (voff)[_i]), (PG8_LAS unsigned*)(lds + (bufoff) + ldsw + _i * 8192), 16, 0, 0); } while (0)
; #define PG8_LDA(dst, b, h) do { _Pragma("unroll") for (int m = 0; m < 4; ++m) _Pragma("unroll") for (int k = 0; k < 2; ++k) dst[m][k] = *(const PG8_LAS bf16x8*)(lds + PG8_SA(b, h) + aoff + m * 2048 + k * 1024); } while (0)
; #define PG8_LDB(dst, b, h) do { _Pragma("unroll") for (int n = 0; n < 2; ++n) _Pragma("unroll") for (int k = 0; k < 2; ++k) dst[n][k] = *(const PG8_LAS bf16x8*)(lds + PG8_SB(b, h) + boff + n * 2048 + k * 1024); } while (0)
; #define PG8_MMA(ai, bj, At, Bt) do { __builtin_amdgcn_s_setprio(1); _Pragma("unroll") for (int m = 0; m < 4; ++m) _Pragma("unroll") for (int n = 0; n < 2; ++n) _Pragma("unroll") for (int k = 0; k < 2; ++k) \
;         acc[ai][bj][m][n] = __builtin_amdgcn_mfma_f32_16x16x32_bf16(Bt[n][k], At[m][k], acc[ai][bj][m][n], 0, 0, 0); __builtin_amdgcn_s_setprio(0); } while (0)
; #define PG8_WAIT_V(n) asm volatile("s_waitcnt vmcnt(" #n ")" ::: "memory")
; #define PG8_WAIT_L(n) asm volatile("s_waitcnt lgkmcnt(" #n ")" ::: "memory")
; #define PG8_BAR __builtin_amdgcn_s_barrier()
; #define PG8_SCHED __builtin_amdgcn_sched_barrier(0)
; template <class Epi, class Sched, bool ALIGN_EPI = false, bool SP2 = false>
; __device__ __forceinline__ void gemm_phase(PG8_LAS unsigned char* lds, const Gemm g, const Sched& S, const Epi& E) {
;     ...
;             PG8_WAIT_V(8); PG8_WAIT_L(0); PG8_BAR; PG8_MMA(1, 0, At, B0); PG8_MMA(1, 1, At, B1); PG8_BAR; PG8_SCHED;
;             PG8_LDB(B0, 1, 0); PG8_LDB(B1, 1, 1); PG8_SCHED; PG8_LDA(At, 1, 0); PG8_STAGE(PG8_SA(0, 1), a2 + hstepA, voffA);
;             PG8_WAIT_V(8); PG8_WAIT_L(0); PG8_BAR; PG8_MMA(0, 0, At, B0); PG8_MMA(0, 1, At, B1); PG8_BAR; PG8_SCHED;
;             PG8_LDA(At, 1, 1); PG8_STAGE(PG8_SB(1, 0), b3, voffB); PG8_STAGE(PG8_SB(1, 1), b3 + hstepB, voffB); PG8_STAGE(PG8_SA(1, 0), a3, voffA);
;             PG8_WAIT_V(8); PG8_WAIT_L(0); PG8_BAR; PG8_MMA(1, 0, At, B0); PG8_MMA(1, 1, At, B1); PG8_BAR; PG8_SCHED;
	s_setprio 1
	v_mfma_f32_16x16x32_bf16 v[60:63], v[128:131], v[176:179], v[60:63]
	v_mfma_f32_16x16x32_bf16 v[56:59], v[136:139], v[176:179], v[56:59]
	v_mfma_f32_16x16x32_bf16 v[44:47], v[128:131], v[196:199], v[44:47]
	v_mfma_f32_16x16x32_bf16 v[40:43], v[136:139], v[196:199], v[40:43]
	v_mfma_f32_16x16x32_bf16 v[28:31], v[128:131], v[204:207], v[28:31]
	v_mfma_f32_16x16x32_bf16 v[24:27], v[136:139], v[204:207], v[24:27]
	v_mfma_f32_16x16x32_bf16 v[12:15], v[128:131], v[212:215], v[12:15]
	v_mfma_f32_16x16x32_bf16 v[8:11], v[136:139], v[212:215], v[8:11]
	v_mfma_f32_16x16x32_bf16 v[60:63], v[132:135], v[180:183], v[60:63]
	v_mfma_f32_16x16x32_bf16 v[56:59], v[140:143], v[180:183], v[56:59]
	v_mfma_f32_16x16x32_bf16 v[44:47], v[132:135], v[200:203], v[44:47]
	v_mfma_f32_16x16x32_bf16 v[40:43], v[140:143], v[200:203], v[40:43]
	v_mfma_f32_16x16x32_bf16 v[28:31], v[132:135], v[208:211], v[28:31]
	v_mfma_f32_16x16x32_bf16 v[24:27], v[140:143], v[208:211], v[24:27]
	v_mfma_f32_16x16x32_bf16 v[12:15], v[132:135], v[216:219], v[12:15]
	v_mfma_f32_16x16x32_bf16 v[8:11], v[140:143], v[216:219], v[8:11]
	s_setprio 0
	s_setprio 1
	v_mfma_f32_16x16x32_bf16 v[52:55], v[144:147], v[176:179], v[52:55]
	v_mfma_f32_16x16x32_bf16 v[48:51], v[168:171], v[176:179], v[48:51]
	v_mfma_f32_16x16x32_bf16 v[36:39], v[144:147], v[196:199], v[36:39]
	v_mfma_f32_16x16x32_bf16 v[32:35], v[168:171], v[196:199], v[32:35]
	v_mfma_f32_16x16x32_bf16 v[20:23], v[144:147], v[204:207], v[20:23]
	v_mfma_f32_16x16x32_bf16 v[16:19], v[168:171], v[204:207], v[16:19]
	v_mfma_f32_16x16x32_bf16 v[4:7], v[144:147], v[212:215], v[4:7]
	v_mfma_f32_16x16x32_bf16 v[0:3], v[168:171], v[212:215], v[0:3]
	v_mfma_f32_16x16x32_bf16 v[52:55], v[148:151], v[180:183], v[52:55]
	v_mfma_f32_16x16x32_bf16 v[48:51], v[172:175], v[180:183], v[48:51]
	v_mfma_f32_16x16x32_bf16 v[36:39], v[148:151], v[200:203], v[36:39]
	v_mfma_f32_16x16x32_bf16 v[32:35], v[172:175], v[200:203], v[32:35]
	v_mfma_f32_16x16x32_bf16 v[20:23], v[148:151], v[208:211], v[20:23]
	v_mfma_f32_16x16x32_bf16 v[16:19], v[172:175], v[208:211], v[16:19]
	v_mfma_f32_16x16x32_bf16 v[4:7], v[148:151], v[216:219], v[4:7]
	v_mfma_f32_16x16x32_bf16 v[0:3], v[172:175], v[216:219], v[0:3]
	s_barrier
	s_setprio 0
	s_nop 0
	s_add_i32 s58, 0, 0x18000
	s_add_i32 s59, 0, 0x1c000
	v_add_u32_e32 v140, s58, v189
	v_add_u32_e32 v172, s59, v189
	ds_read_b128 v[128:131], v140
	ds_read_b128 v[132:135], v140 offset:1024
	ds_read_b128 v[136:139], v140 offset:2048
	ds_read_b128 v[140:143], v140 offset:3072
	ds_read_b128 v[144:147], v172
	ds_read_b128 v[148:151], v172 offset:1024
	ds_read_b128 v[168:171], v172 offset:2048
	ds_read_b128 v[172:175], v172 offset:3072
	s_add_u32 s36, s36, 0x40000
	s_addc_u32 s37, s37, 0
	s_mov_b32 m0, s41
	v_lshl_add_u64 v[226:227], s[36:37], 0, v[152:153]
	ds_read_b128 v[176:179], v193 offset:32768
	ds_read_b128 v[180:183], v193 offset:33792
	ds_read_b128 v[196:199], v193 offset:34816
	ds_read_b128 v[200:203], v193 offset:35840
	ds_read_b128 v[204:207], v193 offset:36864
	ds_read_b128 v[208:211], v193 offset:37888
	ds_read_b128 v[212:215], v193 offset:38912
	ds_read_b128 v[216:219], v193 offset:39936
	global_load_lds_dwordx4 v[226:227], off
	v_lshl_add_u64 v[226:227], s[36:37], 0, v[156:157]
	s_mov_b32 m0, s42
	s_nop 0
	global_load_lds_dwordx4 v[226:227], off
	s_waitcnt vmcnt(8) lgkmcnt(0)
	s_barrier
	s_setprio 1
	v_mfma_f32_16x16x32_bf16 v[124:127], v[128:131], v[176:179], v[124:127]
	v_mfma_f32_16x16x32_bf16 v[120:123], v[136:139], v[176:179], v[120:123]
	v_mfma_f32_16x16x32_bf16 v[108:111], v[128:131], v[196:199], v[108:111]
	v_mfma_f32_16x16x32_bf16 v[104:107], v[136:139], v[196:199], v[104:107]
	v_mfma_f32_16x16x32_bf16 v[92:95], v[128:131], v[204:207], v[92:95]
	v_mfma_f32_16x16x32_bf16 v[88:91], v[136:139], v[204:207], v[88:91]
	v_mfma_f32_16x16x32_bf16 v[76:79], v[128:131], v[212:215], v[76:79]
	v_mfma_f32_16x16x32_bf16 v[72:75], v[136:139], v[212:215], v[72:75]
	v_mfma_f32_16x16x32_bf16 v[124:127], v[132:135], v[180:183], v[124:127]
	v_mfma_f32_16x16x32_bf16 v[120:123], v[140:143], v[180:183], v[120:123]
	v_mfma_f32_16x16x32_bf16 v[108:111], v[132:135], v[200:203], v[108:111]
	v_mfma_f32_16x16x32_bf16 v[104:107], v[140:143], v[200:203], v[104:107]
	v_mfma_f32_16x16x32_bf16 v[92:95], v[132:135], v[208:211], v[92:95]
	v_mfma_f32_16x16x32_bf16 v[88:91], v[140:143], v[208:211], v[88:91]
	v_mfma_f32_16x16x32_bf16 v[76:79], v[132:135], v[216:219], v[76:79]
	v_mfma_f32_16x16x32_bf16 v[72:75], v[140:143], v[216:219], v[72:75]
	s_setprio 0
	s_setprio 1
	v_mfma_f32_16x16x32_bf16 v[116:119], v[144:147], v[176:179], v[116:119]
	v_mfma_f32_16x16x32_bf16 v[112:115], v[168:171], v[176:179], v[112:115]
	v_mfma_f32_16x16x32_bf16 v[100:103], v[144:147], v[196:199], v[100:103]
	v_mfma_f32_16x16x32_bf16 v[96:99], v[168:171], v[196:199], v[96:99]
	v_mfma_f32_16x16x32_bf16 v[84:87], v[144:147], v[204:207], v[84:87]
	v_mfma_f32_16x16x32_bf16 v[80:83], v[168:171], v[204:207], v[80:83]
	v_mfma_f32_16x16x32_bf16 v[68:71], v[144:147], v[212:215], v[68:71]
	v_mfma_f32_16x16x32_bf16 v[64:67], v[168:171], v[212:215], v[64:67]
	v_mfma_f32_16x16x32_bf16 v[116:119], v[148:151], v[180:183], v[116:119]
	v_mfma_f32_16x16x32_bf16 v[112:115], v[172:175], v[180:183], v[112:115]
	v_mfma_f32_16x16x32_bf16 v[100:103], v[148:151], v[200:203], v[100:103]
	v_mfma_f32_16x16x32_bf16 v[96:99], v[172:175], v[200:203], v[96:99]
	v_mfma_f32_16x16x32_bf16 v[84:87], v[148:151], v[208:211], v[84:87]
	v_mfma_f32_16x16x32_bf16 v[80:83], v[172:175], v[208:211], v[80:83]
	v_mfma_f32_16x16x32_bf16 v[68:71], v[148:151], v[216:219], v[68:71]
	v_mfma_f32_16x16x32_bf16 v[64:67], v[172:175], v[216:219], v[64:67]
	s_barrier
; #define PG8_STAGE(bufoff, gbase, voff) do { _Pragma("unroll") for (int _i = 0; _i < 2; ++_i) \
;         __builtin_amdgcn_global_load_lds((const unsigned*)((const char*)(gbase) + (voff)[_i]), (PG8_LAS unsigned*)(lds + (bufoff) + ldsw + _i * 8192), 16, 0, 0); } while (0)
; #define PG8_LDA(dst, b, h) do { _Pragma("unroll") for (int m = 0; m < 4; ++m) _Pragma("unroll") for (int k = 0; k < 2; ++k) dst[m][k] = *(const PG8_LAS bf16x8*)(lds + PG8_SA(b, h) + aoff + m * 2048 + k * 1024); } while (0)
; #define PG8_MMA(ai, bj, At, Bt) do { __builtin_amdgcn_s_setprio(1); _Pragma("unroll") for (int m = 0; m < 4; ++m) _Pragma("unroll") for (int n = 0; n < 2; ++n) _Pragma("unroll") for (int k = 0; k < 2; ++k) \
;         acc[ai][bj][m][n] = __builtin_amdgcn_mfma_f32_16x16x32_bf16(Bt[n][k], At[m][k], acc[ai][bj][m][n], 0, 0, 0); __builtin_amdgcn_s_setprio(0); } while (0)
; #define PG8_WAIT_V(n) asm volatile("s_waitcnt vmcnt(" #n ")" ::: "memory")
; #define PG8_WAIT_L(n) asm volatile("s_waitcnt lgkmcnt(" #n ")" ::: "memory")
; #define PG8_BAR __builtin_amdgcn_s_barrier()
; #define PG8_SCHED __builtin_amdgcn_sched_barrier(0)
; template <class Epi, class Sched, bool ALIGN_EPI = false, bool SP2 = false>
; __device__ __forceinline__ void gemm_phase(PG8_LAS unsigned char* lds, const Gemm g, const Sched& S, const Epi& E) {
;     ...
;         for (int t = 0; t < nt; t += 2) {
;             const bool last = (t == nt - 2);
;             const char* a1 = cA + (size_t)(t + 1) * kstep;
;             const char* a2 = last ? nA : cA + (size_t)(t + 2) * kstep; const char* b2 = last ? nB : cB + (size_t)(t + 2) * kstep;
;     ...
;             PG8_LDA(At, 1, 1); PG8_STAGE(PG8_SB(1, 0), b3, voffB); PG8_STAGE(PG8_SB(1, 1), b3 + hstepB, voffB); PG8_STAGE(PG8_SA(1, 0), a3, voffA);
;             PG8_WAIT_V(8); PG8_WAIT_L(0); PG8_BAR; PG8_MMA(1, 0, At, B0); PG8_MMA(1, 1, At, B1); PG8_BAR; PG8_SCHED;
;     ...
;         if constexpr (ALIGN_EPI) { if (wr == 0) PG8_BAR; }
	s_setprio 0
	s_add_i32 s36, s58, s39
	v_lshl_add_u64 v[184:185], v[184:185], 0, s[14:15]
	s_mov_b32 m0, s36
	ds_read_b128 v[176:179], v193 offset:49152
	ds_read_b128 v[180:183], v193 offset:50176
	ds_read_b128 v[196:199], v193 offset:51200
	ds_read_b128 v[200:203], v193 offset:52224
	ds_read_b128 v[204:207], v193 offset:53248
	ds_read_b128 v[208:211], v193 offset:54272
	ds_read_b128 v[212:215], v193 offset:55296
	ds_read_b128 v[216:219], v193 offset:56320
	global_load_lds_dwordx4 v[184:185], off
	s_add_i32 m0, s36, 0x2000
	s_add_u32 s34, s34, 0x40080
	v_lshl_add_u64 v[184:185], v[220:221], 0, s[14:15]
	s_addc_u32 s35, s35, 0
	s_add_i32 s36, s59, s39
	global_load_lds_dwordx4 v[184:185], off
	v_lshl_add_u64 v[184:185], s[34:35], 0, v[154:155]
	s_mov_b32 m0, s36
	s_nop 0
	global_load_lds_dwordx4 v[184:185], off
	v_lshl_add_u64 v[184:185], s[34:35], 0, v[158:159]
	s_add_i32 m0, s36, 0x2000
	s_nop 0
	global_load_lds_dwordx4 v[184:185], off
	v_lshl_add_u64 v[184:185], v[222:223], 0, s[14:15]
	s_mov_b32 m0, s44
	s_nop 0
	global_load_lds_dwordx4 v[184:185], off
	v_lshl_add_u64 v[184:185], v[224:225], 0, s[14:15]
	s_mov_b32 m0, s45
	s_nop 0
	global_load_lds_dwordx4 v[184:185], off
	s_waitcnt vmcnt(8) lgkmcnt(0)
	s_barrier
	s_setprio 1
	v_mfma_f32_16x16x32_bf16 v[60:63], v[128:131], v[176:179], v[60:63]
	v_mfma_f32_16x16x32_bf16 v[56:59], v[136:139], v[176:179], v[56:59]
	v_mfma_f32_16x16x32_bf16 v[44:47], v[128:131], v[196:199], v[44:47]
	v_mfma_f32_16x16x32_bf16 v[40:43], v[136:139], v[196:199], v[40:43]
	v_mfma_f32_16x16x32_bf16 v[28:31], v[128:131], v[204:207], v[28:31]
	v_mfma_f32_16x16x32_bf16 v[24:27], v[136:139], v[204:207], v[24:27]
	v_mfma_f32_16x16x32_bf16 v[12:15], v[128:131], v[212:215], v[12:15]
	v_mfma_f32_16x16x32_bf16 v[8:11], v[136:139], v[212:215], v[8:11]
	v_mfma_f32_16x16x32_bf16 v[60:63], v[132:135], v[180:183], v[60:63]
	v_mfma_f32_16x16x32_bf16 v[56:59], v[140:143], v[180:183], v[56:59]
	v_mfma_f32_16x16x32_bf16 v[44:47], v[132:135], v[200:203], v[44:47]
	v_mfma_f32_16x16x32_bf16 v[40:43], v[140:143], v[200:203], v[40:43]
	v_mfma_f32_16x16x32_bf16 v[28:31], v[132:135], v[208:211], v[28:31]
	v_mfma_f32_16x16x32_bf16 v[24:27], v[140:143], v[208:211], v[24:27]
	v_mfma_f32_16x16x32_bf16 v[12:15], v[132:135], v[216:219], v[12:15]
	v_mfma_f32_16x16x32_bf16 v[8:11], v[140:143], v[216:219], v[8:11]
	s_setprio 0
	s_setprio 1
	v_mfma_f32_16x16x32_bf16 v[52:55], v[144:147], v[176:179], v[52:55]
	v_mfma_f32_16x16x32_bf16 v[48:51], v[168:171], v[176:179], v[48:51]
	v_mfma_f32_16x16x32_bf16 v[36:39], v[144:147], v[196:199], v[36:39]
	v_mfma_f32_16x16x32_bf16 v[32:35], v[168:171], v[196:199], v[32:35]
	v_mfma_f32_16x16x32_bf16 v[20:23], v[144:147], v[204:207], v[20:23]
	v_mfma_f32_16x16x32_bf16 v[16:19], v[168:171], v[204:207], v[16:19]
	v_mfma_f32_16x16x32_bf16 v[4:7], v[144:147], v[212:215], v[4:7]
	v_mfma_f32_16x16x32_bf16 v[0:3], v[168:171], v[212:215], v[0:3]
	v_mfma_f32_16x16x32_bf16 v[52:55], v[148:151], v[180:183], v[52:55]
	v_mfma_f32_16x16x32_bf16 v[48:51], v[172:175], v[180:183], v[48:51]
	v_mfma_f32_16x16x32_bf16 v[36:39], v[148:151], v[200:203], v[36:39]
	v_mfma_f32_16x16x32_bf16 v[32:35], v[172:175], v[200:203], v[32:35]
	v_mfma_f32_16x16x32_bf16 v[20:23], v[148:151], v[208:211], v[20:23]
	v_mfma_f32_16x16x32_bf16 v[16:19], v[172:175], v[208:211], v[16:19]
	v_mfma_f32_16x16x32_bf16 v[4:7], v[148:151], v[216:219], v[4:7]
	v_mfma_f32_16x16x32_bf16 v[0:3], v[172:175], v[216:219], v[0:3]
	s_barrier
	s_setprio 0
	s_add_i32 s74, s74, 2
	s_add_u32 s30, s30, 0x100
	s_addc_u32 s31, s31, 0
	s_add_u32 s69, s69, 0x100
	s_addc_u32 s73, s73, 0
	s_cmp_gt_u32 s74, 13
	s_cbranch_scc0 .LBB0_971
	s_and_b64 vcc, exec, s[16:17]
	s_cbranch_vccz .LBB0_974
	s_barrier

; #define PG8_STAGE(bufoff, gbase, voff) do { _Pragma("unroll") for (int _i = 0; _i < 2; ++_i) \
;         __builtin_amdgcn_global_load_lds((const unsigned*)((const char*)(gbase) + (voff)[_i]), (PG8_LAS unsigned*)(lds + (bufoff) + ldsw + _i * 8192), 16, 0, 0); } while (0)
; #define PG8_LDA(dst, b, h) do { _Pragma("unroll") for (int m = 0; m < 4; ++m) _Pragma("unroll") for (int k = 0; k < 2; ++k) dst[m][k] = *(const PG8_LAS bf16x8*)(lds + PG8_SA(b, h) + aoff + m * 2048 + k * 1024); } while (0)
; #define PG8_LDB(dst, b, h) do { _Pragma("unroll") for (int n = 0; n < 2; ++n) _Pragma("unroll") for (int k = 0; k < 2; ++k) dst[n][k] = *(const PG8_LAS bf16x8*)(lds + PG8_SB(b, h) + boff + n * 2048 + k * 1024); } while (0)
; #define PG8_MMA(ai, bj, At, Bt) do { __builtin_amdgcn_s_setprio(1); _Pragma("unroll") for (int m = 0; m < 4; ++m) _Pragma("unroll") for (int n = 0; n < 2; ++n) _Pragma("unroll") for (int k = 0; k < 2; ++k) \
;         acc[ai][bj][m][n] = __builtin_amdgcn_mfma_f32_16x16x32_bf16(Bt[n][k], At[m][k], acc[ai][bj][m][n], 0, 0, 0); __builtin_amdgcn_s_setprio(0); } while (0)
; #define PG8_WAIT_V(n) asm volatile("s_waitcnt vmcnt(" #n ")" ::: "memory")
; #define PG8_BAR __builtin_amdgcn_s_barrier()
; template <class Epi, class Sched, bool ALIGN_EPI = false, bool SP2 = false>
; __device__ __forceinline__ void gemm_phase(PG8_LAS unsigned char* lds, const Gemm g, const Sched& S, const Epi& E) {
;     ...
;         for (int t = 0; t < nt; t += 2) {
;             const bool last = (t == nt - 2);
;             const char* a1 = cA + (size_t)(t + 1) * kstep;
;             const char* a2 = last ? nA : cA + (size_t)(t + 2) * kstep; const char* b2 = last ? nB : cB + (size_t)(t + 2) * kstep;
;             const char* a3 = a2 + kstep; const char* b3 = b2 + kstep;
;             if (last && has_next) S.a_ready(nxt);
;             if constexpr (SP2) {
;             PG8_LDB(B0, 0, 0); PG8_LDB(B1, 0, 1); PG8_SCHED; PG8_LDA(At, 0, 0); PG8_STAGE(PG8_SA(1, 1), a1 + hstepA, voffA);
;             PG8_WAIT_V(8); PG8_WAIT_L(0); PG8_BAR; PG8_MMA(0, 0, At, B0); PG8_MMA(0, 1, At, B1); PG8_BAR; PG8_SCHED;
;             PG8_LDA(At, 0, 1); PG8_STAGE(PG8_SB(0, 0), b2, voffB); PG8_STAGE(PG8_SB(0, 1), b2 + hstepB, voffB); PG8_STAGE(PG8_SA(0, 0), a2, voffA);
;             PG8_WAIT_V(8); PG8_WAIT_L(0); PG8_BAR; PG8_MMA(1, 0, At, B0); PG8_MMA(1, 1, At, B1); PG8_BAR; PG8_SCHED;
.LBB0_1055:
	s_nop 0
	ds_read_b128 v[144:147], v153
	ds_read_b128 v[158:161], v153 offset:1024
	ds_read_b128 v[162:165], v153 offset:2048
	ds_read_b128 v[166:169], v153 offset:3072
	ds_read_b128 v[170:173], v154
	ds_read_b128 v[174:177], v154 offset:1024
	ds_read_b128 v[178:181], v154 offset:2048
	ds_read_b128 v[182:185], v154 offset:3072
	s_add_u32 s28, s26, 0xfffc0080
	s_addc_u32 s29, s27, -1
	s_cmp_eq_u32 s69, 12
	s_cselect_b32 s31, s19, s29
	s_cselect_b32 s30, s49, s28
	s_cselect_b32 s29, s17, s68
	s_cselect_b32 s28, s66, s67
	v_lshl_add_u64 v[148:149], s[26:27], 0, v[136:137]
	s_add_i32 m0, s25, 0xc000
	ds_read_b128 v[188:191], v155
	ds_read_b128 v[192:195], v155 offset:1024
	ds_read_b128 v[196:199], v155 offset:2048
	ds_read_b128 v[200:203], v155 offset:3072
	ds_read_b128 v[204:207], v155 offset:4096
	ds_read_b128 v[208:211], v155 offset:5120
	ds_read_b128 v[212:215], v155 offset:6144
	ds_read_b128 v[216:219], v155 offset:7168
	global_load_lds_dwordx4 v[148:149], off
	v_lshl_add_u64 v[148:149], s[26:27], 0, v[138:139]
	s_add_i32 m0, s25, 0xe000
	s_nop 0
	global_load_lds_dwordx4 v[148:149], off
	s_waitcnt vmcnt(8) lgkmcnt(0)
	s_barrier
	s_setprio 1
	v_mfma_f32_16x16x32_bf16 v[116:119], v[144:147], v[188:191], v[116:119]
	v_mfma_f32_16x16x32_bf16 v[112:115], v[162:165], v[188:191], v[112:115]
	v_mfma_f32_16x16x32_bf16 v[108:111], v[144:147], v[196:199], v[108:111]
	v_mfma_f32_16x16x32_bf16 v[100:103], v[162:165], v[196:199], v[100:103]
	v_mfma_f32_16x16x32_bf16 v[92:95], v[144:147], v[204:207], v[92:95]
	v_mfma_f32_16x16x32_bf16 v[84:87], v[162:165], v[204:207], v[84:87]
	v_mfma_f32_16x16x32_bf16 v[76:79], v[144:147], v[212:215], v[76:79]
	v_mfma_f32_16x16x32_bf16 v[68:71], v[162:165], v[212:215], v[68:71]
	v_mfma_f32_16x16x32_bf16 v[116:119], v[158:161], v[192:195], v[116:119]
	v_mfma_f32_16x16x32_bf16 v[112:115], v[166:169], v[192:195], v[112:115]
	v_mfma_f32_16x16x32_bf16 v[108:111], v[158:161], v[200:203], v[108:111]
	v_mfma_f32_16x16x32_bf16 v[100:103], v[166:169], v[200:203], v[100:103]
	v_mfma_f32_16x16x32_bf16 v[92:95], v[158:161], v[208:211], v[92:95]
	v_mfma_f32_16x16x32_bf16 v[84:87], v[166:169], v[208:211], v[84:87]
	v_mfma_f32_16x16x32_bf16 v[76:79], v[158:161], v[216:219], v[76:79]
	v_mfma_f32_16x16x32_bf16 v[68:71], v[166:169], v[216:219], v[68:71]
	s_setprio 0
	s_setprio 1
	v_mfma_f32_16x16x32_bf16 v[124:127], v[170:173], v[188:191], v[124:127]
	v_mfma_f32_16x16x32_bf16 v[120:123], v[178:181], v[188:191], v[120:123]
	v_mfma_f32_16x16x32_bf16 v[104:107], v[170:173], v[196:199], v[104:107]
	v_mfma_f32_16x16x32_bf16 v[96:99], v[178:181], v[196:199], v[96:99]
	v_mfma_f32_16x16x32_bf16 v[88:91], v[170:173], v[204:207], v[88:91]
	v_mfma_f32_16x16x32_bf16 v[80:83], v[178:181], v[204:207], v[80:83]
	v_mfma_f32_16x16x32_bf16 v[72:75], v[170:173], v[212:215], v[72:75]
	v_mfma_f32_16x16x32_bf16 v[64:67], v[178:181], v[212:215], v[64:67]
	v_mfma_f32_16x16x32_bf16 v[124:127], v[174:177], v[192:195], v[124:127]
	v_mfma_f32_16x16x32_bf16 v[120:123], v[182:185], v[192:195], v[120:123]
	v_mfma_f32_16x16x32_bf16 v[104:107], v[174:177], v[200:203], v[104:107]
	v_mfma_f32_16x16x32_bf16 v[96:99], v[182:185], v[200:203], v[96:99]
	v_mfma_f32_16x16x32_bf16 v[88:91], v[174:177], v[208:211], v[88:91]
	v_mfma_f32_16x16x32_bf16 v[80:83], v[182:185], v[208:211], v[80:83]
	v_mfma_f32_16x16x32_bf16 v[72:75], v[174:177], v[216:219], v[72:75]
	v_mfma_f32_16x16x32_bf16 v[64:67], v[182:185], v[216:219], v[64:67]
	s_barrier
	s_setprio 0
	s_nop 0
	s_add_i32 s58, s45, s35
	v_lshl_add_u64 v[148:149], s[28:29], 0, v[132:133]
	s_mov_b32 m0, s58
	ds_read_b128 v[188:191], v155 offset:16384
	ds_read_b128 v[192:195], v155 offset:17408
	ds_read_b128 v[196:199], v155 offset:18432
	ds_read_b128 v[200:203], v155 offset:19456
	ds_read_b128 v[204:207], v155 offset:20480
	ds_read_b128 v[208:211], v155 offset:21504
	ds_read_b128 v[212:215], v155 offset:22528
	ds_read_b128 v[216:219], v155 offset:23552
	global_load_lds_dwordx4 v[148:149], off
	s_add_i32 m0, s58, 0x2000
	s_add_u32 s58, s28, 0x40000
	v_lshl_add_u64 v[220:221], s[28:29], 0, v[128:129]
	s_addc_u32 s59, s29, 0
	s_add_i32 s73, s46, s35
	global_load_lds_dwordx4 v[220:221], off
	v_lshl_add_u64 v[222:223], s[58:59], 0, v[132:133]
	s_mov_b32 m0, s73
	v_lshl_add_u64 v[224:225], s[30:31], 0, v[130:131]
	global_load_lds_dwordx4 v[222:223], off
	v_lshl_add_u64 v[222:223], s[58:59], 0, v[128:129]
	s_add_i32 m0, s73, 0x2000
	s_nop 0
	global_load_lds_dwordx4 v[222:223], off
	v_lshl_add_u64 v[222:223], s[30:31], 0, v[134:135]
	s_mov_b32 m0, s25
	s_nop 0
	global_load_lds_dwordx4 v[222:223], off
	s_mov_b32 m0, s38
	s_nop 0
	global_load_lds_dwordx4 v[224:225], off
	s_waitcnt vmcnt(8) lgkmcnt(0)
	s_barrier
; #define PG8_STAGE(bufoff, gbase, voff) do { _Pragma("unroll") for (int _i = 0; _i < 2; ++_i) \
;         __builtin_amdgcn_global_load_lds((const unsigned*)((const char*)(gbase) + (voff)[_i]), (PG8_LAS unsigned*)(lds + (bufoff) + ldsw + _i * 8192), 16, 0, 0); } while (0)
; #define PG8_LDA(dst, b, h) do { _Pragma("unroll") for (int m = 0; m < 4; ++m) _Pragma("unroll") for (int k = 0; k < 2; ++k) dst[m][k] = *(const PG8_LAS bf16x8*)(lds + PG8_SA(b, h) + aoff + m * 2048 + k * 1024); } while (0)
; #define PG8_LDB(dst, b, h) do { _Pragma("unroll") for (int n = 0; n < 2; ++n) _Pragma("unroll") for (int k = 0; k < 2; ++k) dst[n][k] = *(const PG8_LAS bf16x8*)(lds + PG8_SB(b, h) + boff + n * 2048 + k * 1024); } while (0)
; #define PG8_MMA(ai, bj, At, Bt) do { __builtin_amdgcn_s_setprio(1); _Pragma("unroll") for (int m = 0; m < 4; ++m) _Pragma("unroll") for (int n = 0; n < 2; ++n) _Pragma("unroll") for (int k = 0; k < 2; ++k) \
;         acc[ai][bj][m][n] = __builtin_amdgcn_mfma_f32_16x16x32_bf16(Bt[n][k], At[m][k], acc[ai][bj][m][n], 0, 0, 0); __builtin_amdgcn_s_setprio(0); } while (0)
; #define PG8_WAIT_V(n) asm volatile("s_waitcnt vmcnt(" #n ")" ::: "memory")
; #define PG8_WAIT_L(n) asm volatile("s_waitcnt lgkmcnt(" #n ")" ::: "memory")
; #define PG8_BAR __builtin_amdgcn_s_barrier()
; #define PG8_SCHED __builtin_amdgcn_sched_barrier(0)
; template <class Epi, class Sched, bool ALIGN_EPI = false, bool SP2 = false>
; __device__ __forceinline__ void gemm_phase(PG8_LAS unsigned char* lds, const Gemm g, const Sched& S, const Epi& E) {
;     ...
;             PG8_WAIT_V(8); PG8_WAIT_L(0); PG8_BAR; PG8_MMA(1, 0, At, B0); PG8_MMA(1, 1, At, B1); PG8_BAR; PG8_SCHED;
;             PG8_LDB(B0, 1, 0); PG8_LDB(B1, 1, 1); PG8_SCHED; PG8_LDA(At, 1, 0); PG8_STAGE(PG8_SA(0, 1), a2 + hstepA, voffA);
;             PG8_WAIT_V(8); PG8_WAIT_L(0); PG8_BAR; PG8_MMA(0, 0, At, B0); PG8_MMA(0, 1, At, B1); PG8_BAR; PG8_SCHED;
;             PG8_LDA(At, 1, 1); PG8_STAGE(PG8_SB(1, 0), b3, voffB); PG8_STAGE(PG8_SB(1, 1), b3 + hstepB, voffB); PG8_STAGE(PG8_SA(1, 0), a3, voffA);
;             PG8_WAIT_V(8); PG8_WAIT_L(0); PG8_BAR; PG8_MMA(1, 0, At, B0); PG8_MMA(1, 1, At, B1); PG8_BAR; PG8_SCHED;
	s_setprio 1
	v_mfma_f32_16x16x32_bf16 v[60:63], v[144:147], v[188:191], v[60:63]
	v_mfma_f32_16x16x32_bf16 v[52:55], v[162:165], v[188:191], v[52:55]
	v_mfma_f32_16x16x32_bf16 v[44:47], v[144:147], v[196:199], v[44:47]
	v_mfma_f32_16x16x32_bf16 v[36:39], v[162:165], v[196:199], v[36:39]
	v_mfma_f32_16x16x32_bf16 v[28:31], v[144:147], v[204:207], v[28:31]
	v_mfma_f32_16x16x32_bf16 v[20:23], v[162:165], v[204:207], v[20:23]
	v_mfma_f32_16x16x32_bf16 v[12:15], v[144:147], v[212:215], v[12:15]
	v_mfma_f32_16x16x32_bf16 v[4:7], v[162:165], v[212:215], v[4:7]
	v_mfma_f32_16x16x32_bf16 v[60:63], v[158:161], v[192:195], v[60:63]
	v_mfma_f32_16x16x32_bf16 v[52:55], v[166:169], v[192:195], v[52:55]
	v_mfma_f32_16x16x32_bf16 v[44:47], v[158:161], v[200:203], v[44:47]
	v_mfma_f32_16x16x32_bf16 v[36:39], v[166:169], v[200:203], v[36:39]
	v_mfma_f32_16x16x32_bf16 v[28:31], v[158:161], v[208:211], v[28:31]
	v_mfma_f32_16x16x32_bf16 v[20:23], v[166:169], v[208:211], v[20:23]
	v_mfma_f32_16x16x32_bf16 v[12:15], v[158:161], v[216:219], v[12:15]
	v_mfma_f32_16x16x32_bf16 v[4:7], v[166:169], v[216:219], v[4:7]
	s_setprio 0
	s_setprio 1
	v_mfma_f32_16x16x32_bf16 v[56:59], v[170:173], v[188:191], v[56:59]
	v_mfma_f32_16x16x32_bf16 v[48:51], v[178:181], v[188:191], v[48:51]
	v_mfma_f32_16x16x32_bf16 v[40:43], v[170:173], v[196:199], v[40:43]
	v_mfma_f32_16x16x32_bf16 v[32:35], v[178:181], v[196:199], v[32:35]
	v_mfma_f32_16x16x32_bf16 v[24:27], v[170:173], v[204:207], v[24:27]
	v_mfma_f32_16x16x32_bf16 v[16:19], v[178:181], v[204:207], v[16:19]
	v_mfma_f32_16x16x32_bf16 v[8:11], v[170:173], v[212:215], v[8:11]
	v_mfma_f32_16x16x32_bf16 v[0:3], v[178:181], v[212:215], v[0:3]
	v_mfma_f32_16x16x32_bf16 v[56:59], v[174:177], v[192:195], v[56:59]
	v_mfma_f32_16x16x32_bf16 v[48:51], v[182:185], v[192:195], v[48:51]
	v_mfma_f32_16x16x32_bf16 v[40:43], v[174:177], v[200:203], v[40:43]
	v_mfma_f32_16x16x32_bf16 v[32:35], v[182:185], v[200:203], v[32:35]
	v_mfma_f32_16x16x32_bf16 v[24:27], v[174:177], v[208:211], v[24:27]
	v_mfma_f32_16x16x32_bf16 v[16:19], v[182:185], v[208:211], v[16:19]
	v_mfma_f32_16x16x32_bf16 v[8:11], v[174:177], v[216:219], v[8:11]
	v_mfma_f32_16x16x32_bf16 v[0:3], v[182:185], v[216:219], v[0:3]
	s_barrier
	s_setprio 0
	s_nop 0
	s_add_i32 s58, 0, 0x18000
	v_add_u32_e32 v157, s58, v151
	s_add_i32 s59, 0, 0x1c000
	ds_read_b128 v[144:147], v157
	ds_read_b128 v[158:161], v157 offset:1024
	ds_read_b128 v[162:165], v157 offset:2048
	ds_read_b128 v[166:169], v157 offset:3072
	v_add_u32_e32 v157, s59, v151
	ds_read_b128 v[170:173], v157
	ds_read_b128 v[174:177], v157 offset:1024
	ds_read_b128 v[178:181], v157 offset:2048
	ds_read_b128 v[182:185], v157 offset:3072
	s_add_u32 s30, s30, 0x40000
	s_addc_u32 s31, s31, 0
	s_mov_b32 m0, s39
	v_lshl_add_u64 v[226:227], s[30:31], 0, v[134:135]
	ds_read_b128 v[188:191], v155 offset:32768
	ds_read_b128 v[192:195], v155 offset:33792
	ds_read_b128 v[196:199], v155 offset:34816
	ds_read_b128 v[200:203], v155 offset:35840
	ds_read_b128 v[204:207], v155 offset:36864
	ds_read_b128 v[208:211], v155 offset:37888
	ds_read_b128 v[212:215], v155 offset:38912
	ds_read_b128 v[216:219], v155 offset:39936
	global_load_lds_dwordx4 v[226:227], off
	v_lshl_add_u64 v[226:227], s[30:31], 0, v[130:131]
	s_mov_b32 m0, s40
	s_nop 0
	global_load_lds_dwordx4 v[226:227], off
	s_waitcnt vmcnt(8) lgkmcnt(0)
	s_barrier
	s_setprio 1
	v_mfma_f32_16x16x32_bf16 v[116:119], v[144:147], v[188:191], v[116:119]
	v_mfma_f32_16x16x32_bf16 v[112:115], v[162:165], v[188:191], v[112:115]
	v_mfma_f32_16x16x32_bf16 v[108:111], v[144:147], v[196:199], v[108:111]
	v_mfma_f32_16x16x32_bf16 v[100:103], v[162:165], v[196:199], v[100:103]
	v_mfma_f32_16x16x32_bf16 v[92:95], v[144:147], v[204:207], v[92:95]
	v_mfma_f32_16x16x32_bf16 v[84:87], v[162:165], v[204:207], v[84:87]
	v_mfma_f32_16x16x32_bf16 v[76:79], v[144:147], v[212:215], v[76:79]
	v_mfma_f32_16x16x32_bf16 v[68:71], v[162:165], v[212:215], v[68:71]
	v_mfma_f32_16x16x32_bf16 v[116:119], v[158:161], v[192:195], v[116:119]
	v_mfma_f32_16x16x32_bf16 v[112:115], v[166:169], v[192:195], v[112:115]
	v_mfma_f32_16x16x32_bf16 v[108:111], v[158:161], v[200:203], v[108:111]
	v_mfma_f32_16x16x32_bf16 v[100:103], v[166:169], v[200:203], v[100:103]
	v_mfma_f32_16x16x32_bf16 v[92:95], v[158:161], v[208:211], v[92:95]
	v_mfma_f32_16x16x32_bf16 v[84:87], v[166:169], v[208:211], v[84:87]
	v_mfma_f32_16x16x32_bf16 v[76:79], v[158:161], v[216:219], v[76:79]
	v_mfma_f32_16x16x32_bf16 v[68:71], v[166:169], v[216:219], v[68:71]
	s_setprio 0
	s_setprio 1
	v_mfma_f32_16x16x32_bf16 v[124:127], v[170:173], v[188:191], v[124:127]
	v_mfma_f32_16x16x32_bf16 v[120:123], v[178:181], v[188:191], v[120:123]
	v_mfma_f32_16x16x32_bf16 v[104:107], v[170:173], v[196:199], v[104:107]
	v_mfma_f32_16x16x32_bf16 v[96:99], v[178:181], v[196:199], v[96:99]
	v_mfma_f32_16x16x32_bf16 v[88:91], v[170:173], v[204:207], v[88:91]
	v_mfma_f32_16x16x32_bf16 v[80:83], v[178:181], v[204:207], v[80:83]
	v_mfma_f32_16x16x32_bf16 v[72:75], v[170:173], v[212:215], v[72:75]
	v_mfma_f32_16x16x32_bf16 v[64:67], v[178:181], v[212:215], v[64:67]
	v_mfma_f32_16x16x32_bf16 v[124:127], v[174:177], v[192:195], v[124:127]
	v_mfma_f32_16x16x32_bf16 v[120:123], v[182:185], v[192:195], v[120:123]
	v_mfma_f32_16x16x32_bf16 v[104:107], v[174:177], v[200:203], v[104:107]
	v_mfma_f32_16x16x32_bf16 v[96:99], v[182:185], v[200:203], v[96:99]
	v_mfma_f32_16x16x32_bf16 v[88:91], v[174:177], v[208:211], v[88:91]
	v_mfma_f32_16x16x32_bf16 v[80:83], v[182:185], v[208:211], v[80:83]
	v_mfma_f32_16x16x32_bf16 v[72:75], v[174:177], v[216:219], v[72:75]
	v_mfma_f32_16x16x32_bf16 v[64:67], v[182:185], v[216:219], v[64:67]
	s_barrier
; #define PG8_STAGE(bufoff, gbase, voff) do { _Pragma("unroll") for (int _i = 0; _i < 2; ++_i) \
;         __builtin_amdgcn_global_load_lds((const unsigned*)((const char*)(gbase) + (voff)[_i]), (PG8_LAS unsigned*)(lds + (bufoff) + ldsw + _i * 8192), 16, 0, 0); } while (0)
; #define PG8_LDA(dst, b, h) do { _Pragma("unroll") for (int m = 0; m < 4; ++m) _Pragma("unroll") for (int k = 0; k < 2; ++k) dst[m][k] = *(const PG8_LAS bf16x8*)(lds + PG8_SA(b, h) + aoff + m * 2048 + k * 1024); } while (0)
; #define PG8_MMA(ai, bj, At, Bt) do { __builtin_amdgcn_s_setprio(1); _Pragma("unroll") for (int m = 0; m < 4; ++m) _Pragma("unroll") for (int n = 0; n < 2; ++n) _Pragma("unroll") for (int k = 0; k < 2; ++k) \
;         acc[ai][bj][m][n] = __builtin_amdgcn_mfma_f32_16x16x32_bf16(Bt[n][k], At[m][k], acc[ai][bj][m][n], 0, 0, 0); __builtin_amdgcn_s_setprio(0); } while (0)
; #define PG8_WAIT_V(n) asm volatile("s_waitcnt vmcnt(" #n ")" ::: "memory")
; #define PG8_WAIT_L(n) asm volatile("s_waitcnt lgkmcnt(" #n ")" ::: "memory")
; #define PG8_BAR __builtin_amdgcn_s_barrier()
; #define PG8_SCHED __builtin_amdgcn_sched_barrier(0)
; template <class Epi, class Sched, bool ALIGN_EPI = false, bool SP2 = false>
; __device__ __forceinline__ void gemm_phase(PG8_LAS unsigned char* lds, const Gemm g, const Sched& S, const Epi& E) {
;     ...
;         for (int t = 0; t < nt; t += 2) {
;             const bool last = (t == nt - 2);
;             const char* a1 = cA + (size_t)(t + 1) * kstep;
;             const char* a2 = last ? nA : cA + (size_t)(t + 2) * kstep; const char* b2 = last ? nB : cB + (size_t)(t + 2) * kstep;
;     ...
;             PG8_LDA(At, 1, 1); PG8_STAGE(PG8_SB(1, 0), b3, voffB); PG8_STAGE(PG8_SB(1, 1), b3 + hstepB, voffB); PG8_STAGE(PG8_SA(1, 0), a3, voffA);
;             PG8_WAIT_V(8); PG8_WAIT_L(0); PG8_BAR; PG8_MMA(1, 0, At, B0); PG8_MMA(1, 1, At, B1); PG8_BAR; PG8_SCHED;
;     ...
;         if constexpr (ALIGN_EPI) { if (wr == 0) PG8_BAR; }
	s_setprio 0
	s_add_i32 s30, s58, s35
	v_lshl_add_u64 v[148:149], v[148:149], 0, s[12:13]
	s_mov_b32 m0, s30
	ds_read_b128 v[188:191], v155 offset:49152
	ds_read_b128 v[192:195], v155 offset:50176
	ds_read_b128 v[196:199], v155 offset:51200
	ds_read_b128 v[200:203], v155 offset:52224
	ds_read_b128 v[204:207], v155 offset:53248
	ds_read_b128 v[208:211], v155 offset:54272
	ds_read_b128 v[212:215], v155 offset:55296
	ds_read_b128 v[216:219], v155 offset:56320
	global_load_lds_dwordx4 v[148:149], off
	s_add_i32 m0, s30, 0x2000
	s_add_u32 s28, s28, 0x40080
	v_lshl_add_u64 v[148:149], v[220:221], 0, s[12:13]
	s_addc_u32 s29, s29, 0
	s_add_i32 s30, s59, s35
	global_load_lds_dwordx4 v[148:149], off
	v_lshl_add_u64 v[148:149], s[28:29], 0, v[132:133]
	s_mov_b32 m0, s30
	s_nop 0
	global_load_lds_dwordx4 v[148:149], off
	v_lshl_add_u64 v[148:149], s[28:29], 0, v[128:129]
	s_add_i32 m0, s30, 0x2000
	s_nop 0
	global_load_lds_dwordx4 v[148:149], off
	v_lshl_add_u64 v[148:149], v[222:223], 0, s[12:13]
	s_mov_b32 m0, s42
	s_nop 0
	global_load_lds_dwordx4 v[148:149], off
	v_lshl_add_u64 v[148:149], v[224:225], 0, s[12:13]
	s_mov_b32 m0, s43
	s_nop 0
	global_load_lds_dwordx4 v[148:149], off
	s_waitcnt vmcnt(8) lgkmcnt(0)
	s_barrier
	s_setprio 1
	v_mfma_f32_16x16x32_bf16 v[60:63], v[144:147], v[188:191], v[60:63]
	v_mfma_f32_16x16x32_bf16 v[52:55], v[162:165], v[188:191], v[52:55]
	v_mfma_f32_16x16x32_bf16 v[44:47], v[144:147], v[196:199], v[44:47]
	v_mfma_f32_16x16x32_bf16 v[36:39], v[162:165], v[196:199], v[36:39]
	v_mfma_f32_16x16x32_bf16 v[28:31], v[144:147], v[204:207], v[28:31]
	v_mfma_f32_16x16x32_bf16 v[20:23], v[162:165], v[204:207], v[20:23]
	v_mfma_f32_16x16x32_bf16 v[12:15], v[144:147], v[212:215], v[12:15]
	v_mfma_f32_16x16x32_bf16 v[4:7], v[162:165], v[212:215], v[4:7]
	v_mfma_f32_16x16x32_bf16 v[60:63], v[158:161], v[192:195], v[60:63]
	v_mfma_f32_16x16x32_bf16 v[52:55], v[166:169], v[192:195], v[52:55]
	v_mfma_f32_16x16x32_bf16 v[44:47], v[158:161], v[200:203], v[44:47]
	v_mfma_f32_16x16x32_bf16 v[36:39], v[166:169], v[200:203], v[36:39]
	v_mfma_f32_16x16x32_bf16 v[28:31], v[158:161], v[208:211], v[28:31]
	v_mfma_f32_16x16x32_bf16 v[20:23], v[166:169], v[208:211], v[20:23]
	v_mfma_f32_16x16x32_bf16 v[12:15], v[158:161], v[216:219], v[12:15]
	v_mfma_f32_16x16x32_bf16 v[4:7], v[166:169], v[216:219], v[4:7]
	s_setprio 0
	s_setprio 1
	v_mfma_f32_16x16x32_bf16 v[56:59], v[170:173], v[188:191], v[56:59]
	v_mfma_f32_16x16x32_bf16 v[48:51], v[178:181], v[188:191], v[48:51]
	v_mfma_f32_16x16x32_bf16 v[40:43], v[170:173], v[196:199], v[40:43]
	v_mfma_f32_16x16x32_bf16 v[32:35], v[178:181], v[196:199], v[32:35]
	v_mfma_f32_16x16x32_bf16 v[24:27], v[170:173], v[204:207], v[24:27]
	v_mfma_f32_16x16x32_bf16 v[16:19], v[178:181], v[204:207], v[16:19]
	v_mfma_f32_16x16x32_bf16 v[8:11], v[170:173], v[212:215], v[8:11]
	v_mfma_f32_16x16x32_bf16 v[0:3], v[178:181], v[212:215], v[0:3]
	v_mfma_f32_16x16x32_bf16 v[56:59], v[174:177], v[192:195], v[56:59]
	v_mfma_f32_16x16x32_bf16 v[48:51], v[182:185], v[192:195], v[48:51]
	v_mfma_f32_16x16x32_bf16 v[40:43], v[174:177], v[200:203], v[40:43]
	v_mfma_f32_16x16x32_bf16 v[32:35], v[182:185], v[200:203], v[32:35]
	v_mfma_f32_16x16x32_bf16 v[24:27], v[174:177], v[208:211], v[24:27]
	v_mfma_f32_16x16x32_bf16 v[16:19], v[182:185], v[208:211], v[16:19]
	v_mfma_f32_16x16x32_bf16 v[8:11], v[174:177], v[216:219], v[8:11]
	v_mfma_f32_16x16x32_bf16 v[0:3], v[182:185], v[216:219], v[0:3]
	s_barrier
	s_setprio 0
	s_add_i32 s69, s69, 2
	s_add_u32 s26, s26, 0x100
	s_addc_u32 s27, s27, 0
	s_add_u32 s67, s67, 0x100
	s_addc_u32 s68, s68, 0
	s_cmp_gt_u32 s69, 13
	s_cbranch_scc0 .LBB0_1055
	s_and_b64 vcc, exec, s[14:15]
	s_cbranch_vccz .LBB0_1058
	s_barrier

; #define PG8_STAGE(bufoff, gbase, voff) do { _Pragma("unroll") for (int _i = 0; _i < 2; ++_i) \
;         __builtin_amdgcn_global_load_lds((const unsigned*)((const char*)(gbase) + (voff)[_i]), (PG8_LAS unsigned*)(lds + (bufoff) + ldsw + _i * 8192), 16, 0, 0); } while (0)
; #define PG8_LDA(dst, b, h) do { _Pragma("unroll") for (int m = 0; m < 4; ++m) _Pragma("unroll") for (int k = 0; k < 2; ++k) dst[m][k] = *(const PG8_LAS bf16x8*)(lds + PG8_SA(b, h) + aoff + m * 2048 + k * 1024); } while (0)
; #define PG8_LDB(dst, b, h) do { _Pragma("unroll") for (int n = 0; n < 2; ++n) _Pragma("unroll") for (int k = 0; k < 2; ++k) dst[n][k] = *(const PG8_LAS bf16x8*)(lds + PG8_SB(b, h) + boff + n * 2048 + k * 1024); } while (0)
; #define PG8_MMA(ai, bj, At, Bt) do { __builtin_amdgcn_s_setprio(1); _Pragma("unroll") for (int m = 0; m < 4; ++m) _Pragma("unroll") for (int n = 0; n < 2; ++n) _Pragma("unroll") for (int k = 0; k < 2; ++k) \
;         acc[ai][bj][m][n] = __builtin_amdgcn_mfma_f32_16x16x32_bf16(Bt[n][k], At[m][k], acc[ai][bj][m][n], 0, 0, 0); __builtin_amdgcn_s_setprio(0); } while (0)
; #define PG8_WAIT_V(n) asm volatile("s_waitcnt vmcnt(" #n ")" ::: "memory")
; #define PG8_BAR __builtin_amdgcn_s_barrier()
; template <class Epi, class Sched, bool ALIGN_EPI = false, bool SP2 = false>
; __device__ __forceinline__ void gemm_phase(PG8_LAS unsigned char* lds, const Gemm g, const Sched& S, const Epi& E) {
;     ...
;         for (int t = 0; t < nt; t += 2) {
;             const bool last = (t == nt - 2);
;             const char* a1 = cA + (size_t)(t + 1) * kstep;
;             const char* a2 = last ? nA : cA + (size_t)(t + 2) * kstep; const char* b2 = last ? nB : cB + (size_t)(t + 2) * kstep;
;             const char* a3 = a2 + kstep; const char* b3 = b2 + kstep;
;             if (last && has_next) S.a_ready(nxt);
;             if constexpr (SP2) {
;             PG8_LDB(B0, 0, 0); PG8_LDB(B1, 0, 1); PG8_SCHED; PG8_LDA(At, 0, 0); PG8_STAGE(PG8_SA(1, 1), a1 + hstepA, voffA);
;             PG8_WAIT_V(8); PG8_WAIT_L(0); PG8_BAR; PG8_MMA(0, 0, At, B0); PG8_MMA(0, 1, At, B1); PG8_BAR; PG8_SCHED;
;             PG8_LDA(At, 0, 1); PG8_STAGE(PG8_SB(0, 0), b2, voffB); PG8_STAGE(PG8_SB(0, 1), b2 + hstepB, voffB); PG8_STAGE(PG8_SA(0, 0), a2, voffA);
;             PG8_WAIT_V(8); PG8_WAIT_L(0); PG8_BAR; PG8_MMA(1, 0, At, B0); PG8_MMA(1, 1, At, B1); PG8_BAR; PG8_SCHED;
.LBB0_1129:
	ds_read_b128 v[128:131], v191
	ds_read_b128 v[132:135], v191 offset:1024
	ds_read_b128 v[136:139], v191 offset:2048
	ds_read_b128 v[140:143], v191 offset:3072
	ds_read_b128 v[144:147], v192
	ds_read_b128 v[148:151], v192 offset:1024
	ds_read_b128 v[168:171], v192 offset:2048
	ds_read_b128 v[172:175], v192 offset:3072
	s_add_u32 s24, s22, 0x100
	s_addc_u32 s25, s23, 0
	s_cmp_eq_u32 s69, 40
	s_cselect_b32 s29, s11, s25
	s_cselect_b32 s28, s10, s24
	s_cselect_b32 s27, s21, s68
	s_cselect_b32 s26, s20, s67
	v_lshl_add_u64 v[184:185], s[22:23], 0, v[160:161]
	s_add_i32 m0, s34, 0xc000
	ds_read_b128 v[176:179], v193
	ds_read_b128 v[180:183], v193 offset:1024
	ds_read_b128 v[196:199], v193 offset:2048
	ds_read_b128 v[200:203], v193 offset:3072
	ds_read_b128 v[204:207], v193 offset:4096
	ds_read_b128 v[208:211], v193 offset:5120
	ds_read_b128 v[212:215], v193 offset:6144
	ds_read_b128 v[216:219], v193 offset:7168
	global_load_lds_dwordx4 v[184:185], off
	v_lshl_add_u64 v[184:185], s[22:23], 0, v[162:163]
	s_add_i32 m0, s34, 0xe000
	s_nop 0
	global_load_lds_dwordx4 v[184:185], off
	s_waitcnt vmcnt(8) lgkmcnt(0)
	s_barrier
	s_setprio 1
	v_mfma_f32_16x16x32_bf16 v[124:127], v[128:131], v[176:179], v[124:127]
	v_mfma_f32_16x16x32_bf16 v[120:123], v[136:139], v[176:179], v[120:123]
	v_mfma_f32_16x16x32_bf16 v[108:111], v[128:131], v[196:199], v[108:111]
	v_mfma_f32_16x16x32_bf16 v[104:107], v[136:139], v[196:199], v[104:107]
	v_mfma_f32_16x16x32_bf16 v[92:95], v[128:131], v[204:207], v[92:95]
	v_mfma_f32_16x16x32_bf16 v[88:91], v[136:139], v[204:207], v[88:91]
	v_mfma_f32_16x16x32_bf16 v[76:79], v[128:131], v[212:215], v[76:79]
	v_mfma_f32_16x16x32_bf16 v[72:75], v[136:139], v[212:215], v[72:75]
	v_mfma_f32_16x16x32_bf16 v[124:127], v[132:135], v[180:183], v[124:127]
	v_mfma_f32_16x16x32_bf16 v[120:123], v[140:143], v[180:183], v[120:123]
	v_mfma_f32_16x16x32_bf16 v[108:111], v[132:135], v[200:203], v[108:111]
	v_mfma_f32_16x16x32_bf16 v[104:107], v[140:143], v[200:203], v[104:107]
	v_mfma_f32_16x16x32_bf16 v[92:95], v[132:135], v[208:211], v[92:95]
	v_mfma_f32_16x16x32_bf16 v[88:91], v[140:143], v[208:211], v[88:91]
	v_mfma_f32_16x16x32_bf16 v[76:79], v[132:135], v[216:219], v[76:79]
	v_mfma_f32_16x16x32_bf16 v[72:75], v[140:143], v[216:219], v[72:75]
	s_setprio 0
	s_setprio 1
	v_mfma_f32_16x16x32_bf16 v[116:119], v[144:147], v[176:179], v[116:119]
	v_mfma_f32_16x16x32_bf16 v[112:115], v[168:171], v[176:179], v[112:115]
	v_mfma_f32_16x16x32_bf16 v[100:103], v[144:147], v[196:199], v[100:103]
	v_mfma_f32_16x16x32_bf16 v[96:99], v[168:171], v[196:199], v[96:99]
	v_mfma_f32_16x16x32_bf16 v[84:87], v[144:147], v[204:207], v[84:87]
	v_mfma_f32_16x16x32_bf16 v[80:83], v[168:171], v[204:207], v[80:83]
	v_mfma_f32_16x16x32_bf16 v[68:71], v[144:147], v[212:215], v[68:71]
	v_mfma_f32_16x16x32_bf16 v[64:67], v[168:171], v[212:215], v[64:67]
	v_mfma_f32_16x16x32_bf16 v[116:119], v[148:151], v[180:183], v[116:119]
	v_mfma_f32_16x16x32_bf16 v[112:115], v[172:175], v[180:183], v[112:115]
	v_mfma_f32_16x16x32_bf16 v[100:103], v[148:151], v[200:203], v[100:103]
	v_mfma_f32_16x16x32_bf16 v[96:99], v[172:175], v[200:203], v[96:99]
	v_mfma_f32_16x16x32_bf16 v[84:87], v[148:151], v[208:211], v[84:87]
	v_mfma_f32_16x16x32_bf16 v[80:83], v[172:175], v[208:211], v[80:83]
	v_mfma_f32_16x16x32_bf16 v[68:71], v[148:151], v[216:219], v[68:71]
	v_mfma_f32_16x16x32_bf16 v[64:67], v[172:175], v[216:219], v[64:67]
	s_barrier
	s_setprio 0
	s_nop 0
	s_add_i32 s22, s44, s31
	v_lshl_add_u64 v[184:185], s[26:27], 0, v[154:155]
	s_mov_b32 m0, s22
	ds_read_b128 v[176:179], v193 offset:16384
	ds_read_b128 v[180:183], v193 offset:17408
	ds_read_b128 v[196:199], v193 offset:18432
	ds_read_b128 v[200:203], v193 offset:19456
	ds_read_b128 v[204:207], v193 offset:20480
	ds_read_b128 v[208:211], v193 offset:21504
	ds_read_b128 v[212:215], v193 offset:22528
	ds_read_b128 v[216:219], v193 offset:23552
	global_load_lds_dwordx4 v[184:185], off
	s_add_i32 m0, s22, 0x2000
	s_add_u32 s22, s26, 0xb0000
	v_lshl_add_u64 v[220:221], s[26:27], 0, v[158:159]
	s_addc_u32 s23, s27, 0
	s_add_i32 s58, s45, s31
	global_load_lds_dwordx4 v[220:221], off
	v_lshl_add_u64 v[222:223], s[22:23], 0, v[154:155]
	s_mov_b32 m0, s58
	v_lshl_add_u64 v[224:225], s[28:29], 0, v[156:157]
	global_load_lds_dwordx4 v[222:223], off
	v_lshl_add_u64 v[222:223], s[22:23], 0, v[158:159]
	s_add_i32 m0, s58, 0x2000
	s_nop 0
	global_load_lds_dwordx4 v[222:223], off
	v_lshl_add_u64 v[222:223], s[28:29], 0, v[152:153]
	s_mov_b32 m0, s34
	s_nop 0
	global_load_lds_dwordx4 v[222:223], off
	s_mov_b32 m0, s35
	s_nop 0
	global_load_lds_dwordx4 v[224:225], off
	s_waitcnt vmcnt(8) lgkmcnt(0)
	s_barrier
; #define PG8_STAGE(bufoff, gbase, voff) do { _Pragma("unroll") for (int _i = 0; _i < 2; ++_i) \
;         __builtin_amdgcn_global_load_lds((const unsigned*)((const char*)(gbase) + (voff)[_i]), (PG8_LAS unsigned*)(lds + (bufoff) + ldsw + _i * 8192), 16, 0, 0); } while (0)
; #define PG8_LDA(dst, b, h) do { _Pragma("unroll") for (int m = 0; m < 4; ++m) _Pragma("unroll") for (int k = 0; k < 2; ++k) dst[m][k] = *(const PG8_LAS bf16x8*)(lds + PG8_SA(b, h) + aoff + m * 2048 + k * 1024); } while (0)
; #define PG8_LDB(dst, b, h) do { _Pragma("unroll") for (int n = 0; n < 2; ++n) _Pragma("unroll") for (int k = 0; k < 2; ++k) dst[n][k] = *(const PG8_LAS bf16x8*)(lds + PG8_SB(b, h) + boff + n * 2048 + k * 1024); } while (0)
; #define PG8_MMA(ai, bj, At, Bt) do { __builtin_amdgcn_s_setprio(1); _Pragma("unroll") for (int m = 0; m < 4; ++m) _Pragma("unroll") for (int n = 0; n < 2; ++n) _Pragma("unroll") for (int k = 0; k < 2; ++k) \
;         acc[ai][bj][m][n] = __builtin_amdgcn_mfma_f32_16x16x32_bf16(Bt[n][k], At[m][k], acc[ai][bj][m][n], 0, 0, 0); __builtin_amdgcn_s_setprio(0); } while (0)
; #define PG8_WAIT_V(n) asm volatile("s_waitcnt vmcnt(" #n ")" ::: "memory")
; #define PG8_WAIT_L(n) asm volatile("s_waitcnt lgkmcnt(" #n ")" ::: "memory")
; #define PG8_BAR __builtin_amdgcn_s_barrier()
; #define PG8_SCHED __builtin_amdgcn_sched_barrier(0)
; template <class Epi, class Sched, bool ALIGN_EPI = false, bool SP2 = false>
; __device__ __forceinline__ void gemm_phase(PG8_LAS unsigned char* lds, const Gemm g, const Sched& S, const Epi& E) {
;     ...
;             PG8_WAIT_V(8); PG8_WAIT_L(0); PG8_BAR; PG8_MMA(1, 0, At, B0); PG8_MMA(1, 1, At, B1); PG8_BAR; PG8_SCHED;
;             PG8_LDB(B0, 1, 0); PG8_LDB(B1, 1, 1); PG8_SCHED; PG8_LDA(At, 1, 0); PG8_STAGE(PG8_SA(0, 1), a2 + hstepA, voffA);
;             PG8_WAIT_V(8); PG8_WAIT_L(0); PG8_BAR; PG8_MMA(0, 0, At, B0); PG8_MMA(0, 1, At, B1); PG8_BAR; PG8_SCHED;
;             PG8_LDA(At, 1, 1); PG8_STAGE(PG8_SB(1, 0), b3, voffB); PG8_STAGE(PG8_SB(1, 1), b3 + hstepB, voffB); PG8_STAGE(PG8_SA(1, 0), a3, voffA);
;             PG8_WAIT_V(8); PG8_WAIT_L(0); PG8_BAR; PG8_MMA(1, 0, At, B0); PG8_MMA(1, 1, At, B1); PG8_BAR; PG8_SCHED;
	s_setprio 1
	v_mfma_f32_16x16x32_bf16 v[60:63], v[128:131], v[176:179], v[60:63]
	v_mfma_f32_16x16x32_bf16 v[56:59], v[136:139], v[176:179], v[56:59]
	v_mfma_f32_16x16x32_bf16 v[44:47], v[128:131], v[196:199], v[44:47]
	v_mfma_f32_16x16x32_bf16 v[40:43], v[136:139], v[196:199], v[40:43]
	v_mfma_f32_16x16x32_bf16 v[28:31], v[128:131], v[204:207], v[28:31]
	v_mfma_f32_16x16x32_bf16 v[24:27], v[136:139], v[204:207], v[24:27]
	v_mfma_f32_16x16x32_bf16 v[12:15], v[128:131], v[212:215], v[12:15]
	v_mfma_f32_16x16x32_bf16 v[8:11], v[136:139], v[212:215], v[8:11]
	v_mfma_f32_16x16x32_bf16 v[60:63], v[132:135], v[180:183], v[60:63]
	v_mfma_f32_16x16x32_bf16 v[56:59], v[140:143], v[180:183], v[56:59]
	v_mfma_f32_16x16x32_bf16 v[44:47], v[132:135], v[200:203], v[44:47]
	v_mfma_f32_16x16x32_bf16 v[40:43], v[140:143], v[200:203], v[40:43]
	v_mfma_f32_16x16x32_bf16 v[28:31], v[132:135], v[208:211], v[28:31]
	v_mfma_f32_16x16x32_bf16 v[24:27], v[140:143], v[208:211], v[24:27]
	v_mfma_f32_16x16x32_bf16 v[12:15], v[132:135], v[216:219], v[12:15]
	v_mfma_f32_16x16x32_bf16 v[8:11], v[140:143], v[216:219], v[8:11]
	s_setprio 0
	s_setprio 1
	v_mfma_f32_16x16x32_bf16 v[52:55], v[144:147], v[176:179], v[52:55]
	v_mfma_f32_16x16x32_bf16 v[48:51], v[168:171], v[176:179], v[48:51]
	v_mfma_f32_16x16x32_bf16 v[36:39], v[144:147], v[196:199], v[36:39]
	v_mfma_f32_16x16x32_bf16 v[32:35], v[168:171], v[196:199], v[32:35]
	v_mfma_f32_16x16x32_bf16 v[20:23], v[144:147], v[204:207], v[20:23]
	v_mfma_f32_16x16x32_bf16 v[16:19], v[168:171], v[204:207], v[16:19]
	v_mfma_f32_16x16x32_bf16 v[4:7], v[144:147], v[212:215], v[4:7]
	v_mfma_f32_16x16x32_bf16 v[0:3], v[168:171], v[212:215], v[0:3]
	v_mfma_f32_16x16x32_bf16 v[52:55], v[148:151], v[180:183], v[52:55]
	v_mfma_f32_16x16x32_bf16 v[48:51], v[172:175], v[180:183], v[48:51]
	v_mfma_f32_16x16x32_bf16 v[36:39], v[148:151], v[200:203], v[36:39]
	v_mfma_f32_16x16x32_bf16 v[32:35], v[172:175], v[200:203], v[32:35]
	v_mfma_f32_16x16x32_bf16 v[20:23], v[148:151], v[208:211], v[20:23]
	v_mfma_f32_16x16x32_bf16 v[16:19], v[172:175], v[208:211], v[16:19]
	v_mfma_f32_16x16x32_bf16 v[4:7], v[148:151], v[216:219], v[4:7]
	v_mfma_f32_16x16x32_bf16 v[0:3], v[172:175], v[216:219], v[0:3]
	s_barrier
	s_setprio 0
	s_nop 0
	s_add_i32 s58, 0, 0x18000
	s_add_i32 s59, 0, 0x1c000
	v_add_u32_e32 v140, s58, v189
	v_add_u32_e32 v172, s59, v189
	ds_read_b128 v[128:131], v140
	ds_read_b128 v[132:135], v140 offset:1024
	ds_read_b128 v[136:139], v140 offset:2048
	ds_read_b128 v[140:143], v140 offset:3072
	ds_read_b128 v[144:147], v172
	ds_read_b128 v[148:151], v172 offset:1024
	ds_read_b128 v[168:171], v172 offset:2048
	ds_read_b128 v[172:175], v172 offset:3072
	s_add_u32 s22, s28, 0xb0000
	s_addc_u32 s23, s29, 0
	s_mov_b32 m0, s36
	v_lshl_add_u64 v[226:227], s[22:23], 0, v[152:153]
	ds_read_b128 v[176:179], v193 offset:32768
	ds_read_b128 v[180:183], v193 offset:33792
	ds_read_b128 v[196:199], v193 offset:34816
	ds_read_b128 v[200:203], v193 offset:35840
	ds_read_b128 v[204:207], v193 offset:36864
	ds_read_b128 v[208:211], v193 offset:37888
	ds_read_b128 v[212:215], v193 offset:38912
	ds_read_b128 v[216:219], v193 offset:39936
	global_load_lds_dwordx4 v[226:227], off
	v_lshl_add_u64 v[226:227], s[22:23], 0, v[156:157]
	s_mov_b32 m0, s37
	s_nop 0
	global_load_lds_dwordx4 v[226:227], off
	s_waitcnt vmcnt(8) lgkmcnt(0)
	s_barrier
	s_setprio 1
	v_mfma_f32_16x16x32_bf16 v[124:127], v[128:131], v[176:179], v[124:127]
	v_mfma_f32_16x16x32_bf16 v[120:123], v[136:139], v[176:179], v[120:123]
	v_mfma_f32_16x16x32_bf16 v[108:111], v[128:131], v[196:199], v[108:111]
	v_mfma_f32_16x16x32_bf16 v[104:107], v[136:139], v[196:199], v[104:107]
	v_mfma_f32_16x16x32_bf16 v[92:95], v[128:131], v[204:207], v[92:95]
	v_mfma_f32_16x16x32_bf16 v[88:91], v[136:139], v[204:207], v[88:91]
	v_mfma_f32_16x16x32_bf16 v[76:79], v[128:131], v[212:215], v[76:79]
	v_mfma_f32_16x16x32_bf16 v[72:75], v[136:139], v[212:215], v[72:75]
	v_mfma_f32_16x16x32_bf16 v[124:127], v[132:135], v[180:183], v[124:127]
	v_mfma_f32_16x16x32_bf16 v[120:123], v[140:143], v[180:183], v[120:123]
	v_mfma_f32_16x16x32_bf16 v[108:111], v[132:135], v[200:203], v[108:111]
	v_mfma_f32_16x16x32_bf16 v[104:107], v[140:143], v[200:203], v[104:107]
	v_mfma_f32_16x16x32_bf16 v[92:95], v[132:135], v[208:211], v[92:95]
	v_mfma_f32_16x16x32_bf16 v[88:91], v[140:143], v[208:211], v[88:91]
	v_mfma_f32_16x16x32_bf16 v[76:79], v[132:135], v[216:219], v[76:79]
	v_mfma_f32_16x16x32_bf16 v[72:75], v[140:143], v[216:219], v[72:75]
	s_setprio 0
	s_setprio 1
	v_mfma_f32_16x16x32_bf16 v[116:119], v[144:147], v[176:179], v[116:119]
	v_mfma_f32_16x16x32_bf16 v[112:115], v[168:171], v[176:179], v[112:115]
	v_mfma_f32_16x16x32_bf16 v[100:103], v[144:147], v[196:199], v[100:103]
	v_mfma_f32_16x16x32_bf16 v[96:99], v[168:171], v[196:199], v[96:99]
	v_mfma_f32_16x16x32_bf16 v[84:87], v[144:147], v[204:207], v[84:87]
	v_mfma_f32_16x16x32_bf16 v[80:83], v[168:171], v[204:207], v[80:83]
	v_mfma_f32_16x16x32_bf16 v[68:71], v[144:147], v[212:215], v[68:71]
	v_mfma_f32_16x16x32_bf16 v[64:67], v[168:171], v[212:215], v[64:67]
	v_mfma_f32_16x16x32_bf16 v[116:119], v[148:151], v[180:183], v[116:119]
	v_mfma_f32_16x16x32_bf16 v[112:115], v[172:175], v[180:183], v[112:115]
	v_mfma_f32_16x16x32_bf16 v[100:103], v[148:151], v[200:203], v[100:103]
	v_mfma_f32_16x16x32_bf16 v[96:99], v[172:175], v[200:203], v[96:99]
	v_mfma_f32_16x16x32_bf16 v[84:87], v[148:151], v[208:211], v[84:87]
	v_mfma_f32_16x16x32_bf16 v[80:83], v[172:175], v[208:211], v[80:83]
	v_mfma_f32_16x16x32_bf16 v[68:71], v[148:151], v[216:219], v[68:71]
	v_mfma_f32_16x16x32_bf16 v[64:67], v[172:175], v[216:219], v[64:67]
	s_barrier
; #define PG8_STAGE(bufoff, gbase, voff) do { _Pragma("unroll") for (int _i = 0; _i < 2; ++_i) \
;         __builtin_amdgcn_global_load_lds((const unsigned*)((const char*)(gbase) + (voff)[_i]), (PG8_LAS unsigned*)(lds + (bufoff) + ldsw + _i * 8192), 16, 0, 0); } while (0)
; #define PG8_LDA(dst, b, h) do { _Pragma("unroll") for (int m = 0; m < 4; ++m) _Pragma("unroll") for (int k = 0; k < 2; ++k) dst[m][k] = *(const PG8_LAS bf16x8*)(lds + PG8_SA(b, h) + aoff + m * 2048 + k * 1024); } while (0)
; #define PG8_MMA(ai, bj, At, Bt) do { __builtin_amdgcn_s_setprio(1); _Pragma("unroll") for (int m = 0; m < 4; ++m) _Pragma("unroll") for (int n = 0; n < 2; ++n) _Pragma("unroll") for (int k = 0; k < 2; ++k) \
;         acc[ai][bj][m][n] = __builtin_amdgcn_mfma_f32_16x16x32_bf16(Bt[n][k], At[m][k], acc[ai][bj][m][n], 0, 0, 0); __builtin_amdgcn_s_setprio(0); } while (0)
; #define PG8_WAIT_V(n) asm volatile("s_waitcnt vmcnt(" #n ")" ::: "memory")
; #define PG8_WAIT_L(n) asm volatile("s_waitcnt lgkmcnt(" #n ")" ::: "memory")
; #define PG8_BAR __builtin_amdgcn_s_barrier()
; #define PG8_SCHED __builtin_amdgcn_sched_barrier(0)
; template <class Epi, class Sched, bool ALIGN_EPI = false, bool SP2 = false>
; __device__ __forceinline__ void gemm_phase(PG8_LAS unsigned char* lds, const Gemm g, const Sched& S, const Epi& E) {
;     ...
;         for (int t = 0; t < nt; t += 2) {
;             const bool last = (t == nt - 2);
;             const char* a1 = cA + (size_t)(t + 1) * kstep;
;             const char* a2 = last ? nA : cA + (size_t)(t + 2) * kstep; const char* b2 = last ? nB : cB + (size_t)(t + 2) * kstep;
;     ...
;             PG8_LDA(At, 1, 1); PG8_STAGE(PG8_SB(1, 0), b3, voffB); PG8_STAGE(PG8_SB(1, 1), b3 + hstepB, voffB); PG8_STAGE(PG8_SA(1, 0), a3, voffA);
;             PG8_WAIT_V(8); PG8_WAIT_L(0); PG8_BAR; PG8_MMA(1, 0, At, B0); PG8_MMA(1, 1, At, B1); PG8_BAR; PG8_SCHED;
;     ...
;         if constexpr (ALIGN_EPI) { if (wr == 0) PG8_BAR; }
	s_setprio 0
	s_add_i32 s22, s58, s31
	v_lshl_add_u64 v[184:185], v[184:185], 0, s[16:17]
	s_mov_b32 m0, s22
	ds_read_b128 v[176:179], v193 offset:49152
	ds_read_b128 v[180:183], v193 offset:50176
	ds_read_b128 v[196:199], v193 offset:51200
	ds_read_b128 v[200:203], v193 offset:52224
	ds_read_b128 v[204:207], v193 offset:53248
	ds_read_b128 v[208:211], v193 offset:54272
	ds_read_b128 v[212:215], v193 offset:55296
	ds_read_b128 v[216:219], v193 offset:56320
	global_load_lds_dwordx4 v[184:185], off
	s_add_i32 m0, s22, 0x2000
	s_add_u32 s22, s26, 0xb0080
	v_lshl_add_u64 v[184:185], v[220:221], 0, s[16:17]
	s_addc_u32 s23, s27, 0
	s_add_i32 s26, s59, s31
	global_load_lds_dwordx4 v[184:185], off
	v_lshl_add_u64 v[184:185], s[22:23], 0, v[154:155]
	s_mov_b32 m0, s26
	s_nop 0
	global_load_lds_dwordx4 v[184:185], off
	v_lshl_add_u64 v[184:185], s[22:23], 0, v[158:159]
	s_add_i32 m0, s26, 0x2000
	s_nop 0
	global_load_lds_dwordx4 v[184:185], off
	v_lshl_add_u64 v[184:185], v[222:223], 0, s[16:17]
	s_mov_b32 m0, s39
	s_nop 0
	global_load_lds_dwordx4 v[184:185], off
	v_lshl_add_u64 v[184:185], v[224:225], 0, s[16:17]
	s_mov_b32 m0, s40
	s_nop 0
	global_load_lds_dwordx4 v[184:185], off
	s_waitcnt vmcnt(8) lgkmcnt(0)
	s_barrier
	s_setprio 1
	v_mfma_f32_16x16x32_bf16 v[60:63], v[128:131], v[176:179], v[60:63]
	v_mfma_f32_16x16x32_bf16 v[56:59], v[136:139], v[176:179], v[56:59]
	v_mfma_f32_16x16x32_bf16 v[44:47], v[128:131], v[196:199], v[44:47]
	v_mfma_f32_16x16x32_bf16 v[40:43], v[136:139], v[196:199], v[40:43]
	v_mfma_f32_16x16x32_bf16 v[28:31], v[128:131], v[204:207], v[28:31]
	v_mfma_f32_16x16x32_bf16 v[24:27], v[136:139], v[204:207], v[24:27]
	v_mfma_f32_16x16x32_bf16 v[12:15], v[128:131], v[212:215], v[12:15]
	v_mfma_f32_16x16x32_bf16 v[8:11], v[136:139], v[212:215], v[8:11]
	v_mfma_f32_16x16x32_bf16 v[60:63], v[132:135], v[180:183], v[60:63]
	v_mfma_f32_16x16x32_bf16 v[56:59], v[140:143], v[180:183], v[56:59]
	v_mfma_f32_16x16x32_bf16 v[44:47], v[132:135], v[200:203], v[44:47]
	v_mfma_f32_16x16x32_bf16 v[40:43], v[140:143], v[200:203], v[40:43]
	v_mfma_f32_16x16x32_bf16 v[28:31], v[132:135], v[208:211], v[28:31]
	v_mfma_f32_16x16x32_bf16 v[24:27], v[140:143], v[208:211], v[24:27]
	v_mfma_f32_16x16x32_bf16 v[12:15], v[132:135], v[216:219], v[12:15]
	v_mfma_f32_16x16x32_bf16 v[8:11], v[140:143], v[216:219], v[8:11]
	s_setprio 0
	s_setprio 1
	v_mfma_f32_16x16x32_bf16 v[52:55], v[144:147], v[176:179], v[52:55]
	v_mfma_f32_16x16x32_bf16 v[48:51], v[168:171], v[176:179], v[48:51]
	v_mfma_f32_16x16x32_bf16 v[36:39], v[144:147], v[196:199], v[36:39]
	v_mfma_f32_16x16x32_bf16 v[32:35], v[168:171], v[196:199], v[32:35]
	v_mfma_f32_16x16x32_bf16 v[20:23], v[144:147], v[204:207], v[20:23]
	v_mfma_f32_16x16x32_bf16 v[16:19], v[168:171], v[204:207], v[16:19]
	v_mfma_f32_16x16x32_bf16 v[4:7], v[144:147], v[212:215], v[4:7]
	v_mfma_f32_16x16x32_bf16 v[0:3], v[168:171], v[212:215], v[0:3]
	v_mfma_f32_16x16x32_bf16 v[52:55], v[148:151], v[180:183], v[52:55]
	v_mfma_f32_16x16x32_bf16 v[48:51], v[172:175], v[180:183], v[48:51]
	v_mfma_f32_16x16x32_bf16 v[36:39], v[148:151], v[200:203], v[36:39]
	v_mfma_f32_16x16x32_bf16 v[32:35], v[172:175], v[200:203], v[32:35]
	v_mfma_f32_16x16x32_bf16 v[20:23], v[148:151], v[208:211], v[20:23]
	v_mfma_f32_16x16x32_bf16 v[16:19], v[172:175], v[208:211], v[16:19]
	v_mfma_f32_16x16x32_bf16 v[4:7], v[148:151], v[216:219], v[4:7]
	v_mfma_f32_16x16x32_bf16 v[0:3], v[172:175], v[216:219], v[0:3]
	s_barrier
	s_setprio 0
	s_add_i32 s69, s69, 2
	s_add_u32 s67, s67, 0x100
	s_addc_u32 s68, s68, 0
	s_cmp_gt_u32 s69, 41
	s_mov_b64 s[22:23], s[24:25]
	s_cbranch_scc0 .LBB0_1129
	s_and_b64 vcc, exec, s[18:19]
	s_cbranch_vccz .LBB0_1132
	s_barrier

; #define PG8_STAGE(bufoff, gbase, voff) do { _Pragma("unroll") for (int _i = 0; _i < 2; ++_i) \
;         __builtin_amdgcn_global_load_lds((const unsigned*)((const char*)(gbase) + (voff)[_i]), (PG8_LAS unsigned*)(lds + (bufoff) + ldsw + _i * 8192), 16, 0, 0); } while (0)
; #define PG8_LDA(dst, b, h) do { _Pragma("unroll") for (int m = 0; m < 4; ++m) _Pragma("unroll") for (int k = 0; k < 2; ++k) dst[m][k] = *(const PG8_LAS bf16x8*)(lds + PG8_SA(b, h) + aoff + m * 2048 + k * 1024); } while (0)
; #define PG8_LDB(dst, b, h) do { _Pragma("unroll") for (int n = 0; n < 2; ++n) _Pragma("unroll") for (int k = 0; k < 2; ++k) dst[n][k] = *(const PG8_LAS bf16x8*)(lds + PG8_SB(b, h) + boff + n * 2048 + k * 1024); } while (0)
; #define PG8_MMA(ai, bj, At, Bt) do { __builtin_amdgcn_s_setprio(1); _Pragma("unroll") for (int m = 0; m < 4; ++m) _Pragma("unroll") for (int n = 0; n < 2; ++n) _Pragma("unroll") for (int k = 0; k < 2; ++k) \
;         acc[ai][bj][m][n] = __builtin_amdgcn_mfma_f32_16x16x32_bf16(Bt[n][k], At[m][k], acc[ai][bj][m][n], 0, 0, 0); __builtin_amdgcn_s_setprio(0); } while (0)
; #define PG8_WAIT_V(n) asm volatile("s_waitcnt vmcnt(" #n ")" ::: "memory")
; #define PG8_BAR __builtin_amdgcn_s_barrier()
; template <class Epi, class Sched, bool ALIGN_EPI = false, bool SP2 = false>
; __device__ __forceinline__ void gemm_phase(PG8_LAS unsigned char* lds, const Gemm g, const Sched& S, const Epi& E) {
;     ...
;         for (int t = 0; t < nt; t += 2) {
;             const bool last = (t == nt - 2);
;             const char* a1 = cA + (size_t)(t + 1) * kstep;
;             const char* a2 = last ? nA : cA + (size_t)(t + 2) * kstep; const char* b2 = last ? nB : cB + (size_t)(t + 2) * kstep;
;             const char* a3 = a2 + kstep; const char* b3 = b2 + kstep;
;             if (last && has_next) S.a_ready(nxt);
;             if constexpr (SP2) {
;             PG8_LDB(B0, 0, 0); PG8_LDB(B1, 0, 1); PG8_SCHED; PG8_LDA(At, 0, 0); PG8_STAGE(PG8_SA(1, 1), a1 + hstepA, voffA);
;             PG8_WAIT_V(8); PG8_WAIT_L(0); PG8_BAR; PG8_MMA(0, 0, At, B0); PG8_MMA(0, 1, At, B1); PG8_BAR; PG8_SCHED;
;             PG8_LDA(At, 0, 1); PG8_STAGE(PG8_SB(0, 0), b2, voffB); PG8_STAGE(PG8_SB(0, 1), b2 + hstepB, voffB); PG8_STAGE(PG8_SA(0, 0), a2, voffA);
;             PG8_WAIT_V(8); PG8_WAIT_L(0); PG8_BAR; PG8_MMA(1, 0, At, B0); PG8_MMA(1, 1, At, B1); PG8_BAR; PG8_SCHED;
.LBB0_1231:
	ds_read_b128 v[112:115], v185
	ds_read_b128 v[116:119], v185 offset:1024
	ds_read_b128 v[128:131], v185 offset:2048
	ds_read_b128 v[140:143], v185 offset:3072
	ds_read_b128 v[144:147], v188
	ds_read_b128 v[148:151], v188 offset:1024
	ds_read_b128 v[168:171], v188 offset:2048
	ds_read_b128 v[172:175], v188 offset:3072
	s_add_u32 s34, s30, 0xfffc0080
	s_addc_u32 s35, s31, -1
	s_cmp_eq_u32 s69, 12
	s_cselect_b32 s37, s21, s35
	s_cselect_b32 s36, s27, s34
	s_cselect_b32 s35, s19, s68
	s_cselect_b32 s34, s66, s67
	v_lshl_add_u64 v[180:181], s[30:31], 0, v[160:161]
	s_add_i32 m0, s29, 0xc000
	ds_read_b128 v[176:179], v189
	ds_read_b128 v[192:195], v189 offset:1024
	ds_read_b128 v[196:199], v189 offset:2048
	ds_read_b128 v[200:203], v189 offset:3072
	ds_read_b128 v[204:207], v189 offset:4096
	ds_read_b128 v[208:211], v189 offset:5120
	ds_read_b128 v[212:215], v189 offset:6144
	ds_read_b128 v[216:219], v189 offset:7168
	global_load_lds_dwordx4 v[180:181], off
	v_lshl_add_u64 v[180:181], s[30:31], 0, v[162:163]
	s_add_i32 m0, s29, 0xe000
	s_nop 0
	global_load_lds_dwordx4 v[180:181], off
	s_waitcnt vmcnt(8) lgkmcnt(0)
	s_barrier
	s_setprio 1
	v_mfma_f32_16x16x32_bf16 v[136:139], v[112:115], v[176:179], v[136:139]
	v_mfma_f32_16x16x32_bf16 v[132:135], v[128:131], v[176:179], v[132:135]
	v_mfma_f32_16x16x32_bf16 v[108:111], v[112:115], v[196:199], v[108:111]
	v_mfma_f32_16x16x32_bf16 v[104:107], v[128:131], v[196:199], v[104:107]
	v_mfma_f32_16x16x32_bf16 v[92:95], v[112:115], v[204:207], v[92:95]
	v_mfma_f32_16x16x32_bf16 v[88:91], v[128:131], v[204:207], v[88:91]
	v_mfma_f32_16x16x32_bf16 v[76:79], v[112:115], v[212:215], v[76:79]
	v_mfma_f32_16x16x32_bf16 v[72:75], v[128:131], v[212:215], v[72:75]
	v_mfma_f32_16x16x32_bf16 v[136:139], v[116:119], v[192:195], v[136:139]
	v_mfma_f32_16x16x32_bf16 v[132:135], v[140:143], v[192:195], v[132:135]
	v_mfma_f32_16x16x32_bf16 v[108:111], v[116:119], v[200:203], v[108:111]
	v_mfma_f32_16x16x32_bf16 v[104:107], v[140:143], v[200:203], v[104:107]
	v_mfma_f32_16x16x32_bf16 v[92:95], v[116:119], v[208:211], v[92:95]
	v_mfma_f32_16x16x32_bf16 v[88:91], v[140:143], v[208:211], v[88:91]
	v_mfma_f32_16x16x32_bf16 v[76:79], v[116:119], v[216:219], v[76:79]
	v_mfma_f32_16x16x32_bf16 v[72:75], v[140:143], v[216:219], v[72:75]
	s_setprio 0
	s_setprio 1
	v_mfma_f32_16x16x32_bf16 v[124:127], v[144:147], v[176:179], v[124:127]
	v_mfma_f32_16x16x32_bf16 v[120:123], v[168:171], v[176:179], v[120:123]
	v_mfma_f32_16x16x32_bf16 v[100:103], v[144:147], v[196:199], v[100:103]
	v_mfma_f32_16x16x32_bf16 v[96:99], v[168:171], v[196:199], v[96:99]
	v_mfma_f32_16x16x32_bf16 v[84:87], v[144:147], v[204:207], v[84:87]
	v_mfma_f32_16x16x32_bf16 v[80:83], v[168:171], v[204:207], v[80:83]
	v_mfma_f32_16x16x32_bf16 v[68:71], v[144:147], v[212:215], v[68:71]
	v_mfma_f32_16x16x32_bf16 v[64:67], v[168:171], v[212:215], v[64:67]
	v_mfma_f32_16x16x32_bf16 v[124:127], v[148:151], v[192:195], v[124:127]
	v_mfma_f32_16x16x32_bf16 v[120:123], v[172:175], v[192:195], v[120:123]
	v_mfma_f32_16x16x32_bf16 v[100:103], v[148:151], v[200:203], v[100:103]
	v_mfma_f32_16x16x32_bf16 v[96:99], v[172:175], v[200:203], v[96:99]
	v_mfma_f32_16x16x32_bf16 v[84:87], v[148:151], v[208:211], v[84:87]
	v_mfma_f32_16x16x32_bf16 v[80:83], v[172:175], v[208:211], v[80:83]
	v_mfma_f32_16x16x32_bf16 v[68:71], v[148:151], v[216:219], v[68:71]
	v_mfma_f32_16x16x32_bf16 v[64:67], v[172:175], v[216:219], v[64:67]
	s_barrier
	s_setprio 0
	s_nop 0
	s_add_i32 s58, s49, s39
	v_lshl_add_u64 v[180:181], s[34:35], 0, v[154:155]
	s_mov_b32 m0, s58
	ds_read_b128 v[176:179], v189 offset:16384
	ds_read_b128 v[192:195], v189 offset:17408
	ds_read_b128 v[196:199], v189 offset:18432
	ds_read_b128 v[200:203], v189 offset:19456
	ds_read_b128 v[204:207], v189 offset:20480
	ds_read_b128 v[208:211], v189 offset:21504
	ds_read_b128 v[212:215], v189 offset:22528
	ds_read_b128 v[216:219], v189 offset:23552
	global_load_lds_dwordx4 v[180:181], off
	s_add_i32 m0, s58, 0x2000
	s_add_u32 s58, s34, 0x40000
	v_lshl_add_u64 v[220:221], s[34:35], 0, v[158:159]
	s_addc_u32 s59, s35, 0
	s_add_i32 s73, s64, s39
	global_load_lds_dwordx4 v[220:221], off
	v_lshl_add_u64 v[222:223], s[58:59], 0, v[154:155]
	s_mov_b32 m0, s73
	v_lshl_add_u64 v[224:225], s[36:37], 0, v[156:157]
	global_load_lds_dwordx4 v[222:223], off
	v_lshl_add_u64 v[222:223], s[58:59], 0, v[158:159]
	s_add_i32 m0, s73, 0x2000
	s_nop 0
	global_load_lds_dwordx4 v[222:223], off
	v_lshl_add_u64 v[222:223], s[36:37], 0, v[152:153]
	s_mov_b32 m0, s29
	s_nop 0
	global_load_lds_dwordx4 v[222:223], off
	s_mov_b32 m0, s40
	s_nop 0
	global_load_lds_dwordx4 v[224:225], off
	s_waitcnt vmcnt(8) lgkmcnt(0)
	s_barrier
; #define PG8_STAGE(bufoff, gbase, voff) do { _Pragma("unroll") for (int _i = 0; _i < 2; ++_i) \
;         __builtin_amdgcn_global_load_lds((const unsigned*)((const char*)(gbase) + (voff)[_i]), (PG8_LAS unsigned*)(lds + (bufoff) + ldsw + _i * 8192), 16, 0, 0); } while (0)
; #define PG8_LDA(dst, b, h) do { _Pragma("unroll") for (int m = 0; m < 4; ++m) _Pragma("unroll") for (int k = 0; k < 2; ++k) dst[m][k] = *(const PG8_LAS bf16x8*)(lds + PG8_SA(b, h) + aoff + m * 2048 + k * 1024); } while (0)
; #define PG8_LDB(dst, b, h) do { _Pragma("unroll") for (int n = 0; n < 2; ++n) _Pragma("unroll") for (int k = 0; k < 2; ++k) dst[n][k] = *(const PG8_LAS bf16x8*)(lds + PG8_SB(b, h) + boff + n * 2048 + k * 1024); } while (0)
; #define PG8_MMA(ai, bj, At, Bt) do { __builtin_amdgcn_s_setprio(1); _Pragma("unroll") for (int m = 0; m < 4; ++m) _Pragma("unroll") for (int n = 0; n < 2; ++n) _Pragma("unroll") for (int k = 0; k < 2; ++k) \
;         acc[ai][bj][m][n] = __builtin_amdgcn_mfma_f32_16x16x32_bf16(Bt[n][k], At[m][k], acc[ai][bj][m][n], 0, 0, 0); __builtin_amdgcn_s_setprio(0); } while (0)
; #define PG8_WAIT_V(n) asm volatile("s_waitcnt vmcnt(" #n ")" ::: "memory")
; #define PG8_WAIT_L(n) asm volatile("s_waitcnt lgkmcnt(" #n ")" ::: "memory")
; #define PG8_BAR __builtin_amdgcn_s_barrier()
; #define PG8_SCHED __builtin_amdgcn_sched_barrier(0)
; template <class Epi, class Sched, bool ALIGN_EPI = false, bool SP2 = false>
; __device__ __forceinline__ void gemm_phase(PG8_LAS unsigned char* lds, const Gemm g, const Sched& S, const Epi& E) {
;     ...
;             PG8_WAIT_V(8); PG8_WAIT_L(0); PG8_BAR; PG8_MMA(1, 0, At, B0); PG8_MMA(1, 1, At, B1); PG8_BAR; PG8_SCHED;
;             PG8_LDB(B0, 1, 0); PG8_LDB(B1, 1, 1); PG8_SCHED; PG8_LDA(At, 1, 0); PG8_STAGE(PG8_SA(0, 1), a2 + hstepA, voffA);
;             PG8_WAIT_V(8); PG8_WAIT_L(0); PG8_BAR; PG8_MMA(0, 0, At, B0); PG8_MMA(0, 1, At, B1); PG8_BAR; PG8_SCHED;
;             PG8_LDA(At, 1, 1); PG8_STAGE(PG8_SB(1, 0), b3, voffB); PG8_STAGE(PG8_SB(1, 1), b3 + hstepB, voffB); PG8_STAGE(PG8_SA(1, 0), a3, voffA);
;             PG8_WAIT_V(8); PG8_WAIT_L(0); PG8_BAR; PG8_MMA(1, 0, At, B0); PG8_MMA(1, 1, At, B1); PG8_BAR; PG8_SCHED;
	s_setprio 1
	v_mfma_f32_16x16x32_bf16 v[60:63], v[112:115], v[176:179], v[60:63]
	v_mfma_f32_16x16x32_bf16 v[56:59], v[128:131], v[176:179], v[56:59]
	v_mfma_f32_16x16x32_bf16 v[44:47], v[112:115], v[196:199], v[44:47]
	v_mfma_f32_16x16x32_bf16 v[40:43], v[128:131], v[196:199], v[40:43]
	v_mfma_f32_16x16x32_bf16 v[28:31], v[112:115], v[204:207], v[28:31]
	v_mfma_f32_16x16x32_bf16 v[24:27], v[128:131], v[204:207], v[24:27]
	v_mfma_f32_16x16x32_bf16 v[12:15], v[112:115], v[212:215], v[12:15]
	v_mfma_f32_16x16x32_bf16 v[8:11], v[128:131], v[212:215], v[8:11]
	v_mfma_f32_16x16x32_bf16 v[60:63], v[116:119], v[192:195], v[60:63]
	v_mfma_f32_16x16x32_bf16 v[56:59], v[140:143], v[192:195], v[56:59]
	v_mfma_f32_16x16x32_bf16 v[44:47], v[116:119], v[200:203], v[44:47]
	v_mfma_f32_16x16x32_bf16 v[40:43], v[140:143], v[200:203], v[40:43]
	v_mfma_f32_16x16x32_bf16 v[28:31], v[116:119], v[208:211], v[28:31]
	v_mfma_f32_16x16x32_bf16 v[24:27], v[140:143], v[208:211], v[24:27]
	v_mfma_f32_16x16x32_bf16 v[12:15], v[116:119], v[216:219], v[12:15]
	v_mfma_f32_16x16x32_bf16 v[8:11], v[140:143], v[216:219], v[8:11]
	s_setprio 0
	s_setprio 1
	v_mfma_f32_16x16x32_bf16 v[52:55], v[144:147], v[176:179], v[52:55]
	v_mfma_f32_16x16x32_bf16 v[48:51], v[168:171], v[176:179], v[48:51]
	v_mfma_f32_16x16x32_bf16 v[36:39], v[144:147], v[196:199], v[36:39]
	v_mfma_f32_16x16x32_bf16 v[32:35], v[168:171], v[196:199], v[32:35]
	v_mfma_f32_16x16x32_bf16 v[20:23], v[144:147], v[204:207], v[20:23]
	v_mfma_f32_16x16x32_bf16 v[16:19], v[168:171], v[204:207], v[16:19]
	v_mfma_f32_16x16x32_bf16 v[4:7], v[144:147], v[212:215], v[4:7]
	v_mfma_f32_16x16x32_bf16 v[0:3], v[168:171], v[212:215], v[0:3]
	v_mfma_f32_16x16x32_bf16 v[52:55], v[148:151], v[192:195], v[52:55]
	v_mfma_f32_16x16x32_bf16 v[48:51], v[172:175], v[192:195], v[48:51]
	v_mfma_f32_16x16x32_bf16 v[36:39], v[148:151], v[200:203], v[36:39]
	v_mfma_f32_16x16x32_bf16 v[32:35], v[172:175], v[200:203], v[32:35]
	v_mfma_f32_16x16x32_bf16 v[20:23], v[148:151], v[208:211], v[20:23]
	v_mfma_f32_16x16x32_bf16 v[16:19], v[172:175], v[208:211], v[16:19]
	v_mfma_f32_16x16x32_bf16 v[4:7], v[148:151], v[216:219], v[4:7]
	v_mfma_f32_16x16x32_bf16 v[0:3], v[172:175], v[216:219], v[0:3]
	s_barrier
	s_setprio 0
	s_nop 0
	s_add_i32 s58, 0, 0x18000
	s_add_i32 s59, 0, 0x1c000
	v_add_u32_e32 v140, s58, v183
	v_add_u32_e32 v172, s59, v183
	ds_read_b128 v[112:115], v140
	ds_read_b128 v[116:119], v140 offset:1024
	ds_read_b128 v[128:131], v140 offset:2048
	ds_read_b128 v[140:143], v140 offset:3072
	ds_read_b128 v[144:147], v172
	ds_read_b128 v[148:151], v172 offset:1024
	ds_read_b128 v[168:171], v172 offset:2048
	ds_read_b128 v[172:175], v172 offset:3072
	s_add_u32 s36, s36, 0x40000
	s_addc_u32 s37, s37, 0
	s_mov_b32 m0, s41
	v_lshl_add_u64 v[226:227], s[36:37], 0, v[152:153]
	ds_read_b128 v[176:179], v189 offset:32768
	ds_read_b128 v[192:195], v189 offset:33792
	ds_read_b128 v[196:199], v189 offset:34816
	ds_read_b128 v[200:203], v189 offset:35840
	ds_read_b128 v[204:207], v189 offset:36864
	ds_read_b128 v[208:211], v189 offset:37888
	ds_read_b128 v[212:215], v189 offset:38912
	ds_read_b128 v[216:219], v189 offset:39936
	global_load_lds_dwordx4 v[226:227], off
	v_lshl_add_u64 v[226:227], s[36:37], 0, v[156:157]
	s_mov_b32 m0, s42
	s_nop 0
	global_load_lds_dwordx4 v[226:227], off
	s_waitcnt vmcnt(8) lgkmcnt(0)
	s_barrier
	s_setprio 1
	v_mfma_f32_16x16x32_bf16 v[136:139], v[112:115], v[176:179], v[136:139]
	v_mfma_f32_16x16x32_bf16 v[132:135], v[128:131], v[176:179], v[132:135]
	v_mfma_f32_16x16x32_bf16 v[108:111], v[112:115], v[196:199], v[108:111]
	v_mfma_f32_16x16x32_bf16 v[104:107], v[128:131], v[196:199], v[104:107]
	v_mfma_f32_16x16x32_bf16 v[92:95], v[112:115], v[204:207], v[92:95]
	v_mfma_f32_16x16x32_bf16 v[88:91], v[128:131], v[204:207], v[88:91]
	v_mfma_f32_16x16x32_bf16 v[76:79], v[112:115], v[212:215], v[76:79]
	v_mfma_f32_16x16x32_bf16 v[72:75], v[128:131], v[212:215], v[72:75]
	v_mfma_f32_16x16x32_bf16 v[136:139], v[116:119], v[192:195], v[136:139]
	v_mfma_f32_16x16x32_bf16 v[132:135], v[140:143], v[192:195], v[132:135]
	v_mfma_f32_16x16x32_bf16 v[108:111], v[116:119], v[200:203], v[108:111]
	v_mfma_f32_16x16x32_bf16 v[104:107], v[140:143], v[200:203], v[104:107]
	v_mfma_f32_16x16x32_bf16 v[92:95], v[116:119], v[208:211], v[92:95]
	v_mfma_f32_16x16x32_bf16 v[88:91], v[140:143], v[208:211], v[88:91]
	v_mfma_f32_16x16x32_bf16 v[76:79], v[116:119], v[216:219], v[76:79]
	v_mfma_f32_16x16x32_bf16 v[72:75], v[140:143], v[216:219], v[72:75]
	s_setprio 0
	s_setprio 1
	v_mfma_f32_16x16x32_bf16 v[124:127], v[144:147], v[176:179], v[124:127]
	v_mfma_f32_16x16x32_bf16 v[120:123], v[168:171], v[176:179], v[120:123]
	v_mfma_f32_16x16x32_bf16 v[100:103], v[144:147], v[196:199], v[100:103]
	v_mfma_f32_16x16x32_bf16 v[96:99], v[168:171], v[196:199], v[96:99]
	v_mfma_f32_16x16x32_bf16 v[84:87], v[144:147], v[204:207], v[84:87]
	v_mfma_f32_16x16x32_bf16 v[80:83], v[168:171], v[204:207], v[80:83]
	v_mfma_f32_16x16x32_bf16 v[68:71], v[144:147], v[212:215], v[68:71]
	v_mfma_f32_16x16x32_bf16 v[64:67], v[168:171], v[212:215], v[64:67]
	v_mfma_f32_16x16x32_bf16 v[124:127], v[148:151], v[192:195], v[124:127]
	v_mfma_f32_16x16x32_bf16 v[120:123], v[172:175], v[192:195], v[120:123]
	v_mfma_f32_16x16x32_bf16 v[100:103], v[148:151], v[200:203], v[100:103]
	v_mfma_f32_16x16x32_bf16 v[96:99], v[172:175], v[200:203], v[96:99]
	v_mfma_f32_16x16x32_bf16 v[84:87], v[148:151], v[208:211], v[84:87]
	v_mfma_f32_16x16x32_bf16 v[80:83], v[172:175], v[208:211], v[80:83]
	v_mfma_f32_16x16x32_bf16 v[68:71], v[148:151], v[216:219], v[68:71]
	v_mfma_f32_16x16x32_bf16 v[64:67], v[172:175], v[216:219], v[64:67]
	s_barrier
; #define PG8_STAGE(bufoff, gbase, voff) do { _Pragma("unroll") for (int _i = 0; _i < 2; ++_i) \
;         __builtin_amdgcn_global_load_lds((const unsigned*)((const char*)(gbase) + (voff)[_i]), (PG8_LAS unsigned*)(lds + (bufoff) + ldsw + _i * 8192), 16, 0, 0); } while (0)
; #define PG8_LDA(dst, b, h) do { _Pragma("unroll") for (int m = 0; m < 4; ++m) _Pragma("unroll") for (int k = 0; k < 2; ++k) dst[m][k] = *(const PG8_LAS bf16x8*)(lds + PG8_SA(b, h) + aoff + m * 2048 + k * 1024); } while (0)
; #define PG8_MMA(ai, bj, At, Bt) do { __builtin_amdgcn_s_setprio(1); _Pragma("unroll") for (int m = 0; m < 4; ++m) _Pragma("unroll") for (int n = 0; n < 2; ++n) _Pragma("unroll") for (int k = 0; k < 2; ++k) \
;         acc[ai][bj][m][n] = __builtin_amdgcn_mfma_f32_16x16x32_bf16(Bt[n][k], At[m][k], acc[ai][bj][m][n], 0, 0, 0); __builtin_amdgcn_s_setprio(0); } while (0)
; #define PG8_WAIT_V(n) asm volatile("s_waitcnt vmcnt(" #n ")" ::: "memory")
; #define PG8_WAIT_L(n) asm volatile("s_waitcnt lgkmcnt(" #n ")" ::: "memory")
; #define PG8_BAR __builtin_amdgcn_s_barrier()
; #define PG8_SCHED __builtin_amdgcn_sched_barrier(0)
; template <class Epi, class Sched, bool ALIGN_EPI = false, bool SP2 = false>
; __device__ __forceinline__ void gemm_phase(PG8_LAS unsigned char* lds, const Gemm g, const Sched& S, const Epi& E) {
;     ...
;         for (int t = 0; t < nt; t += 2) {
;             const bool last = (t == nt - 2);
;             const char* a1 = cA + (size_t)(t + 1) * kstep;
;             const char* a2 = last ? nA : cA + (size_t)(t + 2) * kstep; const char* b2 = last ? nB : cB + (size_t)(t + 2) * kstep;
;     ...
;             PG8_LDA(At, 1, 1); PG8_STAGE(PG8_SB(1, 0), b3, voffB); PG8_STAGE(PG8_SB(1, 1), b3 + hstepB, voffB); PG8_STAGE(PG8_SA(1, 0), a3, voffA);
;             PG8_WAIT_V(8); PG8_WAIT_L(0); PG8_BAR; PG8_MMA(1, 0, At, B0); PG8_MMA(1, 1, At, B1); PG8_BAR; PG8_SCHED;
;     ...
;         if constexpr (ALIGN_EPI) { if (wr == 0) PG8_BAR; }
	s_setprio 0
	s_add_i32 s36, s58, s39
	v_lshl_add_u64 v[180:181], v[180:181], 0, s[14:15]
	s_mov_b32 m0, s36
	ds_read_b128 v[176:179], v189 offset:49152
	ds_read_b128 v[192:195], v189 offset:50176
	ds_read_b128 v[196:199], v189 offset:51200
	ds_read_b128 v[200:203], v189 offset:52224
	ds_read_b128 v[204:207], v189 offset:53248
	ds_read_b128 v[208:211], v189 offset:54272
	ds_read_b128 v[212:215], v189 offset:55296
	ds_read_b128 v[216:219], v189 offset:56320
	global_load_lds_dwordx4 v[180:181], off
	s_add_i32 m0, s36, 0x2000
	s_add_u32 s34, s34, 0x40080
	v_lshl_add_u64 v[180:181], v[220:221], 0, s[14:15]
	s_addc_u32 s35, s35, 0
	s_add_i32 s36, s59, s39
	global_load_lds_dwordx4 v[180:181], off
	v_lshl_add_u64 v[180:181], s[34:35], 0, v[154:155]
	s_mov_b32 m0, s36
	s_nop 0
	global_load_lds_dwordx4 v[180:181], off
	v_lshl_add_u64 v[180:181], s[34:35], 0, v[158:159]
	s_add_i32 m0, s36, 0x2000
	s_nop 0
	global_load_lds_dwordx4 v[180:181], off
	v_lshl_add_u64 v[180:181], v[222:223], 0, s[14:15]
	s_mov_b32 m0, s44
	s_nop 0
	global_load_lds_dwordx4 v[180:181], off
	v_lshl_add_u64 v[180:181], v[224:225], 0, s[14:15]
	s_mov_b32 m0, s45
	s_nop 0
	global_load_lds_dwordx4 v[180:181], off
	s_waitcnt vmcnt(8) lgkmcnt(0)
	s_barrier
	s_setprio 1
	v_mfma_f32_16x16x32_bf16 v[60:63], v[112:115], v[176:179], v[60:63]
	v_mfma_f32_16x16x32_bf16 v[56:59], v[128:131], v[176:179], v[56:59]
	v_mfma_f32_16x16x32_bf16 v[44:47], v[112:115], v[196:199], v[44:47]
	v_mfma_f32_16x16x32_bf16 v[40:43], v[128:131], v[196:199], v[40:43]
	v_mfma_f32_16x16x32_bf16 v[28:31], v[112:115], v[204:207], v[28:31]
	v_mfma_f32_16x16x32_bf16 v[24:27], v[128:131], v[204:207], v[24:27]
	v_mfma_f32_16x16x32_bf16 v[12:15], v[112:115], v[212:215], v[12:15]
	v_mfma_f32_16x16x32_bf16 v[8:11], v[128:131], v[212:215], v[8:11]
	v_mfma_f32_16x16x32_bf16 v[60:63], v[116:119], v[192:195], v[60:63]
	v_mfma_f32_16x16x32_bf16 v[56:59], v[140:143], v[192:195], v[56:59]
	v_mfma_f32_16x16x32_bf16 v[44:47], v[116:119], v[200:203], v[44:47]
	v_mfma_f32_16x16x32_bf16 v[40:43], v[140:143], v[200:203], v[40:43]
	v_mfma_f32_16x16x32_bf16 v[28:31], v[116:119], v[208:211], v[28:31]
	v_mfma_f32_16x16x32_bf16 v[24:27], v[140:143], v[208:211], v[24:27]
	v_mfma_f32_16x16x32_bf16 v[12:15], v[116:119], v[216:219], v[12:15]
	v_mfma_f32_16x16x32_bf16 v[8:11], v[140:143], v[216:219], v[8:11]
	s_setprio 0
	s_setprio 1
	v_mfma_f32_16x16x32_bf16 v[52:55], v[144:147], v[176:179], v[52:55]
	v_mfma_f32_16x16x32_bf16 v[48:51], v[168:171], v[176:179], v[48:51]
	v_mfma_f32_16x16x32_bf16 v[36:39], v[144:147], v[196:199], v[36:39]
	v_mfma_f32_16x16x32_bf16 v[32:35], v[168:171], v[196:199], v[32:35]
	v_mfma_f32_16x16x32_bf16 v[20:23], v[144:147], v[204:207], v[20:23]
	v_mfma_f32_16x16x32_bf16 v[16:19], v[168:171], v[204:207], v[16:19]
	v_mfma_f32_16x16x32_bf16 v[4:7], v[144:147], v[212:215], v[4:7]
	v_mfma_f32_16x16x32_bf16 v[0:3], v[168:171], v[212:215], v[0:3]
	v_mfma_f32_16x16x32_bf16 v[52:55], v[148:151], v[192:195], v[52:55]
	v_mfma_f32_16x16x32_bf16 v[48:51], v[172:175], v[192:195], v[48:51]
	v_mfma_f32_16x16x32_bf16 v[36:39], v[148:151], v[200:203], v[36:39]
	v_mfma_f32_16x16x32_bf16 v[32:35], v[172:175], v[200:203], v[32:35]
	v_mfma_f32_16x16x32_bf16 v[20:23], v[148:151], v[208:211], v[20:23]
	v_mfma_f32_16x16x32_bf16 v[16:19], v[172:175], v[208:211], v[16:19]
	v_mfma_f32_16x16x32_bf16 v[4:7], v[148:151], v[216:219], v[4:7]
	v_mfma_f32_16x16x32_bf16 v[0:3], v[172:175], v[216:219], v[0:3]
	s_barrier
	s_setprio 0
	s_add_i32 s69, s69, 2
	s_add_u32 s30, s30, 0x100
	s_addc_u32 s31, s31, 0
	s_add_u32 s67, s67, 0x100
	s_addc_u32 s68, s68, 0
	s_cmp_gt_u32 s69, 13
	s_cbranch_scc0 .LBB0_1231
	s_and_b64 vcc, exec, s[16:17]
	s_cbranch_vccz .LBB0_1234
	s_barrier
